# streaming (nt) policy on the pooling-diff MIX stores only (data not re-read until the w_out phase)
# speedup vs baseline: 1.0041x; 1.0041x over previous
; #define UNPK8(dst, _w) do { dst[0] = pg8::bf_lo(_w.x); dst[1] = pg8::bf_hi(_w.x); dst[2] = pg8::bf_lo(_w.y); dst[3] = pg8::bf_hi(_w.y); dst[4] = pg8::bf_lo(_w.z); dst[5] = pg8::bf_hi(_w.z); dst[6] = pg8::bf_lo(_w.w); dst[7] = pg8::bf_hi(_w.w); } while (0)
; __device__ __forceinline__ void phase_diff(const Args& a, int l, int G, const int bid, const int tid) {
;     ...
;     for (int r = gw; r < M / 32; r += NGW) {
;         const int m0 = r * 32; const bool prm = m0 < MP;
;         int seq, t0, L, mseq; const float* hist; float* hout;
;         if (prm) { seq = m0 / PL; t0 = m0 % PL; L = PL; mseq = seq * PL; hist = nullptr; hout = a.out + O_PPOOL + (size_t)(l * PB_ + seq) * 15 * WB; }
;         else { const int ms = m0 - MP; seq = ms / SL; t0 = ms % SL; L = SL; mseq = MP + seq * SL; hist = a.in[4] + (size_t)(l * SB_ + seq) * 15 * WB; hout = a.out + O_SPOOL + (size_t)(l * SB_ + seq) * 15 * WB; }
;         float ws_[8];
; #pragma unroll
;         for (int e = 0; e < 8; ++e) ws_[e] = 0.f;
;     ...
;         if (t0 >= 15) {
;     ...
;             const bf16_t* ub = UB + (size_t)(mseq + t0) * WB + n0;
;             { u32x4 pre[15];
; #pragma unroll
;               for (int i = 1; i < 16; ++i) pre[i - 1] = *(const u32x4*)(ub - (size_t)i * WB);
; #pragma unroll
;               for (int i = 1; i < 16; ++i) { float f[8]; UNPK8(f, pre[i - 1]);
; #pragma unroll
;                   for (int e = 0; e < 8; ++e) ws_[e] += (i < w) ? f[e] : 0.f; } }
.Ldiff_new:
	v_readfirstlane_b32 s52, v62
	v_readfirstlane_b32 s10, v14
	v_readfirstlane_b32 s18, v0
	v_readfirstlane_b32 s19, v1
	v_readfirstlane_b32 s24, v66
	v_readfirstlane_b32 s25, v67
	v_readfirstlane_b32 s53, v55
	v_readlane_b32 s16, v253, 26
	v_readlane_b32 s17, v253, 27
	v_readlane_b32 s34, v253, 24
	v_readlane_b32 s35, v253, 25
	v_lshrrev_b32_e32 v73, 1, v60
	s_nop 3
	s_add_i32 s10, s10, s52
	s_lshl_b32 s11, s10, 10
	s_add_u32 s16, s16, s11
	s_addc_u32 s17, s17, 0
	s_lshl_b32 s11, s10, 11
	s_add_u32 s34, s34, s11
	s_addc_u32 s35, s35, 0
	s_add_i32 s11, s52, 17
	s_cmp_eq_u32 s11, s53
	s_cselect_b32 s53, 1, 0
	v_mov_b32_e32 v28, 0
	v_mov_b32_e32 v29, 0
	v_mov_b32_e32 v30, 0
	v_mov_b32_e32 v31, 0
	v_mov_b32_e32 v32, 0
	v_mov_b32_e32 v33, 0
	v_mov_b32_e32 v34, 0
	v_mov_b32_e32 v35, 0
	s_cmp_lt_i32 s52, 15
	s_cbranch_scc1 .Ldf_headSP
	s_sub_u32 s16, s16, 0x3000
	s_subb_u32 s17, s17, 0
	global_load_dwordx4 v[76:79], v73, s[16:17] offset:-3072
	global_load_dwordx4 v[80:83], v73, s[16:17] offset:-2048
	global_load_dwordx4 v[84:87], v73, s[16:17] offset:-1024
	global_load_dwordx4 v[88:91], v73, s[16:17] offset:0
	global_load_dwordx4 v[92:95], v73, s[16:17] offset:1024
	global_load_dwordx4 v[96:99], v73, s[16:17] offset:2048
	global_load_dwordx4 v[100:103], v73, s[16:17] offset:3072
	s_add_u32 s16, s16, 0x2000
	s_addc_u32 s17, s17, 0
	global_load_dwordx4 v[104:107], v73, s[16:17] offset:-4096
	global_load_dwordx4 v[108:111], v73, s[16:17] offset:-3072
	global_load_dwordx4 v[112:115], v73, s[16:17] offset:-2048
	global_load_dwordx4 v[116:119], v73, s[16:17] offset:-1024
	global_load_dwordx4 v[120:123], v73, s[16:17] offset:0
	global_load_dwordx4 v[124:127], v73, s[16:17] offset:1024
	global_load_dwordx4 v[134:137], v73, s[16:17] offset:2048
	global_load_dwordx4 v[138:141], v73, s[16:17] offset:3072
	s_add_u32 s16, s16, 0x2000
	s_addc_u32 s17, s17, 0
	global_load_dwordx4 v[142:145], v73, s[16:17] offset:-4096
	global_load_dwordx4 v[146:149], v73, s[16:17] offset:-3072
	global_load_dwordx4 v[164:167], v73, s[16:17] offset:-2048
	global_load_dwordx4 v[168:171], v73, s[16:17] offset:-1024
	global_load_dwordx4 v[172:175], v73, s[16:17] offset:0
	global_load_dwordx4 v[176:179], v73, s[16:17] offset:1024
	global_load_dwordx4 v[180:183], v73, s[16:17] offset:2048
	global_load_dwordx4 v[184:187], v73, s[16:17] offset:3072
	s_add_u32 s16, s16, 0x2000
	s_addc_u32 s17, s17, 0
	global_load_dwordx4 v[188:191], v73, s[16:17] offset:-4096
	global_load_dwordx4 v[210:213], v73, s[16:17] offset:-3072
	global_load_dwordx4 v[214:217], v73, s[16:17] offset:-2048
	global_load_dwordx4 v[218:221], v73, s[16:17] offset:-1024
	global_load_dwordx4 v[222:225], v73, s[16:17] offset:0
	global_load_dwordx4 v[226:229], v73, s[16:17] offset:1024
	global_load_dwordx4 v[230:233], v73, s[16:17] offset:2048
	global_load_dwordx4 v[234:237], v73, s[16:17] offset:3072
	s_add_u32 s16, s16, 0x2000
	s_addc_u32 s17, s17, 0
	global_load_dwordx4 v[238:241], v73, s[16:17] offset:-4096
	global_load_dwordx4 v[0:3], v73, s[16:17] offset:-3072
	global_load_dwordx4 v[4:7], v73, s[16:17] offset:-2048
	global_load_dwordx4 v[8:11], v73, s[16:17] offset:-1024
	global_load_dwordx4 v[12:15], v73, s[16:17] offset:0
	global_load_dwordx4 v[16:19], v73, s[16:17] offset:1024
	global_load_dwordx4 v[20:23], v73, s[16:17] offset:2048
	global_load_dwordx4 v[24:27], v73, s[16:17] offset:3072
	s_add_u32 s16, s16, 0x2000
	s_addc_u32 s17, s17, 0
	s_waitcnt vmcnt(0)
	v_lshlrev_b32_e32 v36, 16, v138
	v_and_b32_e32 v37, 0xffff0000, v138
	v_lshlrev_b32_e32 v38, 16, v139
	v_and_b32_e32 v39, 0xffff0000, v139
	v_lshlrev_b32_e32 v40, 16, v140
	v_and_b32_e32 v41, 0xffff0000, v140
	v_lshlrev_b32_e32 v42, 16, v141
	v_and_b32_e32 v43, 0xffff0000, v141
	v_pk_add_f32 v[28:29], v[28:29], v[36:37]
	v_pk_add_f32 v[30:31], v[30:31], v[38:39]
	v_pk_add_f32 v[32:33], v[32:33], v[40:41]
	v_pk_add_f32 v[34:35], v[34:35], v[42:43]
	v_cndmask_b32_e64 v61, v134, 0, s[4:5]
	v_cndmask_b32_e64 v63, v135, 0, s[4:5]
	v_cndmask_b32_e64 v65, v136, 0, s[4:5]
	v_cndmask_b32_e64 v68, v137, 0, s[4:5]
	v_lshlrev_b32_e32 v36, 16, v61
	v_and_b32_e32 v37, 0xffff0000, v61
	v_lshlrev_b32_e32 v38, 16, v63
	v_and_b32_e32 v39, 0xffff0000, v63
	v_lshlrev_b32_e32 v40, 16, v65
	v_and_b32_e32 v41, 0xffff0000, v65
	v_lshlrev_b32_e32 v42, 16, v68
	v_and_b32_e32 v43, 0xffff0000, v68
	v_pk_add_f32 v[28:29], v[28:29], v[36:37]
	v_pk_add_f32 v[30:31], v[30:31], v[38:39]
	v_pk_add_f32 v[32:33], v[32:33], v[40:41]
	v_pk_add_f32 v[34:35], v[34:35], v[42:43]
	v_cndmask_b32_e64 v61, v124, 0, s[4:5]
	v_cndmask_b32_e64 v63, v125, 0, s[4:5]
	v_cndmask_b32_e64 v65, v126, 0, s[4:5]
	v_cndmask_b32_e64 v68, v127, 0, s[4:5]
	v_lshlrev_b32_e32 v36, 16, v61
	v_and_b32_e32 v37, 0xffff0000, v61
	v_lshlrev_b32_e32 v38, 16, v63
	v_and_b32_e32 v39, 0xffff0000, v63
	v_lshlrev_b32_e32 v40, 16, v65
	v_and_b32_e32 v41, 0xffff0000, v65
	v_lshlrev_b32_e32 v42, 16, v68
	v_and_b32_e32 v43, 0xffff0000, v68
	v_pk_add_f32 v[28:29], v[28:29], v[36:37]
	v_pk_add_f32 v[30:31], v[30:31], v[38:39]
	v_pk_add_f32 v[32:33], v[32:33], v[40:41]
	v_pk_add_f32 v[34:35], v[34:35], v[42:43]
	v_cndmask_b32_e64 v61, 0, v120, s[6:7]
	v_cndmask_b32_e64 v63, 0, v121, s[6:7]
	v_cndmask_b32_e64 v65, 0, v122, s[6:7]
	v_cndmask_b32_e64 v68, 0, v123, s[6:7]
	v_lshlrev_b32_e32 v36, 16, v61
	v_and_b32_e32 v37, 0xffff0000, v61
	v_lshlrev_b32_e32 v38, 16, v63
	v_and_b32_e32 v39, 0xffff0000, v63
	v_lshlrev_b32_e32 v40, 16, v65
	v_and_b32_e32 v41, 0xffff0000, v65
	v_lshlrev_b32_e32 v42, 16, v68
	v_and_b32_e32 v43, 0xffff0000, v68
	v_pk_add_f32 v[28:29], v[28:29], v[36:37]
	v_pk_add_f32 v[30:31], v[30:31], v[38:39]
; #define UNPK8(dst, _w) do { dst[0] = pg8::bf_lo(_w.x); dst[1] = pg8::bf_hi(_w.x); dst[2] = pg8::bf_lo(_w.y); dst[3] = pg8::bf_hi(_w.y); dst[4] = pg8::bf_lo(_w.z); dst[5] = pg8::bf_hi(_w.z); dst[6] = pg8::bf_lo(_w.w); dst[7] = pg8::bf_hi(_w.w); } while (0)
; __device__ __forceinline__ void phase_diff(const Args& a, int l, int G, const int bid, const int tid) {
;     ...
;             { u32x4 pre[15];
; #pragma unroll
;               for (int i = 1; i < 16; ++i) pre[i - 1] = *(const u32x4*)(ub - (size_t)i * WB);
; #pragma unroll
;               for (int i = 1; i < 16; ++i) { float f[8]; UNPK8(f, pre[i - 1]);
; #pragma unroll
;                   for (int e = 0; e < 8; ++e) ws_[e] += (i < w) ? f[e] : 0.f; } }
	v_pk_add_f32 v[32:33], v[32:33], v[40:41]
	v_pk_add_f32 v[34:35], v[34:35], v[42:43]
	v_cndmask_b32_e64 v61, 0, v116, s[6:7]
	v_cndmask_b32_e64 v63, 0, v117, s[6:7]
	v_cndmask_b32_e64 v65, 0, v118, s[6:7]
	v_cndmask_b32_e64 v68, 0, v119, s[6:7]
	v_lshlrev_b32_e32 v36, 16, v61
	v_and_b32_e32 v37, 0xffff0000, v61
	v_lshlrev_b32_e32 v38, 16, v63
	v_and_b32_e32 v39, 0xffff0000, v63
	v_lshlrev_b32_e32 v40, 16, v65
	v_and_b32_e32 v41, 0xffff0000, v65
	v_lshlrev_b32_e32 v42, 16, v68
	v_and_b32_e32 v43, 0xffff0000, v68
	v_pk_add_f32 v[28:29], v[28:29], v[36:37]
	v_pk_add_f32 v[30:31], v[30:31], v[38:39]
	v_pk_add_f32 v[32:33], v[32:33], v[40:41]
	v_pk_add_f32 v[34:35], v[34:35], v[42:43]
	v_cndmask_b32_e64 v61, 0, v112, s[6:7]
	v_cndmask_b32_e64 v63, 0, v113, s[6:7]
	v_cndmask_b32_e64 v65, 0, v114, s[6:7]
	v_cndmask_b32_e64 v68, 0, v115, s[6:7]
	v_lshlrev_b32_e32 v36, 16, v61
	v_and_b32_e32 v37, 0xffff0000, v61
	v_lshlrev_b32_e32 v38, 16, v63
	v_and_b32_e32 v39, 0xffff0000, v63
	v_lshlrev_b32_e32 v40, 16, v65
	v_and_b32_e32 v41, 0xffff0000, v65
	v_lshlrev_b32_e32 v42, 16, v68
	v_and_b32_e32 v43, 0xffff0000, v68
	v_pk_add_f32 v[28:29], v[28:29], v[36:37]
	v_pk_add_f32 v[30:31], v[30:31], v[38:39]
	v_pk_add_f32 v[32:33], v[32:33], v[40:41]
	v_pk_add_f32 v[34:35], v[34:35], v[42:43]
	v_cndmask_b32_e64 v61, 0, v108, s[6:7]
	v_cndmask_b32_e64 v63, 0, v109, s[6:7]
	v_cndmask_b32_e64 v65, 0, v110, s[6:7]
	v_cndmask_b32_e64 v68, 0, v111, s[6:7]
	v_lshlrev_b32_e32 v36, 16, v61
	v_and_b32_e32 v37, 0xffff0000, v61
	v_lshlrev_b32_e32 v38, 16, v63
	v_and_b32_e32 v39, 0xffff0000, v63
	v_lshlrev_b32_e32 v40, 16, v65
	v_and_b32_e32 v41, 0xffff0000, v65
	v_lshlrev_b32_e32 v42, 16, v68
	v_and_b32_e32 v43, 0xffff0000, v68
	v_pk_add_f32 v[28:29], v[28:29], v[36:37]
	v_pk_add_f32 v[30:31], v[30:31], v[38:39]
	v_pk_add_f32 v[32:33], v[32:33], v[40:41]
	v_pk_add_f32 v[34:35], v[34:35], v[42:43]
	v_cndmask_b32_e64 v61, 0, v104, s[8:9]
	v_cndmask_b32_e64 v63, 0, v105, s[8:9]
	v_cndmask_b32_e64 v65, 0, v106, s[8:9]
	v_cndmask_b32_e64 v68, 0, v107, s[8:9]
	v_lshlrev_b32_e32 v36, 16, v61
	v_and_b32_e32 v37, 0xffff0000, v61
	v_lshlrev_b32_e32 v38, 16, v63
	v_and_b32_e32 v39, 0xffff0000, v63
	v_lshlrev_b32_e32 v40, 16, v65
	v_and_b32_e32 v41, 0xffff0000, v65
	v_lshlrev_b32_e32 v42, 16, v68
	v_and_b32_e32 v43, 0xffff0000, v68
	v_pk_add_f32 v[28:29], v[28:29], v[36:37]
	v_pk_add_f32 v[30:31], v[30:31], v[38:39]
	v_pk_add_f32 v[32:33], v[32:33], v[40:41]
	v_pk_add_f32 v[34:35], v[34:35], v[42:43]
	v_cndmask_b32_e64 v61, 0, v100, s[8:9]
	v_cndmask_b32_e64 v63, 0, v101, s[8:9]
	v_cndmask_b32_e64 v65, 0, v102, s[8:9]
	v_cndmask_b32_e64 v68, 0, v103, s[8:9]
	v_lshlrev_b32_e32 v36, 16, v61
	v_and_b32_e32 v37, 0xffff0000, v61
	v_lshlrev_b32_e32 v38, 16, v63
	v_and_b32_e32 v39, 0xffff0000, v63
	v_lshlrev_b32_e32 v40, 16, v65
	v_and_b32_e32 v41, 0xffff0000, v65
	v_lshlrev_b32_e32 v42, 16, v68
	v_and_b32_e32 v43, 0xffff0000, v68
	v_pk_add_f32 v[28:29], v[28:29], v[36:37]
	v_pk_add_f32 v[30:31], v[30:31], v[38:39]
	v_pk_add_f32 v[32:33], v[32:33], v[40:41]
	v_pk_add_f32 v[34:35], v[34:35], v[42:43]
	v_cndmask_b32_e64 v61, 0, v96, s[8:9]
	v_cndmask_b32_e64 v63, 0, v97, s[8:9]
	v_cndmask_b32_e64 v65, 0, v98, s[8:9]
	v_cndmask_b32_e64 v68, 0, v99, s[8:9]
	v_lshlrev_b32_e32 v36, 16, v61
	v_and_b32_e32 v37, 0xffff0000, v61
	v_lshlrev_b32_e32 v38, 16, v63
	v_and_b32_e32 v39, 0xffff0000, v63
	v_lshlrev_b32_e32 v40, 16, v65
	v_and_b32_e32 v41, 0xffff0000, v65
	v_lshlrev_b32_e32 v42, 16, v68
	v_and_b32_e32 v43, 0xffff0000, v68
	v_pk_add_f32 v[28:29], v[28:29], v[36:37]
	v_pk_add_f32 v[30:31], v[30:31], v[38:39]
	v_pk_add_f32 v[32:33], v[32:33], v[40:41]
	v_pk_add_f32 v[34:35], v[34:35], v[42:43]
	v_cndmask_b32_e64 v61, 0, v92, s[8:9]
	v_cndmask_b32_e64 v63, 0, v93, s[8:9]
	v_cndmask_b32_e64 v65, 0, v94, s[8:9]
	v_cndmask_b32_e64 v68, 0, v95, s[8:9]
	v_lshlrev_b32_e32 v36, 16, v61
	v_and_b32_e32 v37, 0xffff0000, v61
	v_lshlrev_b32_e32 v38, 16, v63
	v_and_b32_e32 v39, 0xffff0000, v63
	v_lshlrev_b32_e32 v40, 16, v65
	v_and_b32_e32 v41, 0xffff0000, v65
	v_lshlrev_b32_e32 v42, 16, v68
	v_and_b32_e32 v43, 0xffff0000, v68
	v_pk_add_f32 v[28:29], v[28:29], v[36:37]
	v_pk_add_f32 v[30:31], v[30:31], v[38:39]
	v_pk_add_f32 v[32:33], v[32:33], v[40:41]
	v_pk_add_f32 v[34:35], v[34:35], v[42:43]
	v_cndmask_b32_e64 v61, 0, v88, s[8:9]
	v_cndmask_b32_e64 v63, 0, v89, s[8:9]
	v_cndmask_b32_e64 v65, 0, v90, s[8:9]
	v_cndmask_b32_e64 v68, 0, v91, s[8:9]
	v_lshlrev_b32_e32 v36, 16, v61
	v_and_b32_e32 v37, 0xffff0000, v61
	v_lshlrev_b32_e32 v38, 16, v63
	v_and_b32_e32 v39, 0xffff0000, v63
	v_lshlrev_b32_e32 v40, 16, v65
	v_and_b32_e32 v41, 0xffff0000, v65
	v_lshlrev_b32_e32 v42, 16, v68
	v_and_b32_e32 v43, 0xffff0000, v68
	v_pk_add_f32 v[28:29], v[28:29], v[36:37]
	v_pk_add_f32 v[30:31], v[30:31], v[38:39]
	v_pk_add_f32 v[32:33], v[32:33], v[40:41]
	v_pk_add_f32 v[34:35], v[34:35], v[42:43]
	v_cndmask_b32_e64 v61, 0, v84, s[8:9]
	v_cndmask_b32_e64 v63, 0, v85, s[8:9]
	v_cndmask_b32_e64 v65, 0, v86, s[8:9]
	v_cndmask_b32_e64 v68, 0, v87, s[8:9]
	v_lshlrev_b32_e32 v36, 16, v61
	v_and_b32_e32 v37, 0xffff0000, v61
	v_lshlrev_b32_e32 v38, 16, v63
	v_and_b32_e32 v39, 0xffff0000, v63
	v_lshlrev_b32_e32 v40, 16, v65
	v_and_b32_e32 v41, 0xffff0000, v65
	v_lshlrev_b32_e32 v42, 16, v68
	v_and_b32_e32 v43, 0xffff0000, v68
	v_pk_add_f32 v[28:29], v[28:29], v[36:37]
	v_pk_add_f32 v[30:31], v[30:31], v[38:39]
	v_pk_add_f32 v[32:33], v[32:33], v[40:41]
	v_pk_add_f32 v[34:35], v[34:35], v[42:43]
	v_cndmask_b32_e64 v61, 0, v80, s[8:9]
	v_cndmask_b32_e64 v63, 0, v81, s[8:9]
	v_cndmask_b32_e64 v65, 0, v82, s[8:9]
; __device__ __forceinline__ unsigned pk2(float lo, float hi) { return pg8::cvt_pk_bf16(lo, hi); }
; #define UNPK8(dst, _w) do { dst[0] = pg8::bf_lo(_w.x); dst[1] = pg8::bf_hi(_w.x); dst[2] = pg8::bf_lo(_w.y); dst[3] = pg8::bf_hi(_w.y); dst[4] = pg8::bf_lo(_w.z); dst[5] = pg8::bf_hi(_w.z); dst[6] = pg8::bf_lo(_w.w); dst[7] = pg8::bf_hi(_w.w); } while (0)
; __device__ __forceinline__ void phase_diff(const Args& a, int l, int G, const int bid, const int tid) {
;     ...
;             for (int i0 = 0; i0 < 32; i0 += 4) {
;                 u32x4 cw[4], ow[4];
; #pragma unroll
;                 for (int k = 0; k < 4; ++k) { cw[k] = *(const u32x4*)(ub + (size_t)(i0 + k) * WB); ow[k] = *(const u32x4*)(ub + (size_t)(i0 + k - w + 1) * WB); }
; #pragma unroll
;                 for (int k = 0; k < 4; ++k) {
;                     const int t = t0 + i0 + k; float cur[8], old[8], o[8];
;                     UNPK8(cur, cw[k]); UNPK8(old, ow[k]);
; #pragma unroll
;                     for (int e = 0; e < 8; ++e) { ws_[e] += cur[e]; o[e] = ws_[e] * inv - cur[e]; ws_[e] -= old[e]; }
;                     u32x4 pw; pw.x = pk2(o[0], o[1]); pw.y = pk2(o[2], o[3]); pw.z = pk2(o[4], o[5]); pw.w = pk2(o[6], o[7]);
;                     *(u32x4*)(MIXB + (size_t)(mseq + t) * DM + n0) = pw;
	v_cndmask_b32_e64 v68, 0, v83, s[8:9]
	v_lshlrev_b32_e32 v36, 16, v61
	v_and_b32_e32 v37, 0xffff0000, v61
	v_lshlrev_b32_e32 v38, 16, v63
	v_and_b32_e32 v39, 0xffff0000, v63
	v_lshlrev_b32_e32 v40, 16, v65
	v_and_b32_e32 v41, 0xffff0000, v65
	v_lshlrev_b32_e32 v42, 16, v68
	v_and_b32_e32 v43, 0xffff0000, v68
	v_pk_add_f32 v[28:29], v[28:29], v[36:37]
	v_pk_add_f32 v[30:31], v[30:31], v[38:39]
	v_pk_add_f32 v[32:33], v[32:33], v[40:41]
	v_pk_add_f32 v[34:35], v[34:35], v[42:43]
	v_cndmask_b32_e64 v61, 0, v76, s[8:9]
	v_cndmask_b32_e64 v63, 0, v77, s[8:9]
	v_cndmask_b32_e64 v65, 0, v78, s[8:9]
	v_cndmask_b32_e64 v68, 0, v79, s[8:9]
	v_lshlrev_b32_e32 v36, 16, v61
	v_and_b32_e32 v37, 0xffff0000, v61
	v_lshlrev_b32_e32 v38, 16, v63
	v_and_b32_e32 v39, 0xffff0000, v63
	v_lshlrev_b32_e32 v40, 16, v65
	v_and_b32_e32 v41, 0xffff0000, v65
	v_lshlrev_b32_e32 v42, 16, v68
	v_and_b32_e32 v43, 0xffff0000, v68
	v_pk_add_f32 v[28:29], v[28:29], v[36:37]
	v_pk_add_f32 v[30:31], v[30:31], v[38:39]
	v_pk_add_f32 v[32:33], v[32:33], v[40:41]
	v_pk_add_f32 v[34:35], v[34:35], v[42:43]
	v_lshlrev_b32_e32 v36, 16, v142
	v_and_b32_e32 v37, 0xffff0000, v142
	v_lshlrev_b32_e32 v38, 16, v143
	v_and_b32_e32 v39, 0xffff0000, v143
	v_lshlrev_b32_e32 v40, 16, v144
	v_and_b32_e32 v41, 0xffff0000, v144
	v_lshlrev_b32_e32 v42, 16, v145
	v_and_b32_e32 v43, 0xffff0000, v145
	v_pk_add_f32 v[28:29], v[28:29], v[36:37]
	v_pk_add_f32 v[30:31], v[30:31], v[38:39]
	v_pk_add_f32 v[32:33], v[32:33], v[40:41]
	v_pk_add_f32 v[34:35], v[34:35], v[42:43]
	v_fma_f32 v44, v72, v28, -v36
	v_fma_f32 v45, v72, v29, -v37
	v_fma_f32 v46, v72, v30, -v38
	v_fma_f32 v47, v72, v31, -v39
	v_fma_f32 v52, v72, v32, -v40
	v_fma_f32 v53, v72, v33, -v41
	v_fma_f32 v54, v72, v34, -v42
	v_fma_f32 v55, v72, v35, -v43
	v_cvt_pk_bf16_f32 v56, v44, v45
	v_cvt_pk_bf16_f32 v57, v46, v47
	v_cvt_pk_bf16_f32 v58, v52, v53
	v_cvt_pk_bf16_f32 v59, v54, v55
	global_store_dwordx4 v73, v[56:59], s[34:35] offset:0 nt
	v_cndmask_b32_e64 v61, v108, v76, s[8:9]
	v_cndmask_b32_e64 v61, v124, v61, s[6:7]
	v_cndmask_b32_e64 v61, v61, v138, s[4:5]
	v_cndmask_b32_e64 v63, v109, v77, s[8:9]
	v_cndmask_b32_e64 v63, v125, v63, s[6:7]
	v_cndmask_b32_e64 v63, v63, v139, s[4:5]
	v_cndmask_b32_e64 v65, v110, v78, s[8:9]
	v_cndmask_b32_e64 v65, v126, v65, s[6:7]
	v_cndmask_b32_e64 v65, v65, v140, s[4:5]
	v_cndmask_b32_e64 v68, v111, v79, s[8:9]
	v_cndmask_b32_e64 v68, v127, v68, s[6:7]
	v_cndmask_b32_e64 v68, v68, v141, s[4:5]
	v_lshlrev_b32_e32 v44, 16, v61
	v_and_b32_e32 v45, 0xffff0000, v61
	v_lshlrev_b32_e32 v46, 16, v63
	v_and_b32_e32 v47, 0xffff0000, v63
	v_lshlrev_b32_e32 v52, 16, v65
	v_and_b32_e32 v53, 0xffff0000, v65
	v_lshlrev_b32_e32 v54, 16, v68
	v_and_b32_e32 v55, 0xffff0000, v68
	v_pk_add_f32 v[28:29], v[28:29], v[44:45] neg_lo:[0,1] neg_hi:[0,1]
	v_pk_add_f32 v[30:31], v[30:31], v[46:47] neg_lo:[0,1] neg_hi:[0,1]
	v_pk_add_f32 v[32:33], v[32:33], v[52:53] neg_lo:[0,1] neg_hi:[0,1]
	v_pk_add_f32 v[34:35], v[34:35], v[54:55] neg_lo:[0,1] neg_hi:[0,1]
	global_load_dwordx4 v[76:79], v73, s[16:17] offset:-4096
	v_lshlrev_b32_e32 v36, 16, v146
	v_and_b32_e32 v37, 0xffff0000, v146
	v_lshlrev_b32_e32 v38, 16, v147
	v_and_b32_e32 v39, 0xffff0000, v147
	v_lshlrev_b32_e32 v40, 16, v148
	v_and_b32_e32 v41, 0xffff0000, v148
	v_lshlrev_b32_e32 v42, 16, v149
	v_and_b32_e32 v43, 0xffff0000, v149
	v_pk_add_f32 v[28:29], v[28:29], v[36:37]
	v_pk_add_f32 v[30:31], v[30:31], v[38:39]
	v_pk_add_f32 v[32:33], v[32:33], v[40:41]
	v_pk_add_f32 v[34:35], v[34:35], v[42:43]
	v_fma_f32 v44, v72, v28, -v36
	v_fma_f32 v45, v72, v29, -v37
	v_fma_f32 v46, v72, v30, -v38
	v_fma_f32 v47, v72, v31, -v39
	v_fma_f32 v52, v72, v32, -v40
	v_fma_f32 v53, v72, v33, -v41
	v_fma_f32 v54, v72, v34, -v42
	v_fma_f32 v55, v72, v35, -v43
	v_cvt_pk_bf16_f32 v56, v44, v45
	v_cvt_pk_bf16_f32 v57, v46, v47
	v_cvt_pk_bf16_f32 v58, v52, v53
	v_cvt_pk_bf16_f32 v59, v54, v55
	global_store_dwordx4 v73, v[56:59], s[34:35] offset:2048 nt
	s_add_u32 s34, s34, 0x1000
	s_addc_u32 s35, s35, 0
	v_cndmask_b32_e64 v61, v112, v80, s[8:9]
	v_cndmask_b32_e64 v61, v134, v61, s[6:7]
	v_cndmask_b32_e64 v61, v61, v142, s[4:5]
	v_cndmask_b32_e64 v63, v113, v81, s[8:9]
	v_cndmask_b32_e64 v63, v135, v63, s[6:7]
	v_cndmask_b32_e64 v63, v63, v143, s[4:5]
	v_cndmask_b32_e64 v65, v114, v82, s[8:9]
	v_cndmask_b32_e64 v65, v136, v65, s[6:7]
	v_cndmask_b32_e64 v65, v65, v144, s[4:5]
	v_cndmask_b32_e64 v68, v115, v83, s[8:9]
	v_cndmask_b32_e64 v68, v137, v68, s[6:7]
	v_cndmask_b32_e64 v68, v68, v145, s[4:5]
	v_lshlrev_b32_e32 v44, 16, v61
	v_and_b32_e32 v45, 0xffff0000, v61
	v_lshlrev_b32_e32 v46, 16, v63
	v_and_b32_e32 v47, 0xffff0000, v63
	v_lshlrev_b32_e32 v52, 16, v65
	v_and_b32_e32 v53, 0xffff0000, v65
	v_lshlrev_b32_e32 v54, 16, v68
	v_and_b32_e32 v55, 0xffff0000, v68
	v_pk_add_f32 v[28:29], v[28:29], v[44:45] neg_lo:[0,1] neg_hi:[0,1]
	v_pk_add_f32 v[30:31], v[30:31], v[46:47] neg_lo:[0,1] neg_hi:[0,1]
	v_pk_add_f32 v[32:33], v[32:33], v[52:53] neg_lo:[0,1] neg_hi:[0,1]
	v_pk_add_f32 v[34:35], v[34:35], v[54:55] neg_lo:[0,1] neg_hi:[0,1]
	global_load_dwordx4 v[80:83], v73, s[16:17] offset:-3072
	v_lshlrev_b32_e32 v36, 16, v164
	v_and_b32_e32 v37, 0xffff0000, v164
	v_lshlrev_b32_e32 v38, 16, v165
	v_and_b32_e32 v39, 0xffff0000, v165
	v_lshlrev_b32_e32 v40, 16, v166
	v_and_b32_e32 v41, 0xffff0000, v166
	v_lshlrev_b32_e32 v42, 16, v167
	v_and_b32_e32 v43, 0xffff0000, v167
	v_pk_add_f32 v[28:29], v[28:29], v[36:37]
	v_pk_add_f32 v[30:31], v[30:31], v[38:39]
	v_pk_add_f32 v[32:33], v[32:33], v[40:41]
	v_pk_add_f32 v[34:35], v[34:35], v[42:43]
	v_fma_f32 v44, v72, v28, -v36
	v_fma_f32 v45, v72, v29, -v37
; __device__ __forceinline__ unsigned pk2(float lo, float hi) { return pg8::cvt_pk_bf16(lo, hi); }
; #define UNPK8(dst, _w) do { dst[0] = pg8::bf_lo(_w.x); dst[1] = pg8::bf_hi(_w.x); dst[2] = pg8::bf_lo(_w.y); dst[3] = pg8::bf_hi(_w.y); dst[4] = pg8::bf_lo(_w.z); dst[5] = pg8::bf_hi(_w.z); dst[6] = pg8::bf_lo(_w.w); dst[7] = pg8::bf_hi(_w.w); } while (0)
; __device__ __forceinline__ void phase_diff(const Args& a, int l, int G, const int bid, const int tid) {
;     ...
;             for (int i0 = 0; i0 < 32; i0 += 4) {
;                 u32x4 cw[4], ow[4];
; #pragma unroll
;                 for (int k = 0; k < 4; ++k) { cw[k] = *(const u32x4*)(ub + (size_t)(i0 + k) * WB); ow[k] = *(const u32x4*)(ub + (size_t)(i0 + k - w + 1) * WB); }
; #pragma unroll
;                 for (int k = 0; k < 4; ++k) {
;                     const int t = t0 + i0 + k; float cur[8], old[8], o[8];
;                     UNPK8(cur, cw[k]); UNPK8(old, ow[k]);
; #pragma unroll
;                     for (int e = 0; e < 8; ++e) { ws_[e] += cur[e]; o[e] = ws_[e] * inv - cur[e]; ws_[e] -= old[e]; }
;                     u32x4 pw; pw.x = pk2(o[0], o[1]); pw.y = pk2(o[2], o[3]); pw.z = pk2(o[4], o[5]); pw.w = pk2(o[6], o[7]);
;                     *(u32x4*)(MIXB + (size_t)(mseq + t) * DM + n0) = pw;
	v_fma_f32 v46, v72, v30, -v38
	v_fma_f32 v47, v72, v31, -v39
	v_fma_f32 v52, v72, v32, -v40
	v_fma_f32 v53, v72, v33, -v41
	v_fma_f32 v54, v72, v34, -v42
	v_fma_f32 v55, v72, v35, -v43
	v_cvt_pk_bf16_f32 v56, v44, v45
	v_cvt_pk_bf16_f32 v57, v46, v47
	v_cvt_pk_bf16_f32 v58, v52, v53
	v_cvt_pk_bf16_f32 v59, v54, v55
	global_store_dwordx4 v73, v[56:59], s[34:35] offset:0 nt
	v_cndmask_b32_e64 v61, v116, v84, s[8:9]
	v_cndmask_b32_e64 v61, v138, v61, s[6:7]
	v_cndmask_b32_e64 v61, v61, v146, s[4:5]
	v_cndmask_b32_e64 v63, v117, v85, s[8:9]
	v_cndmask_b32_e64 v63, v139, v63, s[6:7]
	v_cndmask_b32_e64 v63, v63, v147, s[4:5]
	v_cndmask_b32_e64 v65, v118, v86, s[8:9]
	v_cndmask_b32_e64 v65, v140, v65, s[6:7]
	v_cndmask_b32_e64 v65, v65, v148, s[4:5]
	v_cndmask_b32_e64 v68, v119, v87, s[8:9]
	v_cndmask_b32_e64 v68, v141, v68, s[6:7]
	v_cndmask_b32_e64 v68, v68, v149, s[4:5]
	v_lshlrev_b32_e32 v44, 16, v61
	v_and_b32_e32 v45, 0xffff0000, v61
	v_lshlrev_b32_e32 v46, 16, v63
	v_and_b32_e32 v47, 0xffff0000, v63
	v_lshlrev_b32_e32 v52, 16, v65
	v_and_b32_e32 v53, 0xffff0000, v65
	v_lshlrev_b32_e32 v54, 16, v68
	v_and_b32_e32 v55, 0xffff0000, v68
	v_pk_add_f32 v[28:29], v[28:29], v[44:45] neg_lo:[0,1] neg_hi:[0,1]
	v_pk_add_f32 v[30:31], v[30:31], v[46:47] neg_lo:[0,1] neg_hi:[0,1]
	v_pk_add_f32 v[32:33], v[32:33], v[52:53] neg_lo:[0,1] neg_hi:[0,1]
	v_pk_add_f32 v[34:35], v[34:35], v[54:55] neg_lo:[0,1] neg_hi:[0,1]
	global_load_dwordx4 v[84:87], v73, s[16:17] offset:-2048
	v_lshlrev_b32_e32 v36, 16, v168
	v_and_b32_e32 v37, 0xffff0000, v168
	v_lshlrev_b32_e32 v38, 16, v169
	v_and_b32_e32 v39, 0xffff0000, v169
	v_lshlrev_b32_e32 v40, 16, v170
	v_and_b32_e32 v41, 0xffff0000, v170
	v_lshlrev_b32_e32 v42, 16, v171
	v_and_b32_e32 v43, 0xffff0000, v171
	v_pk_add_f32 v[28:29], v[28:29], v[36:37]
	v_pk_add_f32 v[30:31], v[30:31], v[38:39]
	v_pk_add_f32 v[32:33], v[32:33], v[40:41]
	v_pk_add_f32 v[34:35], v[34:35], v[42:43]
	v_fma_f32 v44, v72, v28, -v36
	v_fma_f32 v45, v72, v29, -v37
	v_fma_f32 v46, v72, v30, -v38
	v_fma_f32 v47, v72, v31, -v39
	v_fma_f32 v52, v72, v32, -v40
	v_fma_f32 v53, v72, v33, -v41
	v_fma_f32 v54, v72, v34, -v42
	v_fma_f32 v55, v72, v35, -v43
	v_cvt_pk_bf16_f32 v56, v44, v45
	v_cvt_pk_bf16_f32 v57, v46, v47
	v_cvt_pk_bf16_f32 v58, v52, v53
	v_cvt_pk_bf16_f32 v59, v54, v55
	global_store_dwordx4 v73, v[56:59], s[34:35] offset:2048 nt
	s_add_u32 s34, s34, 0x1000
	s_addc_u32 s35, s35, 0
	v_cndmask_b32_e64 v61, v120, v88, s[8:9]
	v_cndmask_b32_e64 v61, v142, v61, s[6:7]
	v_cndmask_b32_e64 v61, v61, v164, s[4:5]
	v_cndmask_b32_e64 v63, v121, v89, s[8:9]
	v_cndmask_b32_e64 v63, v143, v63, s[6:7]
	v_cndmask_b32_e64 v63, v63, v165, s[4:5]
	v_cndmask_b32_e64 v65, v122, v90, s[8:9]
	v_cndmask_b32_e64 v65, v144, v65, s[6:7]
	v_cndmask_b32_e64 v65, v65, v166, s[4:5]
	v_cndmask_b32_e64 v68, v123, v91, s[8:9]
	v_cndmask_b32_e64 v68, v145, v68, s[6:7]
	v_cndmask_b32_e64 v68, v68, v167, s[4:5]
	v_lshlrev_b32_e32 v44, 16, v61
	v_and_b32_e32 v45, 0xffff0000, v61
	v_lshlrev_b32_e32 v46, 16, v63
	v_and_b32_e32 v47, 0xffff0000, v63
	v_lshlrev_b32_e32 v52, 16, v65
	v_and_b32_e32 v53, 0xffff0000, v65
	v_lshlrev_b32_e32 v54, 16, v68
	v_and_b32_e32 v55, 0xffff0000, v68
	v_pk_add_f32 v[28:29], v[28:29], v[44:45] neg_lo:[0,1] neg_hi:[0,1]
	v_pk_add_f32 v[30:31], v[30:31], v[46:47] neg_lo:[0,1] neg_hi:[0,1]
	v_pk_add_f32 v[32:33], v[32:33], v[52:53] neg_lo:[0,1] neg_hi:[0,1]
	v_pk_add_f32 v[34:35], v[34:35], v[54:55] neg_lo:[0,1] neg_hi:[0,1]
	global_load_dwordx4 v[88:91], v73, s[16:17] offset:-1024
	v_lshlrev_b32_e32 v36, 16, v172
	v_and_b32_e32 v37, 0xffff0000, v172
	v_lshlrev_b32_e32 v38, 16, v173
	v_and_b32_e32 v39, 0xffff0000, v173
	v_lshlrev_b32_e32 v40, 16, v174
	v_and_b32_e32 v41, 0xffff0000, v174
	v_lshlrev_b32_e32 v42, 16, v175
	v_and_b32_e32 v43, 0xffff0000, v175
	v_pk_add_f32 v[28:29], v[28:29], v[36:37]
	v_pk_add_f32 v[30:31], v[30:31], v[38:39]
	v_pk_add_f32 v[32:33], v[32:33], v[40:41]
	v_pk_add_f32 v[34:35], v[34:35], v[42:43]
	v_fma_f32 v44, v72, v28, -v36
	v_fma_f32 v45, v72, v29, -v37
	v_fma_f32 v46, v72, v30, -v38
	v_fma_f32 v47, v72, v31, -v39
	v_fma_f32 v52, v72, v32, -v40
	v_fma_f32 v53, v72, v33, -v41
	v_fma_f32 v54, v72, v34, -v42
	v_fma_f32 v55, v72, v35, -v43
	v_cvt_pk_bf16_f32 v56, v44, v45
	v_cvt_pk_bf16_f32 v57, v46, v47
	v_cvt_pk_bf16_f32 v58, v52, v53
	v_cvt_pk_bf16_f32 v59, v54, v55
	global_store_dwordx4 v73, v[56:59], s[34:35] offset:0 nt
	v_cndmask_b32_e64 v61, v124, v92, s[8:9]
	v_cndmask_b32_e64 v61, v146, v61, s[6:7]
	v_cndmask_b32_e64 v61, v61, v168, s[4:5]
	v_cndmask_b32_e64 v63, v125, v93, s[8:9]
	v_cndmask_b32_e64 v63, v147, v63, s[6:7]
	v_cndmask_b32_e64 v63, v63, v169, s[4:5]
	v_cndmask_b32_e64 v65, v126, v94, s[8:9]
	v_cndmask_b32_e64 v65, v148, v65, s[6:7]
	v_cndmask_b32_e64 v65, v65, v170, s[4:5]
	v_cndmask_b32_e64 v68, v127, v95, s[8:9]
	v_cndmask_b32_e64 v68, v149, v68, s[6:7]
	v_cndmask_b32_e64 v68, v68, v171, s[4:5]
	v_lshlrev_b32_e32 v44, 16, v61
	v_and_b32_e32 v45, 0xffff0000, v61
	v_lshlrev_b32_e32 v46, 16, v63
	v_and_b32_e32 v47, 0xffff0000, v63
	v_lshlrev_b32_e32 v52, 16, v65
	v_and_b32_e32 v53, 0xffff0000, v65
	v_lshlrev_b32_e32 v54, 16, v68
	v_and_b32_e32 v55, 0xffff0000, v68
	v_pk_add_f32 v[28:29], v[28:29], v[44:45] neg_lo:[0,1] neg_hi:[0,1]
	v_pk_add_f32 v[30:31], v[30:31], v[46:47] neg_lo:[0,1] neg_hi:[0,1]
	v_pk_add_f32 v[32:33], v[32:33], v[52:53] neg_lo:[0,1] neg_hi:[0,1]
	v_pk_add_f32 v[34:35], v[34:35], v[54:55] neg_lo:[0,1] neg_hi:[0,1]
	global_load_dwordx4 v[92:95], v73, s[16:17] offset:0
	v_lshlrev_b32_e32 v36, 16, v176
	v_and_b32_e32 v37, 0xffff0000, v176
	v_lshlrev_b32_e32 v38, 16, v177
; __device__ __forceinline__ unsigned pk2(float lo, float hi) { return pg8::cvt_pk_bf16(lo, hi); }
; #define UNPK8(dst, _w) do { dst[0] = pg8::bf_lo(_w.x); dst[1] = pg8::bf_hi(_w.x); dst[2] = pg8::bf_lo(_w.y); dst[3] = pg8::bf_hi(_w.y); dst[4] = pg8::bf_lo(_w.z); dst[5] = pg8::bf_hi(_w.z); dst[6] = pg8::bf_lo(_w.w); dst[7] = pg8::bf_hi(_w.w); } while (0)
; __device__ __forceinline__ void phase_diff(const Args& a, int l, int G, const int bid, const int tid) {
;     ...
;             for (int i0 = 0; i0 < 32; i0 += 4) {
;                 u32x4 cw[4], ow[4];
; #pragma unroll
;                 for (int k = 0; k < 4; ++k) { cw[k] = *(const u32x4*)(ub + (size_t)(i0 + k) * WB); ow[k] = *(const u32x4*)(ub + (size_t)(i0 + k - w + 1) * WB); }
; #pragma unroll
;                 for (int k = 0; k < 4; ++k) {
;                     const int t = t0 + i0 + k; float cur[8], old[8], o[8];
;                     UNPK8(cur, cw[k]); UNPK8(old, ow[k]);
; #pragma unroll
;                     for (int e = 0; e < 8; ++e) { ws_[e] += cur[e]; o[e] = ws_[e] * inv - cur[e]; ws_[e] -= old[e]; }
;                     u32x4 pw; pw.x = pk2(o[0], o[1]); pw.y = pk2(o[2], o[3]); pw.z = pk2(o[4], o[5]); pw.w = pk2(o[6], o[7]);
;                     *(u32x4*)(MIXB + (size_t)(mseq + t) * DM + n0) = pw;
	v_and_b32_e32 v39, 0xffff0000, v177
	v_lshlrev_b32_e32 v40, 16, v178
	v_and_b32_e32 v41, 0xffff0000, v178
	v_lshlrev_b32_e32 v42, 16, v179
	v_and_b32_e32 v43, 0xffff0000, v179
	v_pk_add_f32 v[28:29], v[28:29], v[36:37]
	v_pk_add_f32 v[30:31], v[30:31], v[38:39]
	v_pk_add_f32 v[32:33], v[32:33], v[40:41]
	v_pk_add_f32 v[34:35], v[34:35], v[42:43]
	v_fma_f32 v44, v72, v28, -v36
	v_fma_f32 v45, v72, v29, -v37
	v_fma_f32 v46, v72, v30, -v38
	v_fma_f32 v47, v72, v31, -v39
	v_fma_f32 v52, v72, v32, -v40
	v_fma_f32 v53, v72, v33, -v41
	v_fma_f32 v54, v72, v34, -v42
	v_fma_f32 v55, v72, v35, -v43
	v_cvt_pk_bf16_f32 v56, v44, v45
	v_cvt_pk_bf16_f32 v57, v46, v47
	v_cvt_pk_bf16_f32 v58, v52, v53
	v_cvt_pk_bf16_f32 v59, v54, v55
	global_store_dwordx4 v73, v[56:59], s[34:35] offset:2048 nt
	s_add_u32 s34, s34, 0x1000
	s_addc_u32 s35, s35, 0
	v_cndmask_b32_e64 v61, v134, v96, s[8:9]
	v_cndmask_b32_e64 v61, v164, v61, s[6:7]
	v_cndmask_b32_e64 v61, v61, v172, s[4:5]
	v_cndmask_b32_e64 v63, v135, v97, s[8:9]
	v_cndmask_b32_e64 v63, v165, v63, s[6:7]
	v_cndmask_b32_e64 v63, v63, v173, s[4:5]
	v_cndmask_b32_e64 v65, v136, v98, s[8:9]
	v_cndmask_b32_e64 v65, v166, v65, s[6:7]
	v_cndmask_b32_e64 v65, v65, v174, s[4:5]
	v_cndmask_b32_e64 v68, v137, v99, s[8:9]
	v_cndmask_b32_e64 v68, v167, v68, s[6:7]
	v_cndmask_b32_e64 v68, v68, v175, s[4:5]
	v_lshlrev_b32_e32 v44, 16, v61
	v_and_b32_e32 v45, 0xffff0000, v61
	v_lshlrev_b32_e32 v46, 16, v63
	v_and_b32_e32 v47, 0xffff0000, v63
	v_lshlrev_b32_e32 v52, 16, v65
	v_and_b32_e32 v53, 0xffff0000, v65
	v_lshlrev_b32_e32 v54, 16, v68
	v_and_b32_e32 v55, 0xffff0000, v68
	v_pk_add_f32 v[28:29], v[28:29], v[44:45] neg_lo:[0,1] neg_hi:[0,1]
	v_pk_add_f32 v[30:31], v[30:31], v[46:47] neg_lo:[0,1] neg_hi:[0,1]
	v_pk_add_f32 v[32:33], v[32:33], v[52:53] neg_lo:[0,1] neg_hi:[0,1]
	v_pk_add_f32 v[34:35], v[34:35], v[54:55] neg_lo:[0,1] neg_hi:[0,1]
	global_load_dwordx4 v[96:99], v73, s[16:17] offset:1024
	v_lshlrev_b32_e32 v36, 16, v180
	v_and_b32_e32 v37, 0xffff0000, v180
	v_lshlrev_b32_e32 v38, 16, v181
	v_and_b32_e32 v39, 0xffff0000, v181
	v_lshlrev_b32_e32 v40, 16, v182
	v_and_b32_e32 v41, 0xffff0000, v182
	v_lshlrev_b32_e32 v42, 16, v183
	v_and_b32_e32 v43, 0xffff0000, v183
	v_pk_add_f32 v[28:29], v[28:29], v[36:37]
	v_pk_add_f32 v[30:31], v[30:31], v[38:39]
	v_pk_add_f32 v[32:33], v[32:33], v[40:41]
	v_pk_add_f32 v[34:35], v[34:35], v[42:43]
	v_fma_f32 v44, v72, v28, -v36
	v_fma_f32 v45, v72, v29, -v37
	v_fma_f32 v46, v72, v30, -v38
	v_fma_f32 v47, v72, v31, -v39
	v_fma_f32 v52, v72, v32, -v40
	v_fma_f32 v53, v72, v33, -v41
	v_fma_f32 v54, v72, v34, -v42
	v_fma_f32 v55, v72, v35, -v43
	v_cvt_pk_bf16_f32 v56, v44, v45
	v_cvt_pk_bf16_f32 v57, v46, v47
	v_cvt_pk_bf16_f32 v58, v52, v53
	v_cvt_pk_bf16_f32 v59, v54, v55
	global_store_dwordx4 v73, v[56:59], s[34:35] offset:0 nt
	v_cndmask_b32_e64 v61, v138, v100, s[8:9]
	v_cndmask_b32_e64 v61, v168, v61, s[6:7]
	v_cndmask_b32_e64 v61, v61, v176, s[4:5]
	v_cndmask_b32_e64 v63, v139, v101, s[8:9]
	v_cndmask_b32_e64 v63, v169, v63, s[6:7]
	v_cndmask_b32_e64 v63, v63, v177, s[4:5]
	v_cndmask_b32_e64 v65, v140, v102, s[8:9]
	v_cndmask_b32_e64 v65, v170, v65, s[6:7]
	v_cndmask_b32_e64 v65, v65, v178, s[4:5]
	v_cndmask_b32_e64 v68, v141, v103, s[8:9]
	v_cndmask_b32_e64 v68, v171, v68, s[6:7]
	v_cndmask_b32_e64 v68, v68, v179, s[4:5]
	v_lshlrev_b32_e32 v44, 16, v61
	v_and_b32_e32 v45, 0xffff0000, v61
	v_lshlrev_b32_e32 v46, 16, v63
	v_and_b32_e32 v47, 0xffff0000, v63
	v_lshlrev_b32_e32 v52, 16, v65
	v_and_b32_e32 v53, 0xffff0000, v65
	v_lshlrev_b32_e32 v54, 16, v68
	v_and_b32_e32 v55, 0xffff0000, v68
	v_pk_add_f32 v[28:29], v[28:29], v[44:45] neg_lo:[0,1] neg_hi:[0,1]
	v_pk_add_f32 v[30:31], v[30:31], v[46:47] neg_lo:[0,1] neg_hi:[0,1]
	v_pk_add_f32 v[32:33], v[32:33], v[52:53] neg_lo:[0,1] neg_hi:[0,1]
	v_pk_add_f32 v[34:35], v[34:35], v[54:55] neg_lo:[0,1] neg_hi:[0,1]
	global_load_dwordx4 v[100:103], v73, s[16:17] offset:2048
	v_lshlrev_b32_e32 v36, 16, v184
	v_and_b32_e32 v37, 0xffff0000, v184
	v_lshlrev_b32_e32 v38, 16, v185
	v_and_b32_e32 v39, 0xffff0000, v185
	v_lshlrev_b32_e32 v40, 16, v186
	v_and_b32_e32 v41, 0xffff0000, v186
	v_lshlrev_b32_e32 v42, 16, v187
	v_and_b32_e32 v43, 0xffff0000, v187
	v_pk_add_f32 v[28:29], v[28:29], v[36:37]
	v_pk_add_f32 v[30:31], v[30:31], v[38:39]
	v_pk_add_f32 v[32:33], v[32:33], v[40:41]
	v_pk_add_f32 v[34:35], v[34:35], v[42:43]
	v_fma_f32 v44, v72, v28, -v36
	v_fma_f32 v45, v72, v29, -v37
	v_fma_f32 v46, v72, v30, -v38
	v_fma_f32 v47, v72, v31, -v39
	v_fma_f32 v52, v72, v32, -v40
	v_fma_f32 v53, v72, v33, -v41
	v_fma_f32 v54, v72, v34, -v42
	v_fma_f32 v55, v72, v35, -v43
	v_cvt_pk_bf16_f32 v56, v44, v45
	v_cvt_pk_bf16_f32 v57, v46, v47
	v_cvt_pk_bf16_f32 v58, v52, v53
	v_cvt_pk_bf16_f32 v59, v54, v55
	global_store_dwordx4 v73, v[56:59], s[34:35] offset:2048 nt
	s_add_u32 s34, s34, 0x1000
	s_addc_u32 s35, s35, 0
	v_cndmask_b32_e64 v61, v142, v104, s[8:9]
	v_cndmask_b32_e64 v61, v172, v61, s[6:7]
	v_cndmask_b32_e64 v61, v61, v180, s[4:5]
	v_cndmask_b32_e64 v63, v143, v105, s[8:9]
	v_cndmask_b32_e64 v63, v173, v63, s[6:7]
	v_cndmask_b32_e64 v63, v63, v181, s[4:5]
	v_cndmask_b32_e64 v65, v144, v106, s[8:9]
	v_cndmask_b32_e64 v65, v174, v65, s[6:7]
	v_cndmask_b32_e64 v65, v65, v182, s[4:5]
	v_cndmask_b32_e64 v68, v145, v107, s[8:9]
	v_cndmask_b32_e64 v68, v175, v68, s[6:7]
	v_cndmask_b32_e64 v68, v68, v183, s[4:5]
	v_lshlrev_b32_e32 v44, 16, v61
	v_and_b32_e32 v45, 0xffff0000, v61
	v_lshlrev_b32_e32 v46, 16, v63
	v_and_b32_e32 v47, 0xffff0000, v63
	v_lshlrev_b32_e32 v52, 16, v65
	v_and_b32_e32 v53, 0xffff0000, v65
	v_lshlrev_b32_e32 v54, 16, v68
; __device__ __forceinline__ unsigned pk2(float lo, float hi) { return pg8::cvt_pk_bf16(lo, hi); }
; #define UNPK8(dst, _w) do { dst[0] = pg8::bf_lo(_w.x); dst[1] = pg8::bf_hi(_w.x); dst[2] = pg8::bf_lo(_w.y); dst[3] = pg8::bf_hi(_w.y); dst[4] = pg8::bf_lo(_w.z); dst[5] = pg8::bf_hi(_w.z); dst[6] = pg8::bf_lo(_w.w); dst[7] = pg8::bf_hi(_w.w); } while (0)
; __device__ __forceinline__ void phase_diff(const Args& a, int l, int G, const int bid, const int tid) {
;     ...
;             for (int i0 = 0; i0 < 32; i0 += 4) {
;                 u32x4 cw[4], ow[4];
; #pragma unroll
;                 for (int k = 0; k < 4; ++k) { cw[k] = *(const u32x4*)(ub + (size_t)(i0 + k) * WB); ow[k] = *(const u32x4*)(ub + (size_t)(i0 + k - w + 1) * WB); }
; #pragma unroll
;                 for (int k = 0; k < 4; ++k) {
;                     const int t = t0 + i0 + k; float cur[8], old[8], o[8];
;                     UNPK8(cur, cw[k]); UNPK8(old, ow[k]);
; #pragma unroll
;                     for (int e = 0; e < 8; ++e) { ws_[e] += cur[e]; o[e] = ws_[e] * inv - cur[e]; ws_[e] -= old[e]; }
;                     u32x4 pw; pw.x = pk2(o[0], o[1]); pw.y = pk2(o[2], o[3]); pw.z = pk2(o[4], o[5]); pw.w = pk2(o[6], o[7]);
;                     *(u32x4*)(MIXB + (size_t)(mseq + t) * DM + n0) = pw;
	v_and_b32_e32 v55, 0xffff0000, v68
	v_pk_add_f32 v[28:29], v[28:29], v[44:45] neg_lo:[0,1] neg_hi:[0,1]
	v_pk_add_f32 v[30:31], v[30:31], v[46:47] neg_lo:[0,1] neg_hi:[0,1]
	v_pk_add_f32 v[32:33], v[32:33], v[52:53] neg_lo:[0,1] neg_hi:[0,1]
	v_pk_add_f32 v[34:35], v[34:35], v[54:55] neg_lo:[0,1] neg_hi:[0,1]
	global_load_dwordx4 v[104:107], v73, s[16:17] offset:3072
	v_lshlrev_b32_e32 v36, 16, v188
	v_and_b32_e32 v37, 0xffff0000, v188
	v_lshlrev_b32_e32 v38, 16, v189
	v_and_b32_e32 v39, 0xffff0000, v189
	v_lshlrev_b32_e32 v40, 16, v190
	v_and_b32_e32 v41, 0xffff0000, v190
	v_lshlrev_b32_e32 v42, 16, v191
	v_and_b32_e32 v43, 0xffff0000, v191
	v_pk_add_f32 v[28:29], v[28:29], v[36:37]
	v_pk_add_f32 v[30:31], v[30:31], v[38:39]
	v_pk_add_f32 v[32:33], v[32:33], v[40:41]
	v_pk_add_f32 v[34:35], v[34:35], v[42:43]
	v_fma_f32 v44, v72, v28, -v36
	v_fma_f32 v45, v72, v29, -v37
	v_fma_f32 v46, v72, v30, -v38
	v_fma_f32 v47, v72, v31, -v39
	v_fma_f32 v52, v72, v32, -v40
	v_fma_f32 v53, v72, v33, -v41
	v_fma_f32 v54, v72, v34, -v42
	v_fma_f32 v55, v72, v35, -v43
	v_cvt_pk_bf16_f32 v56, v44, v45
	v_cvt_pk_bf16_f32 v57, v46, v47
	v_cvt_pk_bf16_f32 v58, v52, v53
	v_cvt_pk_bf16_f32 v59, v54, v55
	global_store_dwordx4 v73, v[56:59], s[34:35] offset:0 nt
	v_cndmask_b32_e64 v61, v146, v108, s[8:9]
	v_cndmask_b32_e64 v61, v176, v61, s[6:7]
	v_cndmask_b32_e64 v61, v61, v184, s[4:5]
	v_cndmask_b32_e64 v63, v147, v109, s[8:9]
	v_cndmask_b32_e64 v63, v177, v63, s[6:7]
	v_cndmask_b32_e64 v63, v63, v185, s[4:5]
	v_cndmask_b32_e64 v65, v148, v110, s[8:9]
	v_cndmask_b32_e64 v65, v178, v65, s[6:7]
	v_cndmask_b32_e64 v65, v65, v186, s[4:5]
	v_cndmask_b32_e64 v68, v149, v111, s[8:9]
	v_cndmask_b32_e64 v68, v179, v68, s[6:7]
	v_cndmask_b32_e64 v68, v68, v187, s[4:5]
	v_lshlrev_b32_e32 v44, 16, v61
	v_and_b32_e32 v45, 0xffff0000, v61
	v_lshlrev_b32_e32 v46, 16, v63
	v_and_b32_e32 v47, 0xffff0000, v63
	v_lshlrev_b32_e32 v52, 16, v65
	v_and_b32_e32 v53, 0xffff0000, v65
	v_lshlrev_b32_e32 v54, 16, v68
	v_and_b32_e32 v55, 0xffff0000, v68
	v_pk_add_f32 v[28:29], v[28:29], v[44:45] neg_lo:[0,1] neg_hi:[0,1]
	v_pk_add_f32 v[30:31], v[30:31], v[46:47] neg_lo:[0,1] neg_hi:[0,1]
	v_pk_add_f32 v[32:33], v[32:33], v[52:53] neg_lo:[0,1] neg_hi:[0,1]
	v_pk_add_f32 v[34:35], v[34:35], v[54:55] neg_lo:[0,1] neg_hi:[0,1]
	v_lshlrev_b32_e32 v36, 16, v210
	v_and_b32_e32 v37, 0xffff0000, v210
	v_lshlrev_b32_e32 v38, 16, v211
	v_and_b32_e32 v39, 0xffff0000, v211
	v_lshlrev_b32_e32 v40, 16, v212
	v_and_b32_e32 v41, 0xffff0000, v212
	v_lshlrev_b32_e32 v42, 16, v213
	v_and_b32_e32 v43, 0xffff0000, v213
	v_pk_add_f32 v[28:29], v[28:29], v[36:37]
	v_pk_add_f32 v[30:31], v[30:31], v[38:39]
	v_pk_add_f32 v[32:33], v[32:33], v[40:41]
	v_pk_add_f32 v[34:35], v[34:35], v[42:43]
	v_fma_f32 v44, v72, v28, -v36
	v_fma_f32 v45, v72, v29, -v37
	v_fma_f32 v46, v72, v30, -v38
	v_fma_f32 v47, v72, v31, -v39
	v_fma_f32 v52, v72, v32, -v40
	v_fma_f32 v53, v72, v33, -v41
	v_fma_f32 v54, v72, v34, -v42
	v_fma_f32 v55, v72, v35, -v43
	v_cvt_pk_bf16_f32 v56, v44, v45
	v_cvt_pk_bf16_f32 v57, v46, v47
	v_cvt_pk_bf16_f32 v58, v52, v53
	v_cvt_pk_bf16_f32 v59, v54, v55
	global_store_dwordx4 v73, v[56:59], s[34:35] offset:2048 nt
	s_add_u32 s34, s34, 0x1000
	s_addc_u32 s35, s35, 0
	v_cndmask_b32_e64 v61, v164, v112, s[8:9]
	v_cndmask_b32_e64 v61, v180, v61, s[6:7]
	v_cndmask_b32_e64 v61, v61, v188, s[4:5]
	v_cndmask_b32_e64 v63, v165, v113, s[8:9]
	v_cndmask_b32_e64 v63, v181, v63, s[6:7]
	v_cndmask_b32_e64 v63, v63, v189, s[4:5]
	v_cndmask_b32_e64 v65, v166, v114, s[8:9]
	v_cndmask_b32_e64 v65, v182, v65, s[6:7]
	v_cndmask_b32_e64 v65, v65, v190, s[4:5]
	v_cndmask_b32_e64 v68, v167, v115, s[8:9]
	v_cndmask_b32_e64 v68, v183, v68, s[6:7]
	v_cndmask_b32_e64 v68, v68, v191, s[4:5]
	v_lshlrev_b32_e32 v44, 16, v61
	v_and_b32_e32 v45, 0xffff0000, v61
	v_lshlrev_b32_e32 v46, 16, v63
	v_and_b32_e32 v47, 0xffff0000, v63
	v_lshlrev_b32_e32 v52, 16, v65
	v_and_b32_e32 v53, 0xffff0000, v65
	v_lshlrev_b32_e32 v54, 16, v68
	v_and_b32_e32 v55, 0xffff0000, v68
	v_pk_add_f32 v[28:29], v[28:29], v[44:45] neg_lo:[0,1] neg_hi:[0,1]
	v_pk_add_f32 v[30:31], v[30:31], v[46:47] neg_lo:[0,1] neg_hi:[0,1]
	v_pk_add_f32 v[32:33], v[32:33], v[52:53] neg_lo:[0,1] neg_hi:[0,1]
	v_pk_add_f32 v[34:35], v[34:35], v[54:55] neg_lo:[0,1] neg_hi:[0,1]
	v_lshlrev_b32_e32 v36, 16, v214
	v_and_b32_e32 v37, 0xffff0000, v214
	v_lshlrev_b32_e32 v38, 16, v215
	v_and_b32_e32 v39, 0xffff0000, v215
	v_lshlrev_b32_e32 v40, 16, v216
	v_and_b32_e32 v41, 0xffff0000, v216
	v_lshlrev_b32_e32 v42, 16, v217
	v_and_b32_e32 v43, 0xffff0000, v217
	v_pk_add_f32 v[28:29], v[28:29], v[36:37]
	v_pk_add_f32 v[30:31], v[30:31], v[38:39]
	v_pk_add_f32 v[32:33], v[32:33], v[40:41]
	v_pk_add_f32 v[34:35], v[34:35], v[42:43]
	v_fma_f32 v44, v72, v28, -v36
	v_fma_f32 v45, v72, v29, -v37
	v_fma_f32 v46, v72, v30, -v38
	v_fma_f32 v47, v72, v31, -v39
	v_fma_f32 v52, v72, v32, -v40
	v_fma_f32 v53, v72, v33, -v41
	v_fma_f32 v54, v72, v34, -v42
	v_fma_f32 v55, v72, v35, -v43
	v_cvt_pk_bf16_f32 v56, v44, v45
	v_cvt_pk_bf16_f32 v57, v46, v47
	v_cvt_pk_bf16_f32 v58, v52, v53
	v_cvt_pk_bf16_f32 v59, v54, v55
	global_store_dwordx4 v73, v[56:59], s[34:35] offset:0 nt
	v_cndmask_b32_e64 v61, v168, v116, s[8:9]
	v_cndmask_b32_e64 v61, v184, v61, s[6:7]
	v_cndmask_b32_e64 v61, v61, v210, s[4:5]
	v_cndmask_b32_e64 v63, v169, v117, s[8:9]
	v_cndmask_b32_e64 v63, v185, v63, s[6:7]
	v_cndmask_b32_e64 v63, v63, v211, s[4:5]
	v_cndmask_b32_e64 v65, v170, v118, s[8:9]
	v_cndmask_b32_e64 v65, v186, v65, s[6:7]
	v_cndmask_b32_e64 v65, v65, v212, s[4:5]
	v_cndmask_b32_e64 v68, v171, v119, s[8:9]
; __device__ __forceinline__ unsigned pk2(float lo, float hi) { return pg8::cvt_pk_bf16(lo, hi); }
; #define UNPK8(dst, _w) do { dst[0] = pg8::bf_lo(_w.x); dst[1] = pg8::bf_hi(_w.x); dst[2] = pg8::bf_lo(_w.y); dst[3] = pg8::bf_hi(_w.y); dst[4] = pg8::bf_lo(_w.z); dst[5] = pg8::bf_hi(_w.z); dst[6] = pg8::bf_lo(_w.w); dst[7] = pg8::bf_hi(_w.w); } while (0)
; __device__ __forceinline__ void phase_diff(const Args& a, int l, int G, const int bid, const int tid) {
;     ...
;             for (int i0 = 0; i0 < 32; i0 += 4) {
;                 u32x4 cw[4], ow[4];
; #pragma unroll
;                 for (int k = 0; k < 4; ++k) { cw[k] = *(const u32x4*)(ub + (size_t)(i0 + k) * WB); ow[k] = *(const u32x4*)(ub + (size_t)(i0 + k - w + 1) * WB); }
; #pragma unroll
;                 for (int k = 0; k < 4; ++k) {
;                     const int t = t0 + i0 + k; float cur[8], old[8], o[8];
;                     UNPK8(cur, cw[k]); UNPK8(old, ow[k]);
; #pragma unroll
;                     for (int e = 0; e < 8; ++e) { ws_[e] += cur[e]; o[e] = ws_[e] * inv - cur[e]; ws_[e] -= old[e]; }
;                     u32x4 pw; pw.x = pk2(o[0], o[1]); pw.y = pk2(o[2], o[3]); pw.z = pk2(o[4], o[5]); pw.w = pk2(o[6], o[7]);
;                     *(u32x4*)(MIXB + (size_t)(mseq + t) * DM + n0) = pw;
	v_cndmask_b32_e64 v68, v187, v68, s[6:7]
	v_cndmask_b32_e64 v68, v68, v213, s[4:5]
	v_lshlrev_b32_e32 v44, 16, v61
	v_and_b32_e32 v45, 0xffff0000, v61
	v_lshlrev_b32_e32 v46, 16, v63
	v_and_b32_e32 v47, 0xffff0000, v63
	v_lshlrev_b32_e32 v52, 16, v65
	v_and_b32_e32 v53, 0xffff0000, v65
	v_lshlrev_b32_e32 v54, 16, v68
	v_and_b32_e32 v55, 0xffff0000, v68
	v_pk_add_f32 v[28:29], v[28:29], v[44:45] neg_lo:[0,1] neg_hi:[0,1]
	v_pk_add_f32 v[30:31], v[30:31], v[46:47] neg_lo:[0,1] neg_hi:[0,1]
	v_pk_add_f32 v[32:33], v[32:33], v[52:53] neg_lo:[0,1] neg_hi:[0,1]
	v_pk_add_f32 v[34:35], v[34:35], v[54:55] neg_lo:[0,1] neg_hi:[0,1]
	v_lshlrev_b32_e32 v36, 16, v218
	v_and_b32_e32 v37, 0xffff0000, v218
	v_lshlrev_b32_e32 v38, 16, v219
	v_and_b32_e32 v39, 0xffff0000, v219
	v_lshlrev_b32_e32 v40, 16, v220
	v_and_b32_e32 v41, 0xffff0000, v220
	v_lshlrev_b32_e32 v42, 16, v221
	v_and_b32_e32 v43, 0xffff0000, v221
	v_pk_add_f32 v[28:29], v[28:29], v[36:37]
	v_pk_add_f32 v[30:31], v[30:31], v[38:39]
	v_pk_add_f32 v[32:33], v[32:33], v[40:41]
	v_pk_add_f32 v[34:35], v[34:35], v[42:43]
	v_fma_f32 v44, v72, v28, -v36
	v_fma_f32 v45, v72, v29, -v37
	v_fma_f32 v46, v72, v30, -v38
	v_fma_f32 v47, v72, v31, -v39
	v_fma_f32 v52, v72, v32, -v40
	v_fma_f32 v53, v72, v33, -v41
	v_fma_f32 v54, v72, v34, -v42
	v_fma_f32 v55, v72, v35, -v43
	v_cvt_pk_bf16_f32 v56, v44, v45
	v_cvt_pk_bf16_f32 v57, v46, v47
	v_cvt_pk_bf16_f32 v58, v52, v53
	v_cvt_pk_bf16_f32 v59, v54, v55
	global_store_dwordx4 v73, v[56:59], s[34:35] offset:2048 nt
	s_add_u32 s34, s34, 0x1000
	s_addc_u32 s35, s35, 0
	v_cndmask_b32_e64 v61, v172, v120, s[8:9]
	v_cndmask_b32_e64 v61, v188, v61, s[6:7]
	v_cndmask_b32_e64 v61, v61, v214, s[4:5]
	v_cndmask_b32_e64 v63, v173, v121, s[8:9]
	v_cndmask_b32_e64 v63, v189, v63, s[6:7]
	v_cndmask_b32_e64 v63, v63, v215, s[4:5]
	v_cndmask_b32_e64 v65, v174, v122, s[8:9]
	v_cndmask_b32_e64 v65, v190, v65, s[6:7]
	v_cndmask_b32_e64 v65, v65, v216, s[4:5]
	v_cndmask_b32_e64 v68, v175, v123, s[8:9]
	v_cndmask_b32_e64 v68, v191, v68, s[6:7]
	v_cndmask_b32_e64 v68, v68, v217, s[4:5]
	v_lshlrev_b32_e32 v44, 16, v61
	v_and_b32_e32 v45, 0xffff0000, v61
	v_lshlrev_b32_e32 v46, 16, v63
	v_and_b32_e32 v47, 0xffff0000, v63
	v_lshlrev_b32_e32 v52, 16, v65
	v_and_b32_e32 v53, 0xffff0000, v65
	v_lshlrev_b32_e32 v54, 16, v68
	v_and_b32_e32 v55, 0xffff0000, v68
	v_pk_add_f32 v[28:29], v[28:29], v[44:45] neg_lo:[0,1] neg_hi:[0,1]
	v_pk_add_f32 v[30:31], v[30:31], v[46:47] neg_lo:[0,1] neg_hi:[0,1]
	v_pk_add_f32 v[32:33], v[32:33], v[52:53] neg_lo:[0,1] neg_hi:[0,1]
	v_pk_add_f32 v[34:35], v[34:35], v[54:55] neg_lo:[0,1] neg_hi:[0,1]
	v_lshlrev_b32_e32 v36, 16, v222
	v_and_b32_e32 v37, 0xffff0000, v222
	v_lshlrev_b32_e32 v38, 16, v223
	v_and_b32_e32 v39, 0xffff0000, v223
	v_lshlrev_b32_e32 v40, 16, v224
	v_and_b32_e32 v41, 0xffff0000, v224
	v_lshlrev_b32_e32 v42, 16, v225
	v_and_b32_e32 v43, 0xffff0000, v225
	v_pk_add_f32 v[28:29], v[28:29], v[36:37]
	v_pk_add_f32 v[30:31], v[30:31], v[38:39]
	v_pk_add_f32 v[32:33], v[32:33], v[40:41]
	v_pk_add_f32 v[34:35], v[34:35], v[42:43]
	v_fma_f32 v44, v72, v28, -v36
	v_fma_f32 v45, v72, v29, -v37
	v_fma_f32 v46, v72, v30, -v38
	v_fma_f32 v47, v72, v31, -v39
	v_fma_f32 v52, v72, v32, -v40
	v_fma_f32 v53, v72, v33, -v41
	v_fma_f32 v54, v72, v34, -v42
	v_fma_f32 v55, v72, v35, -v43
	v_cvt_pk_bf16_f32 v56, v44, v45
	v_cvt_pk_bf16_f32 v57, v46, v47
	v_cvt_pk_bf16_f32 v58, v52, v53
	v_cvt_pk_bf16_f32 v59, v54, v55
	global_store_dwordx4 v73, v[56:59], s[34:35] offset:0 nt
	v_cndmask_b32_e64 v61, v176, v124, s[8:9]
	v_cndmask_b32_e64 v61, v210, v61, s[6:7]
	v_cndmask_b32_e64 v61, v61, v218, s[4:5]
	v_cndmask_b32_e64 v63, v177, v125, s[8:9]
	v_cndmask_b32_e64 v63, v211, v63, s[6:7]
	v_cndmask_b32_e64 v63, v63, v219, s[4:5]
	v_cndmask_b32_e64 v65, v178, v126, s[8:9]
	v_cndmask_b32_e64 v65, v212, v65, s[6:7]
	v_cndmask_b32_e64 v65, v65, v220, s[4:5]
	v_cndmask_b32_e64 v68, v179, v127, s[8:9]
	v_cndmask_b32_e64 v68, v213, v68, s[6:7]
	v_cndmask_b32_e64 v68, v68, v221, s[4:5]
	v_lshlrev_b32_e32 v44, 16, v61
	v_and_b32_e32 v45, 0xffff0000, v61
	v_lshlrev_b32_e32 v46, 16, v63
	v_and_b32_e32 v47, 0xffff0000, v63
	v_lshlrev_b32_e32 v52, 16, v65
	v_and_b32_e32 v53, 0xffff0000, v65
	v_lshlrev_b32_e32 v54, 16, v68
; __device__ __forceinline__ unsigned pk2(float lo, float hi) { return pg8::cvt_pk_bf16(lo, hi); }
; #define UNPK8(dst, _w) do { dst[0] = pg8::bf_lo(_w.x); dst[1] = pg8::bf_hi(_w.x); dst[2] = pg8::bf_lo(_w.y); dst[3] = pg8::bf_hi(_w.y); dst[4] = pg8::bf_lo(_w.z); dst[5] = pg8::bf_hi(_w.z); dst[6] = pg8::bf_lo(_w.w); dst[7] = pg8::bf_hi(_w.w); } while (0)
; __device__ __forceinline__ void phase_diff(const Args& a, int l, int G, const int bid, const int tid) {
;     ...
;             for (int i0 = 0; i0 < 32; i0 += 4) {
;                 u32x4 cw[4], ow[4];
; #pragma unroll
;                 for (int k = 0; k < 4; ++k) { cw[k] = *(const u32x4*)(ub + (size_t)(i0 + k) * WB); ow[k] = *(const u32x4*)(ub + (size_t)(i0 + k - w + 1) * WB); }
; #pragma unroll
;                 for (int k = 0; k < 4; ++k) {
;                     const int t = t0 + i0 + k; float cur[8], old[8], o[8];
;                     UNPK8(cur, cw[k]); UNPK8(old, ow[k]);
; #pragma unroll
;                     for (int e = 0; e < 8; ++e) { ws_[e] += cur[e]; o[e] = ws_[e] * inv - cur[e]; ws_[e] -= old[e]; }
;                     u32x4 pw; pw.x = pk2(o[0], o[1]); pw.y = pk2(o[2], o[3]); pw.z = pk2(o[4], o[5]); pw.w = pk2(o[6], o[7]);
;                     *(u32x4*)(MIXB + (size_t)(mseq + t) * DM + n0) = pw;
	v_and_b32_e32 v55, 0xffff0000, v68
	v_pk_add_f32 v[28:29], v[28:29], v[44:45] neg_lo:[0,1] neg_hi:[0,1]
	v_pk_add_f32 v[30:31], v[30:31], v[46:47] neg_lo:[0,1] neg_hi:[0,1]
	v_pk_add_f32 v[32:33], v[32:33], v[52:53] neg_lo:[0,1] neg_hi:[0,1]
	v_pk_add_f32 v[34:35], v[34:35], v[54:55] neg_lo:[0,1] neg_hi:[0,1]
	v_lshlrev_b32_e32 v36, 16, v226
	v_and_b32_e32 v37, 0xffff0000, v226
	v_lshlrev_b32_e32 v38, 16, v227
	v_and_b32_e32 v39, 0xffff0000, v227
	v_lshlrev_b32_e32 v40, 16, v228
	v_and_b32_e32 v41, 0xffff0000, v228
	v_lshlrev_b32_e32 v42, 16, v229
	v_and_b32_e32 v43, 0xffff0000, v229
	v_pk_add_f32 v[28:29], v[28:29], v[36:37]
	v_pk_add_f32 v[30:31], v[30:31], v[38:39]
	v_pk_add_f32 v[32:33], v[32:33], v[40:41]
	v_pk_add_f32 v[34:35], v[34:35], v[42:43]
	v_fma_f32 v44, v72, v28, -v36
	v_fma_f32 v45, v72, v29, -v37
	v_fma_f32 v46, v72, v30, -v38
	v_fma_f32 v47, v72, v31, -v39
	v_fma_f32 v52, v72, v32, -v40
	v_fma_f32 v53, v72, v33, -v41
	v_fma_f32 v54, v72, v34, -v42
	v_fma_f32 v55, v72, v35, -v43
	v_cvt_pk_bf16_f32 v56, v44, v45
	v_cvt_pk_bf16_f32 v57, v46, v47
	v_cvt_pk_bf16_f32 v58, v52, v53
	v_cvt_pk_bf16_f32 v59, v54, v55
	global_store_dwordx4 v73, v[56:59], s[34:35] offset:2048 nt
	s_add_u32 s34, s34, 0x1000
	s_addc_u32 s35, s35, 0
	v_cndmask_b32_e64 v61, v180, v134, s[8:9]
	v_cndmask_b32_e64 v61, v214, v61, s[6:7]
	v_cndmask_b32_e64 v61, v61, v222, s[4:5]
	v_cndmask_b32_e64 v63, v181, v135, s[8:9]
	v_cndmask_b32_e64 v63, v215, v63, s[6:7]
	v_cndmask_b32_e64 v63, v63, v223, s[4:5]
	v_cndmask_b32_e64 v65, v182, v136, s[8:9]
	v_cndmask_b32_e64 v65, v216, v65, s[6:7]
	v_cndmask_b32_e64 v65, v65, v224, s[4:5]
	v_cndmask_b32_e64 v68, v183, v137, s[8:9]
	v_cndmask_b32_e64 v68, v217, v68, s[6:7]
	v_cndmask_b32_e64 v68, v68, v225, s[4:5]
	v_lshlrev_b32_e32 v44, 16, v61
	v_and_b32_e32 v45, 0xffff0000, v61
	v_lshlrev_b32_e32 v46, 16, v63
	v_and_b32_e32 v47, 0xffff0000, v63
	v_lshlrev_b32_e32 v52, 16, v65
	v_and_b32_e32 v53, 0xffff0000, v65
	v_lshlrev_b32_e32 v54, 16, v68
	v_and_b32_e32 v55, 0xffff0000, v68
	v_pk_add_f32 v[28:29], v[28:29], v[44:45] neg_lo:[0,1] neg_hi:[0,1]
	v_pk_add_f32 v[30:31], v[30:31], v[46:47] neg_lo:[0,1] neg_hi:[0,1]
	v_pk_add_f32 v[32:33], v[32:33], v[52:53] neg_lo:[0,1] neg_hi:[0,1]
	v_pk_add_f32 v[34:35], v[34:35], v[54:55] neg_lo:[0,1] neg_hi:[0,1]
	v_lshlrev_b32_e32 v36, 16, v230
	v_and_b32_e32 v37, 0xffff0000, v230
	v_lshlrev_b32_e32 v38, 16, v231
	v_and_b32_e32 v39, 0xffff0000, v231
	v_lshlrev_b32_e32 v40, 16, v232
	v_and_b32_e32 v41, 0xffff0000, v232
	v_lshlrev_b32_e32 v42, 16, v233
	v_and_b32_e32 v43, 0xffff0000, v233
	v_pk_add_f32 v[28:29], v[28:29], v[36:37]
	v_pk_add_f32 v[30:31], v[30:31], v[38:39]
	v_pk_add_f32 v[32:33], v[32:33], v[40:41]
	v_pk_add_f32 v[34:35], v[34:35], v[42:43]
	v_fma_f32 v44, v72, v28, -v36
	v_fma_f32 v45, v72, v29, -v37
	v_fma_f32 v46, v72, v30, -v38
	v_fma_f32 v47, v72, v31, -v39
	v_fma_f32 v52, v72, v32, -v40
	v_fma_f32 v53, v72, v33, -v41
	v_fma_f32 v54, v72, v34, -v42
	v_fma_f32 v55, v72, v35, -v43
	v_cvt_pk_bf16_f32 v56, v44, v45
	v_cvt_pk_bf16_f32 v57, v46, v47
	v_cvt_pk_bf16_f32 v58, v52, v53
	v_cvt_pk_bf16_f32 v59, v54, v55
	global_store_dwordx4 v73, v[56:59], s[34:35] offset:0 nt
	v_cndmask_b32_e64 v61, v184, v138, s[8:9]
	v_cndmask_b32_e64 v61, v218, v61, s[6:7]
	v_cndmask_b32_e64 v61, v61, v226, s[4:5]
	v_cndmask_b32_e64 v63, v185, v139, s[8:9]
	v_cndmask_b32_e64 v63, v219, v63, s[6:7]
	v_cndmask_b32_e64 v63, v63, v227, s[4:5]
	v_cndmask_b32_e64 v65, v186, v140, s[8:9]
	v_cndmask_b32_e64 v65, v220, v65, s[6:7]
	v_cndmask_b32_e64 v65, v65, v228, s[4:5]
	v_cndmask_b32_e64 v68, v187, v141, s[8:9]
	v_cndmask_b32_e64 v68, v221, v68, s[6:7]
	v_cndmask_b32_e64 v68, v68, v229, s[4:5]
	v_lshlrev_b32_e32 v44, 16, v61
	v_and_b32_e32 v45, 0xffff0000, v61
	v_lshlrev_b32_e32 v46, 16, v63
	v_and_b32_e32 v47, 0xffff0000, v63
	v_lshlrev_b32_e32 v52, 16, v65
	v_and_b32_e32 v53, 0xffff0000, v65
	v_lshlrev_b32_e32 v54, 16, v68
	v_and_b32_e32 v55, 0xffff0000, v68
	v_pk_add_f32 v[28:29], v[28:29], v[44:45] neg_lo:[0,1] neg_hi:[0,1]
	v_pk_add_f32 v[30:31], v[30:31], v[46:47] neg_lo:[0,1] neg_hi:[0,1]
	v_pk_add_f32 v[32:33], v[32:33], v[52:53] neg_lo:[0,1] neg_hi:[0,1]
	v_pk_add_f32 v[34:35], v[34:35], v[54:55] neg_lo:[0,1] neg_hi:[0,1]
	s_branch .Ldf_tail

; __device__ __forceinline__ unsigned pk2(float lo, float hi) { return pg8::cvt_pk_bf16(lo, hi); }
; __device__ __forceinline__ void phase_diff(const Args& a, int l, int G, const int bid, const int tid) {
;     ...
;         for (int i = 1; i < w; ++i) { float f[8]; FETCH8(f, t0 - i);
; #pragma unroll
;             for (int e = 0; e < 8; ++e) ws_[e] += f[e]; }
;         for (int i = 0; i < 32; ++i) {
;             const int t = t0 + i; float cur[8], old[8], o[8];
;             FETCH8(cur, t); FETCH8(old, t - w + 1);
;             const float inv = 1.0f / (float)(prm ? min(t + 1, w) : w);
; #pragma unroll
;             for (int e = 0; e < 8; ++e) { ws_[e] += cur[e]; o[e] = ws_[e] * inv - cur[e]; ws_[e] -= old[e]; }
;             u32x4 pw; pw.x = pk2(o[0], o[1]); pw.y = pk2(o[2], o[3]); pw.z = pk2(o[4], o[5]); pw.w = pk2(o[6], o[7]);
;             *(u32x4*)(MIXB + (size_t)(mseq + t) * DM + n0) = pw;
.Ldf_np_3:
	v_fma_f32 v44, v74, v28, -v36
	v_fma_f32 v45, v74, v29, -v37
	v_fma_f32 v46, v74, v30, -v38
	v_fma_f32 v47, v74, v31, -v39
	v_cvt_pk_bf16_f32 v56, v44, v45
	v_cvt_pk_bf16_f32 v57, v46, v47
	global_store_dwordx2 v73, v[56:57], s[54:55] offset:0 nt
	v_cndmask_b32_e64 v44, v108, v76, s[8:9]
	v_cndmask_b32_e64 v44, v124, v44, s[6:7]
	v_cndmask_b32_e64 v44, v44, v138, s[4:5]
	v_cndmask_b32_e64 v45, v109, v77, s[8:9]
	v_cndmask_b32_e64 v45, v125, v45, s[6:7]
	v_cndmask_b32_e64 v45, v45, v139, s[4:5]
	v_cndmask_b32_e64 v46, v110, v78, s[8:9]
	v_cndmask_b32_e64 v46, v126, v46, s[6:7]
	v_cndmask_b32_e64 v46, v46, v140, s[4:5]
	v_cndmask_b32_e64 v47, v111, v79, s[8:9]
	v_cndmask_b32_e64 v47, v127, v47, s[6:7]
	v_cndmask_b32_e64 v47, v47, v141, s[4:5]
	v_pk_add_f32 v[28:29], v[28:29], v[44:45] neg_lo:[0,1] neg_hi:[0,1]
	v_pk_add_f32 v[30:31], v[30:31], v[46:47] neg_lo:[0,1] neg_hi:[0,1]
	v_lshlrev_b32_e32 v36, 16, v146
	v_and_b32_e32 v37, 0xffff0000, v146
	v_lshlrev_b32_e32 v38, 16, v147
	v_and_b32_e32 v39, 0xffff0000, v147
	v_pk_add_f32 v[28:29], v[28:29], v[36:37]
	v_pk_add_f32 v[30:31], v[30:31], v[38:39]
	s_cmp_eq_u32 s11, 0
	s_cbranch_scc1 .Ldf_np_4
	v_mov_b32_e32 v74, 0x3f000000
	v_mov_b32_e32 v69, 0x3f000000
	v_mov_b32_e32 v150, 0x3f000000
	v_mov_b32_e32 v151, 0x3f000000
	v_cndmask_b32_e64 v74, v69, v74, s[8:9]
	v_cndmask_b32_e64 v74, v150, v74, s[6:7]
	v_cndmask_b32_e64 v74, v74, v151, s[4:5]
.Ldf_np_4:
	v_fma_f32 v44, v74, v28, -v36
	v_fma_f32 v45, v74, v29, -v37
	v_fma_f32 v46, v74, v30, -v38
	v_fma_f32 v47, v74, v31, -v39
	v_cvt_pk_bf16_f32 v56, v44, v45
	v_cvt_pk_bf16_f32 v57, v46, v47
	global_store_dwordx2 v73, v[56:57], s[54:55] offset:2048 nt
	s_add_u32 s54, s54, 0x1000
	s_addc_u32 s55, s55, 0
	v_lshlrev_b32_e32 v40, 16, v142
	v_and_b32_e32 v41, 0xffff0000, v142
	v_lshlrev_b32_e32 v42, 16, v143
	v_and_b32_e32 v43, 0xffff0000, v143
	v_cndmask_b32_e64 v44, v112, v80, s[8:9]
	v_cndmask_b32_e64 v44, v134, v44, s[6:7]
	v_cndmask_b32_e64 v44, v44, v40, s[4:5]
	v_cndmask_b32_e64 v45, v113, v81, s[8:9]
	v_cndmask_b32_e64 v45, v135, v45, s[6:7]
	v_cndmask_b32_e64 v45, v45, v41, s[4:5]
	v_cndmask_b32_e64 v46, v114, v82, s[8:9]
	v_cndmask_b32_e64 v46, v136, v46, s[6:7]
	v_cndmask_b32_e64 v46, v46, v42, s[4:5]
	v_cndmask_b32_e64 v47, v115, v83, s[8:9]
	v_cndmask_b32_e64 v47, v137, v47, s[6:7]
	v_cndmask_b32_e64 v47, v47, v43, s[4:5]
	v_pk_add_f32 v[28:29], v[28:29], v[44:45] neg_lo:[0,1] neg_hi:[0,1]
	v_pk_add_f32 v[30:31], v[30:31], v[46:47] neg_lo:[0,1] neg_hi:[0,1]
	v_lshlrev_b32_e32 v36, 16, v164
	v_and_b32_e32 v37, 0xffff0000, v164
	v_lshlrev_b32_e32 v38, 16, v165
	v_and_b32_e32 v39, 0xffff0000, v165
	v_pk_add_f32 v[28:29], v[28:29], v[36:37]
	v_pk_add_f32 v[30:31], v[30:31], v[38:39]
	s_cmp_eq_u32 s11, 0
	s_cbranch_scc1 .Ldf_np_5
	v_mov_b32_e32 v74, 0x3eaaaaab
	v_mov_b32_e32 v69, 0x3eaaaaab
	v_mov_b32_e32 v150, 0x3eaaaaab
	v_mov_b32_e32 v151, 0x3f000000
	v_cndmask_b32_e64 v74, v69, v74, s[8:9]
	v_cndmask_b32_e64 v74, v150, v74, s[6:7]
	v_cndmask_b32_e64 v74, v74, v151, s[4:5]
.Ldf_np_5:
	v_fma_f32 v44, v74, v28, -v36
	v_fma_f32 v45, v74, v29, -v37
	v_fma_f32 v46, v74, v30, -v38
	v_fma_f32 v47, v74, v31, -v39
	v_cvt_pk_bf16_f32 v56, v44, v45
	v_cvt_pk_bf16_f32 v57, v46, v47
	global_store_dwordx2 v73, v[56:57], s[54:55] offset:0 nt
	v_lshlrev_b32_e32 v40, 16, v146
	v_and_b32_e32 v41, 0xffff0000, v146
	v_lshlrev_b32_e32 v42, 16, v147
	v_and_b32_e32 v43, 0xffff0000, v147
	v_cndmask_b32_e64 v44, v116, v84, s[8:9]
	v_cndmask_b32_e64 v44, v138, v44, s[6:7]
	v_cndmask_b32_e64 v44, v44, v40, s[4:5]
	v_cndmask_b32_e64 v45, v117, v85, s[8:9]
	v_cndmask_b32_e64 v45, v139, v45, s[6:7]
	v_cndmask_b32_e64 v45, v45, v41, s[4:5]
	v_cndmask_b32_e64 v46, v118, v86, s[8:9]
	v_cndmask_b32_e64 v46, v140, v46, s[6:7]
	v_cndmask_b32_e64 v46, v46, v42, s[4:5]
	v_cndmask_b32_e64 v47, v119, v87, s[8:9]
	v_cndmask_b32_e64 v47, v141, v47, s[6:7]
	v_cndmask_b32_e64 v47, v47, v43, s[4:5]
	v_pk_add_f32 v[28:29], v[28:29], v[44:45] neg_lo:[0,1] neg_hi:[0,1]
	v_pk_add_f32 v[30:31], v[30:31], v[46:47] neg_lo:[0,1] neg_hi:[0,1]
	v_lshlrev_b32_e32 v36, 16, v168
	v_and_b32_e32 v37, 0xffff0000, v168
	v_lshlrev_b32_e32 v38, 16, v169
	v_and_b32_e32 v39, 0xffff0000, v169
	v_pk_add_f32 v[28:29], v[28:29], v[36:37]
	v_pk_add_f32 v[30:31], v[30:31], v[38:39]
	s_cmp_eq_u32 s11, 0
	s_cbranch_scc1 .Ldf_np_6
	v_mov_b32_e32 v74, 0x3e800000
	v_mov_b32_e32 v69, 0x3e800000
	v_mov_b32_e32 v150, 0x3e800000
	v_mov_b32_e32 v151, 0x3f000000
	v_cndmask_b32_e64 v74, v69, v74, s[8:9]
	v_cndmask_b32_e64 v74, v150, v74, s[6:7]
	v_cndmask_b32_e64 v74, v74, v151, s[4:5]
.Ldf_np_6:
	v_fma_f32 v44, v74, v28, -v36
	v_fma_f32 v45, v74, v29, -v37
	v_fma_f32 v46, v74, v30, -v38
	v_fma_f32 v47, v74, v31, -v39
	v_cvt_pk_bf16_f32 v56, v44, v45
	v_cvt_pk_bf16_f32 v57, v46, v47
	global_store_dwordx2 v73, v[56:57], s[54:55] offset:2048 nt
	s_add_u32 s54, s54, 0x1000
	s_addc_u32 s55, s55, 0
	v_lshlrev_b32_e32 v62, 16, v142
	v_and_b32_e32 v64, 0xffff0000, v142
	v_lshlrev_b32_e32 v66, 16, v143
	v_and_b32_e32 v67, 0xffff0000, v143
	v_lshlrev_b32_e32 v40, 16, v164
	v_and_b32_e32 v41, 0xffff0000, v164
	v_lshlrev_b32_e32 v42, 16, v165
	v_and_b32_e32 v43, 0xffff0000, v165
	v_cndmask_b32_e64 v44, v120, v88, s[8:9]
	v_cndmask_b32_e64 v44, v62, v44, s[6:7]
	v_cndmask_b32_e64 v44, v44, v40, s[4:5]
	v_cndmask_b32_e64 v45, v121, v89, s[8:9]
	v_cndmask_b32_e64 v45, v64, v45, s[6:7]
	v_cndmask_b32_e64 v45, v45, v41, s[4:5]
	v_cndmask_b32_e64 v46, v122, v90, s[8:9]
	v_cndmask_b32_e64 v46, v66, v46, s[6:7]
	v_cndmask_b32_e64 v46, v46, v42, s[4:5]
	v_cndmask_b32_e64 v47, v123, v91, s[8:9]
	v_cndmask_b32_e64 v47, v67, v47, s[6:7]
	v_cndmask_b32_e64 v47, v47, v43, s[4:5]
	v_pk_add_f32 v[28:29], v[28:29], v[44:45] neg_lo:[0,1] neg_hi:[0,1]
	v_pk_add_f32 v[30:31], v[30:31], v[46:47] neg_lo:[0,1] neg_hi:[0,1]
	v_lshlrev_b32_e32 v36, 16, v172
	v_and_b32_e32 v37, 0xffff0000, v172
	v_lshlrev_b32_e32 v38, 16, v173
	v_and_b32_e32 v39, 0xffff0000, v173
	v_pk_add_f32 v[28:29], v[28:29], v[36:37]
	v_pk_add_f32 v[30:31], v[30:31], v[38:39]
	s_cmp_eq_u32 s11, 0
	s_cbranch_scc1 .Ldf_np_7
	v_mov_b32_e32 v74, 0x3e4ccccd
	v_mov_b32_e32 v69, 0x3e4ccccd
	v_mov_b32_e32 v150, 0x3e800000
	v_mov_b32_e32 v151, 0x3f000000
	v_cndmask_b32_e64 v74, v69, v74, s[8:9]
	v_cndmask_b32_e64 v74, v150, v74, s[6:7]
	v_cndmask_b32_e64 v74, v74, v151, s[4:5]
; __device__ __forceinline__ unsigned pk2(float lo, float hi) { return pg8::cvt_pk_bf16(lo, hi); }
; __device__ __forceinline__ void phase_diff(const Args& a, int l, int G, const int bid, const int tid) {
;     ...
;         for (int i = 1; i < w; ++i) { float f[8]; FETCH8(f, t0 - i);
; #pragma unroll
;             for (int e = 0; e < 8; ++e) ws_[e] += f[e]; }
;         for (int i = 0; i < 32; ++i) {
;             const int t = t0 + i; float cur[8], old[8], o[8];
;             FETCH8(cur, t); FETCH8(old, t - w + 1);
;             const float inv = 1.0f / (float)(prm ? min(t + 1, w) : w);
; #pragma unroll
;             for (int e = 0; e < 8; ++e) { ws_[e] += cur[e]; o[e] = ws_[e] * inv - cur[e]; ws_[e] -= old[e]; }
;             u32x4 pw; pw.x = pk2(o[0], o[1]); pw.y = pk2(o[2], o[3]); pw.z = pk2(o[4], o[5]); pw.w = pk2(o[6], o[7]);
;             *(u32x4*)(MIXB + (size_t)(mseq + t) * DM + n0) = pw;
.Ldf_np_7:
	v_fma_f32 v44, v74, v28, -v36
	v_fma_f32 v45, v74, v29, -v37
	v_fma_f32 v46, v74, v30, -v38
	v_fma_f32 v47, v74, v31, -v39
	v_cvt_pk_bf16_f32 v56, v44, v45
	v_cvt_pk_bf16_f32 v57, v46, v47
	global_store_dwordx2 v73, v[56:57], s[54:55] offset:0 nt
	v_lshlrev_b32_e32 v62, 16, v146
	v_and_b32_e32 v64, 0xffff0000, v146
	v_lshlrev_b32_e32 v66, 16, v147
	v_and_b32_e32 v67, 0xffff0000, v147
	v_lshlrev_b32_e32 v40, 16, v168
	v_and_b32_e32 v41, 0xffff0000, v168
	v_lshlrev_b32_e32 v42, 16, v169
	v_and_b32_e32 v43, 0xffff0000, v169
	v_cndmask_b32_e64 v44, v124, v92, s[8:9]
	v_cndmask_b32_e64 v44, v62, v44, s[6:7]
	v_cndmask_b32_e64 v44, v44, v40, s[4:5]
	v_cndmask_b32_e64 v45, v125, v93, s[8:9]
	v_cndmask_b32_e64 v45, v64, v45, s[6:7]
	v_cndmask_b32_e64 v45, v45, v41, s[4:5]
	v_cndmask_b32_e64 v46, v126, v94, s[8:9]
	v_cndmask_b32_e64 v46, v66, v46, s[6:7]
	v_cndmask_b32_e64 v46, v46, v42, s[4:5]
	v_cndmask_b32_e64 v47, v127, v95, s[8:9]
	v_cndmask_b32_e64 v47, v67, v47, s[6:7]
	v_cndmask_b32_e64 v47, v47, v43, s[4:5]
	v_pk_add_f32 v[28:29], v[28:29], v[44:45] neg_lo:[0,1] neg_hi:[0,1]
	v_pk_add_f32 v[30:31], v[30:31], v[46:47] neg_lo:[0,1] neg_hi:[0,1]
	v_lshlrev_b32_e32 v36, 16, v176
	v_and_b32_e32 v37, 0xffff0000, v176
	v_lshlrev_b32_e32 v38, 16, v177
	v_and_b32_e32 v39, 0xffff0000, v177
	v_pk_add_f32 v[28:29], v[28:29], v[36:37]
	v_pk_add_f32 v[30:31], v[30:31], v[38:39]
	s_cmp_eq_u32 s11, 0
	s_cbranch_scc1 .Ldf_np_8
	v_mov_b32_e32 v74, 0x3e2aaaab
	v_mov_b32_e32 v69, 0x3e2aaaab
	v_mov_b32_e32 v150, 0x3e800000
	v_mov_b32_e32 v151, 0x3f000000
	v_cndmask_b32_e64 v74, v69, v74, s[8:9]
	v_cndmask_b32_e64 v74, v150, v74, s[6:7]
	v_cndmask_b32_e64 v74, v74, v151, s[4:5]
.Ldf_np_8:
	v_fma_f32 v44, v74, v28, -v36
	v_fma_f32 v45, v74, v29, -v37
	v_fma_f32 v46, v74, v30, -v38
	v_fma_f32 v47, v74, v31, -v39
	v_cvt_pk_bf16_f32 v56, v44, v45
	v_cvt_pk_bf16_f32 v57, v46, v47
	global_store_dwordx2 v73, v[56:57], s[54:55] offset:2048 nt
	s_add_u32 s54, s54, 0x1000
	s_addc_u32 s55, s55, 0
	v_lshlrev_b32_e32 v62, 16, v164
	v_and_b32_e32 v64, 0xffff0000, v164
	v_lshlrev_b32_e32 v66, 16, v165
	v_and_b32_e32 v67, 0xffff0000, v165
	v_lshlrev_b32_e32 v40, 16, v172
	v_and_b32_e32 v41, 0xffff0000, v172
	v_lshlrev_b32_e32 v42, 16, v173
	v_and_b32_e32 v43, 0xffff0000, v173
	v_cndmask_b32_e64 v44, v134, v96, s[8:9]
	v_cndmask_b32_e64 v44, v62, v44, s[6:7]
	v_cndmask_b32_e64 v44, v44, v40, s[4:5]
	v_cndmask_b32_e64 v45, v135, v97, s[8:9]
	v_cndmask_b32_e64 v45, v64, v45, s[6:7]
	v_cndmask_b32_e64 v45, v45, v41, s[4:5]
	v_cndmask_b32_e64 v46, v136, v98, s[8:9]
	v_cndmask_b32_e64 v46, v66, v46, s[6:7]
	v_cndmask_b32_e64 v46, v46, v42, s[4:5]
	v_cndmask_b32_e64 v47, v137, v99, s[8:9]
	v_cndmask_b32_e64 v47, v67, v47, s[6:7]
	v_cndmask_b32_e64 v47, v47, v43, s[4:5]
	v_pk_add_f32 v[28:29], v[28:29], v[44:45] neg_lo:[0,1] neg_hi:[0,1]
	v_pk_add_f32 v[30:31], v[30:31], v[46:47] neg_lo:[0,1] neg_hi:[0,1]
	v_lshlrev_b32_e32 v36, 16, v180
	v_and_b32_e32 v37, 0xffff0000, v180
	v_lshlrev_b32_e32 v38, 16, v181
	v_and_b32_e32 v39, 0xffff0000, v181
	v_pk_add_f32 v[28:29], v[28:29], v[36:37]
	v_pk_add_f32 v[30:31], v[30:31], v[38:39]
	s_cmp_eq_u32 s11, 0
	s_cbranch_scc1 .Ldf_np_9
	v_mov_b32_e32 v74, 0x3e124925
	v_mov_b32_e32 v69, 0x3e124925
	v_mov_b32_e32 v150, 0x3e800000
	v_mov_b32_e32 v151, 0x3f000000
	v_cndmask_b32_e64 v74, v69, v74, s[8:9]
	v_cndmask_b32_e64 v74, v150, v74, s[6:7]
	v_cndmask_b32_e64 v74, v74, v151, s[4:5]
.Ldf_np_9:
	v_fma_f32 v44, v74, v28, -v36
	v_fma_f32 v45, v74, v29, -v37
	v_fma_f32 v46, v74, v30, -v38
	v_fma_f32 v47, v74, v31, -v39
	v_cvt_pk_bf16_f32 v56, v44, v45
	v_cvt_pk_bf16_f32 v57, v46, v47
	global_store_dwordx2 v73, v[56:57], s[54:55] offset:0 nt
	v_lshlrev_b32_e32 v62, 16, v168
	v_and_b32_e32 v64, 0xffff0000, v168
	v_lshlrev_b32_e32 v66, 16, v169
	v_and_b32_e32 v67, 0xffff0000, v169
	v_lshlrev_b32_e32 v40, 16, v176
	v_and_b32_e32 v41, 0xffff0000, v176
	v_lshlrev_b32_e32 v42, 16, v177
	v_and_b32_e32 v43, 0xffff0000, v177
	v_cndmask_b32_e64 v44, v138, v100, s[8:9]
	v_cndmask_b32_e64 v44, v62, v44, s[6:7]
	v_cndmask_b32_e64 v44, v44, v40, s[4:5]
	v_cndmask_b32_e64 v45, v139, v101, s[8:9]
	v_cndmask_b32_e64 v45, v64, v45, s[6:7]
	v_cndmask_b32_e64 v45, v45, v41, s[4:5]
	v_cndmask_b32_e64 v46, v140, v102, s[8:9]
	v_cndmask_b32_e64 v46, v66, v46, s[6:7]
	v_cndmask_b32_e64 v46, v46, v42, s[4:5]
	v_cndmask_b32_e64 v47, v141, v103, s[8:9]
	v_cndmask_b32_e64 v47, v67, v47, s[6:7]
	v_cndmask_b32_e64 v47, v47, v43, s[4:5]
	v_pk_add_f32 v[28:29], v[28:29], v[44:45] neg_lo:[0,1] neg_hi:[0,1]
	v_pk_add_f32 v[30:31], v[30:31], v[46:47] neg_lo:[0,1] neg_hi:[0,1]
	v_lshlrev_b32_e32 v36, 16, v184
	v_and_b32_e32 v37, 0xffff0000, v184
	v_lshlrev_b32_e32 v38, 16, v185
	v_and_b32_e32 v39, 0xffff0000, v185
	v_pk_add_f32 v[28:29], v[28:29], v[36:37]
	v_pk_add_f32 v[30:31], v[30:31], v[38:39]
	s_cmp_eq_u32 s11, 0
	s_cbranch_scc1 .Ldf_np_10
	v_mov_b32_e32 v74, 0x3e000000
	v_mov_b32_e32 v69, 0x3e000000
	v_mov_b32_e32 v150, 0x3e800000
	v_mov_b32_e32 v151, 0x3f000000
	v_cndmask_b32_e64 v74, v69, v74, s[8:9]
	v_cndmask_b32_e64 v74, v150, v74, s[6:7]
	v_cndmask_b32_e64 v74, v74, v151, s[4:5]
; __device__ __forceinline__ unsigned pk2(float lo, float hi) { return pg8::cvt_pk_bf16(lo, hi); }
; __device__ __forceinline__ void phase_diff(const Args& a, int l, int G, const int bid, const int tid) {
;     ...
;         for (int i = 1; i < w; ++i) { float f[8]; FETCH8(f, t0 - i);
; #pragma unroll
;             for (int e = 0; e < 8; ++e) ws_[e] += f[e]; }
;         for (int i = 0; i < 32; ++i) {
;             const int t = t0 + i; float cur[8], old[8], o[8];
;             FETCH8(cur, t); FETCH8(old, t - w + 1);
;             const float inv = 1.0f / (float)(prm ? min(t + 1, w) : w);
; #pragma unroll
;             for (int e = 0; e < 8; ++e) { ws_[e] += cur[e]; o[e] = ws_[e] * inv - cur[e]; ws_[e] -= old[e]; }
;             u32x4 pw; pw.x = pk2(o[0], o[1]); pw.y = pk2(o[2], o[3]); pw.z = pk2(o[4], o[5]); pw.w = pk2(o[6], o[7]);
;             *(u32x4*)(MIXB + (size_t)(mseq + t) * DM + n0) = pw;
.Ldf_np_10:
	v_fma_f32 v44, v74, v28, -v36
	v_fma_f32 v45, v74, v29, -v37
	v_fma_f32 v46, v74, v30, -v38
	v_fma_f32 v47, v74, v31, -v39
	v_cvt_pk_bf16_f32 v56, v44, v45
	v_cvt_pk_bf16_f32 v57, v46, v47
	global_store_dwordx2 v73, v[56:57], s[54:55] offset:2048 nt
	s_add_u32 s54, s54, 0x1000
	s_addc_u32 s55, s55, 0
	v_lshlrev_b32_e32 v192, 16, v142
	v_and_b32_e32 v193, 0xffff0000, v142
	v_lshlrev_b32_e32 v242, 16, v143
	v_and_b32_e32 v243, 0xffff0000, v143
	v_lshlrev_b32_e32 v62, 16, v172
	v_and_b32_e32 v64, 0xffff0000, v172
	v_lshlrev_b32_e32 v66, 16, v173
	v_and_b32_e32 v67, 0xffff0000, v173
	v_lshlrev_b32_e32 v40, 16, v180
	v_and_b32_e32 v41, 0xffff0000, v180
	v_lshlrev_b32_e32 v42, 16, v181
	v_and_b32_e32 v43, 0xffff0000, v181
	v_cndmask_b32_e64 v44, v192, v104, s[8:9]
	v_cndmask_b32_e64 v44, v62, v44, s[6:7]
	v_cndmask_b32_e64 v44, v44, v40, s[4:5]
	v_cndmask_b32_e64 v45, v193, v105, s[8:9]
	v_cndmask_b32_e64 v45, v64, v45, s[6:7]
	v_cndmask_b32_e64 v45, v45, v41, s[4:5]
	v_cndmask_b32_e64 v46, v242, v106, s[8:9]
	v_cndmask_b32_e64 v46, v66, v46, s[6:7]
	v_cndmask_b32_e64 v46, v46, v42, s[4:5]
	v_cndmask_b32_e64 v47, v243, v107, s[8:9]
	v_cndmask_b32_e64 v47, v67, v47, s[6:7]
	v_cndmask_b32_e64 v47, v47, v43, s[4:5]
	v_pk_add_f32 v[28:29], v[28:29], v[44:45] neg_lo:[0,1] neg_hi:[0,1]
	v_pk_add_f32 v[30:31], v[30:31], v[46:47] neg_lo:[0,1] neg_hi:[0,1]
	v_lshlrev_b32_e32 v36, 16, v188
	v_and_b32_e32 v37, 0xffff0000, v188
	v_lshlrev_b32_e32 v38, 16, v189
	v_and_b32_e32 v39, 0xffff0000, v189
	v_pk_add_f32 v[28:29], v[28:29], v[36:37]
	v_pk_add_f32 v[30:31], v[30:31], v[38:39]
	s_cmp_eq_u32 s11, 0
	s_cbranch_scc1 .Ldf_np_11
	v_mov_b32_e32 v74, 0x3de38e39
	v_mov_b32_e32 v69, 0x3e000000
	v_mov_b32_e32 v150, 0x3e800000
	v_mov_b32_e32 v151, 0x3f000000
	v_cndmask_b32_e64 v74, v69, v74, s[8:9]
	v_cndmask_b32_e64 v74, v150, v74, s[6:7]
	v_cndmask_b32_e64 v74, v74, v151, s[4:5]
.Ldf_np_11:
	v_fma_f32 v44, v74, v28, -v36
	v_fma_f32 v45, v74, v29, -v37
	v_fma_f32 v46, v74, v30, -v38
	v_fma_f32 v47, v74, v31, -v39
	v_cvt_pk_bf16_f32 v56, v44, v45
	v_cvt_pk_bf16_f32 v57, v46, v47
	global_store_dwordx2 v73, v[56:57], s[54:55] offset:0 nt
	v_lshlrev_b32_e32 v192, 16, v146
	v_and_b32_e32 v193, 0xffff0000, v146
	v_lshlrev_b32_e32 v242, 16, v147
	v_and_b32_e32 v243, 0xffff0000, v147
	v_lshlrev_b32_e32 v62, 16, v176
	v_and_b32_e32 v64, 0xffff0000, v176
	v_lshlrev_b32_e32 v66, 16, v177
	v_and_b32_e32 v67, 0xffff0000, v177
	v_lshlrev_b32_e32 v40, 16, v184
	v_and_b32_e32 v41, 0xffff0000, v184
	v_lshlrev_b32_e32 v42, 16, v185
	v_and_b32_e32 v43, 0xffff0000, v185
	v_cndmask_b32_e64 v44, v192, v108, s[8:9]
	v_cndmask_b32_e64 v44, v62, v44, s[6:7]
	v_cndmask_b32_e64 v44, v44, v40, s[4:5]
	v_cndmask_b32_e64 v45, v193, v109, s[8:9]
	v_cndmask_b32_e64 v45, v64, v45, s[6:7]
	v_cndmask_b32_e64 v45, v45, v41, s[4:5]
	v_cndmask_b32_e64 v46, v242, v110, s[8:9]
	v_cndmask_b32_e64 v46, v66, v46, s[6:7]
	v_cndmask_b32_e64 v46, v46, v42, s[4:5]
	v_cndmask_b32_e64 v47, v243, v111, s[8:9]
	v_cndmask_b32_e64 v47, v67, v47, s[6:7]
	v_cndmask_b32_e64 v47, v47, v43, s[4:5]
	v_pk_add_f32 v[28:29], v[28:29], v[44:45] neg_lo:[0,1] neg_hi:[0,1]
	v_pk_add_f32 v[30:31], v[30:31], v[46:47] neg_lo:[0,1] neg_hi:[0,1]
	v_lshlrev_b32_e32 v36, 16, v210
	v_and_b32_e32 v37, 0xffff0000, v210
	v_lshlrev_b32_e32 v38, 16, v211
	v_and_b32_e32 v39, 0xffff0000, v211
	v_pk_add_f32 v[28:29], v[28:29], v[36:37]
	v_pk_add_f32 v[30:31], v[30:31], v[38:39]
	s_cmp_eq_u32 s11, 0
	s_cbranch_scc1 .Ldf_np_12
	v_mov_b32_e32 v74, 0x3dcccccd
	v_mov_b32_e32 v69, 0x3e000000
	v_mov_b32_e32 v150, 0x3e800000
	v_mov_b32_e32 v151, 0x3f000000
	v_cndmask_b32_e64 v74, v69, v74, s[8:9]
	v_cndmask_b32_e64 v74, v150, v74, s[6:7]
	v_cndmask_b32_e64 v74, v74, v151, s[4:5]
.Ldf_np_12:
	v_fma_f32 v44, v74, v28, -v36
	v_fma_f32 v45, v74, v29, -v37
	v_fma_f32 v46, v74, v30, -v38
	v_fma_f32 v47, v74, v31, -v39
	v_cvt_pk_bf16_f32 v56, v44, v45
	v_cvt_pk_bf16_f32 v57, v46, v47
	global_store_dwordx2 v73, v[56:57], s[54:55] offset:2048 nt
	s_add_u32 s54, s54, 0x1000
	s_addc_u32 s55, s55, 0
	v_lshlrev_b32_e32 v192, 16, v164
	v_and_b32_e32 v193, 0xffff0000, v164
	v_lshlrev_b32_e32 v242, 16, v165
	v_and_b32_e32 v243, 0xffff0000, v165
	v_lshlrev_b32_e32 v62, 16, v180
	v_and_b32_e32 v64, 0xffff0000, v180
	v_lshlrev_b32_e32 v66, 16, v181
	v_and_b32_e32 v67, 0xffff0000, v181
	v_lshlrev_b32_e32 v40, 16, v188
	v_and_b32_e32 v41, 0xffff0000, v188
	v_lshlrev_b32_e32 v42, 16, v189
	v_and_b32_e32 v43, 0xffff0000, v189
	v_cndmask_b32_e64 v44, v192, v112, s[8:9]
	v_cndmask_b32_e64 v44, v62, v44, s[6:7]
	v_cndmask_b32_e64 v44, v44, v40, s[4:5]
	v_cndmask_b32_e64 v45, v193, v113, s[8:9]
	v_cndmask_b32_e64 v45, v64, v45, s[6:7]
	v_cndmask_b32_e64 v45, v45, v41, s[4:5]
	v_cndmask_b32_e64 v46, v242, v114, s[8:9]
	v_cndmask_b32_e64 v46, v66, v46, s[6:7]
	v_cndmask_b32_e64 v46, v46, v42, s[4:5]
	v_cndmask_b32_e64 v47, v243, v115, s[8:9]
	v_cndmask_b32_e64 v47, v67, v47, s[6:7]
	v_cndmask_b32_e64 v47, v47, v43, s[4:5]
	v_pk_add_f32 v[28:29], v[28:29], v[44:45] neg_lo:[0,1] neg_hi:[0,1]
	v_pk_add_f32 v[30:31], v[30:31], v[46:47] neg_lo:[0,1] neg_hi:[0,1]
	v_lshlrev_b32_e32 v36, 16, v214
	v_and_b32_e32 v37, 0xffff0000, v214
	v_lshlrev_b32_e32 v38, 16, v215
	v_and_b32_e32 v39, 0xffff0000, v215
	v_pk_add_f32 v[28:29], v[28:29], v[36:37]
	v_pk_add_f32 v[30:31], v[30:31], v[38:39]
	s_cmp_eq_u32 s11, 0
	s_cbranch_scc1 .Ldf_np_13
	v_mov_b32_e32 v74, 0x3dba2e8c
	v_mov_b32_e32 v69, 0x3e000000
	v_mov_b32_e32 v150, 0x3e800000
	v_mov_b32_e32 v151, 0x3f000000
	v_cndmask_b32_e64 v74, v69, v74, s[8:9]
	v_cndmask_b32_e64 v74, v150, v74, s[6:7]
	v_cndmask_b32_e64 v74, v74, v151, s[4:5]
; __device__ __forceinline__ unsigned pk2(float lo, float hi) { return pg8::cvt_pk_bf16(lo, hi); }
; __device__ __forceinline__ void phase_diff(const Args& a, int l, int G, const int bid, const int tid) {
;     ...
;         for (int i = 1; i < w; ++i) { float f[8]; FETCH8(f, t0 - i);
; #pragma unroll
;             for (int e = 0; e < 8; ++e) ws_[e] += f[e]; }
;         for (int i = 0; i < 32; ++i) {
;             const int t = t0 + i; float cur[8], old[8], o[8];
;             FETCH8(cur, t); FETCH8(old, t - w + 1);
;             const float inv = 1.0f / (float)(prm ? min(t + 1, w) : w);
; #pragma unroll
;             for (int e = 0; e < 8; ++e) { ws_[e] += cur[e]; o[e] = ws_[e] * inv - cur[e]; ws_[e] -= old[e]; }
;             u32x4 pw; pw.x = pk2(o[0], o[1]); pw.y = pk2(o[2], o[3]); pw.z = pk2(o[4], o[5]); pw.w = pk2(o[6], o[7]);
;             *(u32x4*)(MIXB + (size_t)(mseq + t) * DM + n0) = pw;
.Ldf_np_13:
	v_fma_f32 v44, v74, v28, -v36
	v_fma_f32 v45, v74, v29, -v37
	v_fma_f32 v46, v74, v30, -v38
	v_fma_f32 v47, v74, v31, -v39
	v_cvt_pk_bf16_f32 v56, v44, v45
	v_cvt_pk_bf16_f32 v57, v46, v47
	global_store_dwordx2 v73, v[56:57], s[54:55] offset:0 nt
	v_lshlrev_b32_e32 v192, 16, v168
	v_and_b32_e32 v193, 0xffff0000, v168
	v_lshlrev_b32_e32 v242, 16, v169
	v_and_b32_e32 v243, 0xffff0000, v169
	v_lshlrev_b32_e32 v62, 16, v184
	v_and_b32_e32 v64, 0xffff0000, v184
	v_lshlrev_b32_e32 v66, 16, v185
	v_and_b32_e32 v67, 0xffff0000, v185
	v_lshlrev_b32_e32 v40, 16, v210
	v_and_b32_e32 v41, 0xffff0000, v210
	v_lshlrev_b32_e32 v42, 16, v211
	v_and_b32_e32 v43, 0xffff0000, v211
	v_cndmask_b32_e64 v44, v192, v116, s[8:9]
	v_cndmask_b32_e64 v44, v62, v44, s[6:7]
	v_cndmask_b32_e64 v44, v44, v40, s[4:5]
	v_cndmask_b32_e64 v45, v193, v117, s[8:9]
	v_cndmask_b32_e64 v45, v64, v45, s[6:7]
	v_cndmask_b32_e64 v45, v45, v41, s[4:5]
	v_cndmask_b32_e64 v46, v242, v118, s[8:9]
	v_cndmask_b32_e64 v46, v66, v46, s[6:7]
	v_cndmask_b32_e64 v46, v46, v42, s[4:5]
	v_cndmask_b32_e64 v47, v243, v119, s[8:9]
	v_cndmask_b32_e64 v47, v67, v47, s[6:7]
	v_cndmask_b32_e64 v47, v47, v43, s[4:5]
	v_pk_add_f32 v[28:29], v[28:29], v[44:45] neg_lo:[0,1] neg_hi:[0,1]
	v_pk_add_f32 v[30:31], v[30:31], v[46:47] neg_lo:[0,1] neg_hi:[0,1]
	v_lshlrev_b32_e32 v36, 16, v218
	v_and_b32_e32 v37, 0xffff0000, v218
	v_lshlrev_b32_e32 v38, 16, v219
	v_and_b32_e32 v39, 0xffff0000, v219
	v_pk_add_f32 v[28:29], v[28:29], v[36:37]
	v_pk_add_f32 v[30:31], v[30:31], v[38:39]
	s_cmp_eq_u32 s11, 0
	s_cbranch_scc1 .Ldf_np_14
	v_mov_b32_e32 v74, 0x3daaaaab
	v_mov_b32_e32 v69, 0x3e000000
	v_mov_b32_e32 v150, 0x3e800000
	v_mov_b32_e32 v151, 0x3f000000
	v_cndmask_b32_e64 v74, v69, v74, s[8:9]
	v_cndmask_b32_e64 v74, v150, v74, s[6:7]
	v_cndmask_b32_e64 v74, v74, v151, s[4:5]
.Ldf_np_14:
	v_fma_f32 v44, v74, v28, -v36
	v_fma_f32 v45, v74, v29, -v37
	v_fma_f32 v46, v74, v30, -v38
	v_fma_f32 v47, v74, v31, -v39
	v_cvt_pk_bf16_f32 v56, v44, v45
	v_cvt_pk_bf16_f32 v57, v46, v47
	global_store_dwordx2 v73, v[56:57], s[54:55] offset:2048 nt
	s_add_u32 s54, s54, 0x1000
	s_addc_u32 s55, s55, 0
	v_lshlrev_b32_e32 v192, 16, v172
	v_and_b32_e32 v193, 0xffff0000, v172
	v_lshlrev_b32_e32 v242, 16, v173
	v_and_b32_e32 v243, 0xffff0000, v173
	v_lshlrev_b32_e32 v62, 16, v188
	v_and_b32_e32 v64, 0xffff0000, v188
	v_lshlrev_b32_e32 v66, 16, v189
	v_and_b32_e32 v67, 0xffff0000, v189
	v_lshlrev_b32_e32 v40, 16, v214
	v_and_b32_e32 v41, 0xffff0000, v214
	v_lshlrev_b32_e32 v42, 16, v215
	v_and_b32_e32 v43, 0xffff0000, v215
	v_cndmask_b32_e64 v44, v192, v120, s[8:9]
	v_cndmask_b32_e64 v44, v62, v44, s[6:7]
	v_cndmask_b32_e64 v44, v44, v40, s[4:5]
	v_cndmask_b32_e64 v45, v193, v121, s[8:9]
	v_cndmask_b32_e64 v45, v64, v45, s[6:7]
	v_cndmask_b32_e64 v45, v45, v41, s[4:5]
	v_cndmask_b32_e64 v46, v242, v122, s[8:9]
	v_cndmask_b32_e64 v46, v66, v46, s[6:7]
	v_cndmask_b32_e64 v46, v46, v42, s[4:5]
	v_cndmask_b32_e64 v47, v243, v123, s[8:9]
	v_cndmask_b32_e64 v47, v67, v47, s[6:7]
	v_cndmask_b32_e64 v47, v47, v43, s[4:5]
	v_pk_add_f32 v[28:29], v[28:29], v[44:45] neg_lo:[0,1] neg_hi:[0,1]
	v_pk_add_f32 v[30:31], v[30:31], v[46:47] neg_lo:[0,1] neg_hi:[0,1]
	v_lshlrev_b32_e32 v36, 16, v222
	v_and_b32_e32 v37, 0xffff0000, v222
	v_lshlrev_b32_e32 v38, 16, v223
	v_and_b32_e32 v39, 0xffff0000, v223
	v_pk_add_f32 v[28:29], v[28:29], v[36:37]
	v_pk_add_f32 v[30:31], v[30:31], v[38:39]
	s_cmp_eq_u32 s11, 0
	s_cbranch_scc1 .Ldf_np_15
	v_mov_b32_e32 v74, 0x3d9d89d9
	v_mov_b32_e32 v69, 0x3e000000
	v_mov_b32_e32 v150, 0x3e800000
	v_mov_b32_e32 v151, 0x3f000000
	v_cndmask_b32_e64 v74, v69, v74, s[8:9]
	v_cndmask_b32_e64 v74, v150, v74, s[6:7]
	v_cndmask_b32_e64 v74, v74, v151, s[4:5]
; __device__ __forceinline__ unsigned pk2(float lo, float hi) { return pg8::cvt_pk_bf16(lo, hi); }
; __device__ __forceinline__ void phase_diff(const Args& a, int l, int G, const int bid, const int tid) {
;     ...
;         for (int i = 1; i < w; ++i) { float f[8]; FETCH8(f, t0 - i);
; #pragma unroll
;             for (int e = 0; e < 8; ++e) ws_[e] += f[e]; }
;         for (int i = 0; i < 32; ++i) {
;             const int t = t0 + i; float cur[8], old[8], o[8];
;             FETCH8(cur, t); FETCH8(old, t - w + 1);
;             const float inv = 1.0f / (float)(prm ? min(t + 1, w) : w);
; #pragma unroll
;             for (int e = 0; e < 8; ++e) { ws_[e] += cur[e]; o[e] = ws_[e] * inv - cur[e]; ws_[e] -= old[e]; }
;             u32x4 pw; pw.x = pk2(o[0], o[1]); pw.y = pk2(o[2], o[3]); pw.z = pk2(o[4], o[5]); pw.w = pk2(o[6], o[7]);
;             *(u32x4*)(MIXB + (size_t)(mseq + t) * DM + n0) = pw;
.Ldf_np_15:
	v_fma_f32 v44, v74, v28, -v36
	v_fma_f32 v45, v74, v29, -v37
	v_fma_f32 v46, v74, v30, -v38
	v_fma_f32 v47, v74, v31, -v39
	v_cvt_pk_bf16_f32 v56, v44, v45
	v_cvt_pk_bf16_f32 v57, v46, v47
	global_store_dwordx2 v73, v[56:57], s[54:55] offset:0 nt
	v_lshlrev_b32_e32 v192, 16, v176
	v_and_b32_e32 v193, 0xffff0000, v176
	v_lshlrev_b32_e32 v242, 16, v177
	v_and_b32_e32 v243, 0xffff0000, v177
	v_lshlrev_b32_e32 v62, 16, v210
	v_and_b32_e32 v64, 0xffff0000, v210
	v_lshlrev_b32_e32 v66, 16, v211
	v_and_b32_e32 v67, 0xffff0000, v211
	v_lshlrev_b32_e32 v40, 16, v218
	v_and_b32_e32 v41, 0xffff0000, v218
	v_lshlrev_b32_e32 v42, 16, v219
	v_and_b32_e32 v43, 0xffff0000, v219
	v_cndmask_b32_e64 v44, v192, v124, s[8:9]
	v_cndmask_b32_e64 v44, v62, v44, s[6:7]
	v_cndmask_b32_e64 v44, v44, v40, s[4:5]
	v_cndmask_b32_e64 v45, v193, v125, s[8:9]
	v_cndmask_b32_e64 v45, v64, v45, s[6:7]
	v_cndmask_b32_e64 v45, v45, v41, s[4:5]
	v_cndmask_b32_e64 v46, v242, v126, s[8:9]
	v_cndmask_b32_e64 v46, v66, v46, s[6:7]
	v_cndmask_b32_e64 v46, v46, v42, s[4:5]
	v_cndmask_b32_e64 v47, v243, v127, s[8:9]
	v_cndmask_b32_e64 v47, v67, v47, s[6:7]
	v_cndmask_b32_e64 v47, v47, v43, s[4:5]
	v_pk_add_f32 v[28:29], v[28:29], v[44:45] neg_lo:[0,1] neg_hi:[0,1]
	v_pk_add_f32 v[30:31], v[30:31], v[46:47] neg_lo:[0,1] neg_hi:[0,1]
	v_lshlrev_b32_e32 v36, 16, v226
	v_and_b32_e32 v37, 0xffff0000, v226
	v_lshlrev_b32_e32 v38, 16, v227
	v_and_b32_e32 v39, 0xffff0000, v227
	v_pk_add_f32 v[28:29], v[28:29], v[36:37]
	v_pk_add_f32 v[30:31], v[30:31], v[38:39]
	s_cmp_eq_u32 s11, 0
	s_cbranch_scc1 .Ldf_np_16
	v_mov_b32_e32 v74, 0x3d924925
	v_mov_b32_e32 v69, 0x3e000000
	v_mov_b32_e32 v150, 0x3e800000
	v_mov_b32_e32 v151, 0x3f000000
	v_cndmask_b32_e64 v74, v69, v74, s[8:9]
	v_cndmask_b32_e64 v74, v150, v74, s[6:7]
	v_cndmask_b32_e64 v74, v74, v151, s[4:5]
.Ldf_np_16:
	v_fma_f32 v44, v74, v28, -v36
	v_fma_f32 v45, v74, v29, -v37
	v_fma_f32 v46, v74, v30, -v38
	v_fma_f32 v47, v74, v31, -v39
	v_cvt_pk_bf16_f32 v56, v44, v45
	v_cvt_pk_bf16_f32 v57, v46, v47
	global_store_dwordx2 v73, v[56:57], s[54:55] offset:2048 nt
	s_add_u32 s54, s54, 0x1000
	s_addc_u32 s55, s55, 0
	v_lshlrev_b32_e32 v192, 16, v180
	v_and_b32_e32 v193, 0xffff0000, v180
	v_lshlrev_b32_e32 v242, 16, v181
	v_and_b32_e32 v243, 0xffff0000, v181
	v_lshlrev_b32_e32 v62, 16, v214
	v_and_b32_e32 v64, 0xffff0000, v214
	v_lshlrev_b32_e32 v66, 16, v215
	v_and_b32_e32 v67, 0xffff0000, v215
	v_lshlrev_b32_e32 v40, 16, v222
	v_and_b32_e32 v41, 0xffff0000, v222
	v_lshlrev_b32_e32 v42, 16, v223
	v_and_b32_e32 v43, 0xffff0000, v223
	v_cndmask_b32_e64 v44, v192, v134, s[8:9]
	v_cndmask_b32_e64 v44, v62, v44, s[6:7]
	v_cndmask_b32_e64 v44, v44, v40, s[4:5]
	v_cndmask_b32_e64 v45, v193, v135, s[8:9]
	v_cndmask_b32_e64 v45, v64, v45, s[6:7]
	v_cndmask_b32_e64 v45, v45, v41, s[4:5]
	v_cndmask_b32_e64 v46, v242, v136, s[8:9]
	v_cndmask_b32_e64 v46, v66, v46, s[6:7]
	v_cndmask_b32_e64 v46, v46, v42, s[4:5]
	v_cndmask_b32_e64 v47, v243, v137, s[8:9]
	v_cndmask_b32_e64 v47, v67, v47, s[6:7]
	v_cndmask_b32_e64 v47, v47, v43, s[4:5]
	v_pk_add_f32 v[28:29], v[28:29], v[44:45] neg_lo:[0,1] neg_hi:[0,1]
	v_pk_add_f32 v[30:31], v[30:31], v[46:47] neg_lo:[0,1] neg_hi:[0,1]
	v_lshlrev_b32_e32 v36, 16, v230
	v_and_b32_e32 v37, 0xffff0000, v230
	v_lshlrev_b32_e32 v38, 16, v231
	v_and_b32_e32 v39, 0xffff0000, v231
	v_pk_add_f32 v[28:29], v[28:29], v[36:37]
	v_pk_add_f32 v[30:31], v[30:31], v[38:39]
	s_cmp_eq_u32 s11, 0
	s_cbranch_scc1 .Ldf_np_17
	v_mov_b32_e32 v74, 0x3d888889
	v_mov_b32_e32 v69, 0x3e000000
	v_mov_b32_e32 v150, 0x3e800000
	v_mov_b32_e32 v151, 0x3f000000
	v_cndmask_b32_e64 v74, v69, v74, s[8:9]
	v_cndmask_b32_e64 v74, v150, v74, s[6:7]
	v_cndmask_b32_e64 v74, v74, v151, s[4:5]
.Ldf_np_17:
	v_fma_f32 v44, v74, v28, -v36
	v_fma_f32 v45, v74, v29, -v37
	v_fma_f32 v46, v74, v30, -v38
	v_fma_f32 v47, v74, v31, -v39
	v_cvt_pk_bf16_f32 v56, v44, v45
	v_cvt_pk_bf16_f32 v57, v46, v47
	global_store_dwordx2 v73, v[56:57], s[54:55] offset:0 nt
	v_lshlrev_b32_e32 v192, 16, v184
	v_and_b32_e32 v193, 0xffff0000, v184
	v_lshlrev_b32_e32 v242, 16, v185
	v_and_b32_e32 v243, 0xffff0000, v185
	v_lshlrev_b32_e32 v62, 16, v218
	v_and_b32_e32 v64, 0xffff0000, v218
	v_lshlrev_b32_e32 v66, 16, v219
	v_and_b32_e32 v67, 0xffff0000, v219
	v_lshlrev_b32_e32 v40, 16, v226
	v_and_b32_e32 v41, 0xffff0000, v226
	v_lshlrev_b32_e32 v42, 16, v227
	v_and_b32_e32 v43, 0xffff0000, v227
	v_cndmask_b32_e64 v44, v192, v138, s[8:9]
	v_cndmask_b32_e64 v44, v62, v44, s[6:7]
	v_cndmask_b32_e64 v44, v44, v40, s[4:5]
	v_cndmask_b32_e64 v45, v193, v139, s[8:9]
	v_cndmask_b32_e64 v45, v64, v45, s[6:7]
	v_cndmask_b32_e64 v45, v45, v41, s[4:5]
	v_cndmask_b32_e64 v46, v242, v140, s[8:9]
	v_cndmask_b32_e64 v46, v66, v46, s[6:7]
	v_cndmask_b32_e64 v46, v46, v42, s[4:5]
	v_cndmask_b32_e64 v47, v243, v141, s[8:9]
	v_cndmask_b32_e64 v47, v67, v47, s[6:7]
	v_cndmask_b32_e64 v47, v47, v43, s[4:5]
	v_pk_add_f32 v[28:29], v[28:29], v[44:45] neg_lo:[0,1] neg_hi:[0,1]
	v_pk_add_f32 v[30:31], v[30:31], v[46:47] neg_lo:[0,1] neg_hi:[0,1]
	s_cmp_eq_u32 s11, 0
	s_cbranch_scc1 .Ldf_zh_18
	s_branch .Ldf_hd_19

; __device__ __forceinline__ unsigned pk2(float lo, float hi) { return pg8::cvt_pk_bf16(lo, hi); }
; __device__ __forceinline__ void phase_diff(const Args& a, int l, int G, const int bid, const int tid) {
;     ...
;         for (int i = 1; i < w; ++i) { float f[8]; FETCH8(f, t0 - i);
; #pragma unroll
;             for (int e = 0; e < 8; ++e) ws_[e] += f[e]; }
;         for (int i = 0; i < 32; ++i) {
;             const int t = t0 + i; float cur[8], old[8], o[8];
;             FETCH8(cur, t); FETCH8(old, t - w + 1);
;             const float inv = 1.0f / (float)(prm ? min(t + 1, w) : w);
; #pragma unroll
;             for (int e = 0; e < 8; ++e) { ws_[e] += cur[e]; o[e] = ws_[e] * inv - cur[e]; ws_[e] -= old[e]; }
;             u32x4 pw; pw.x = pk2(o[0], o[1]); pw.y = pk2(o[2], o[3]); pw.z = pk2(o[4], o[5]); pw.w = pk2(o[6], o[7]);
;             *(u32x4*)(MIXB + (size_t)(mseq + t) * DM + n0) = pw;
.Ldf_np_20:
	v_fma_f32 v44, v74, v32, -v36
	v_fma_f32 v45, v74, v33, -v37
	v_fma_f32 v46, v74, v34, -v38
	v_fma_f32 v47, v74, v35, -v39
	v_cvt_pk_bf16_f32 v56, v44, v45
	v_cvt_pk_bf16_f32 v57, v46, v47
	global_store_dwordx2 v73, v[56:57], s[54:55] offset:8 nt
	v_cndmask_b32_e64 v44, v108, v76, s[8:9]
	v_cndmask_b32_e64 v44, v124, v44, s[6:7]
	v_cndmask_b32_e64 v44, v44, v138, s[4:5]
	v_cndmask_b32_e64 v45, v109, v77, s[8:9]
	v_cndmask_b32_e64 v45, v125, v45, s[6:7]
	v_cndmask_b32_e64 v45, v45, v139, s[4:5]
	v_cndmask_b32_e64 v46, v110, v78, s[8:9]
	v_cndmask_b32_e64 v46, v126, v46, s[6:7]
	v_cndmask_b32_e64 v46, v46, v140, s[4:5]
	v_cndmask_b32_e64 v47, v111, v79, s[8:9]
	v_cndmask_b32_e64 v47, v127, v47, s[6:7]
	v_cndmask_b32_e64 v47, v47, v141, s[4:5]
	v_pk_add_f32 v[32:33], v[32:33], v[44:45] neg_lo:[0,1] neg_hi:[0,1]
	v_pk_add_f32 v[34:35], v[34:35], v[46:47] neg_lo:[0,1] neg_hi:[0,1]
	v_lshlrev_b32_e32 v36, 16, v148
	v_and_b32_e32 v37, 0xffff0000, v148
	v_lshlrev_b32_e32 v38, 16, v149
	v_and_b32_e32 v39, 0xffff0000, v149
	v_pk_add_f32 v[32:33], v[32:33], v[36:37]
	v_pk_add_f32 v[34:35], v[34:35], v[38:39]
	s_cmp_eq_u32 s11, 0
	s_cbranch_scc1 .Ldf_np_21
	v_mov_b32_e32 v74, 0x3f000000
	v_mov_b32_e32 v69, 0x3f000000
	v_mov_b32_e32 v150, 0x3f000000
	v_mov_b32_e32 v151, 0x3f000000
	v_cndmask_b32_e64 v74, v69, v74, s[8:9]
	v_cndmask_b32_e64 v74, v150, v74, s[6:7]
	v_cndmask_b32_e64 v74, v74, v151, s[4:5]
.Ldf_np_21:
	v_fma_f32 v44, v74, v32, -v36
	v_fma_f32 v45, v74, v33, -v37
	v_fma_f32 v46, v74, v34, -v38
	v_fma_f32 v47, v74, v35, -v39
	v_cvt_pk_bf16_f32 v56, v44, v45
	v_cvt_pk_bf16_f32 v57, v46, v47
	global_store_dwordx2 v73, v[56:57], s[54:55] offset:2056 nt
	s_add_u32 s54, s54, 0x1000
	s_addc_u32 s55, s55, 0
	v_lshlrev_b32_e32 v40, 16, v144
	v_and_b32_e32 v41, 0xffff0000, v144
	v_lshlrev_b32_e32 v42, 16, v145
	v_and_b32_e32 v43, 0xffff0000, v145
	v_cndmask_b32_e64 v44, v112, v80, s[8:9]
	v_cndmask_b32_e64 v44, v134, v44, s[6:7]
	v_cndmask_b32_e64 v44, v44, v40, s[4:5]
	v_cndmask_b32_e64 v45, v113, v81, s[8:9]
	v_cndmask_b32_e64 v45, v135, v45, s[6:7]
	v_cndmask_b32_e64 v45, v45, v41, s[4:5]
	v_cndmask_b32_e64 v46, v114, v82, s[8:9]
	v_cndmask_b32_e64 v46, v136, v46, s[6:7]
	v_cndmask_b32_e64 v46, v46, v42, s[4:5]
	v_cndmask_b32_e64 v47, v115, v83, s[8:9]
	v_cndmask_b32_e64 v47, v137, v47, s[6:7]
	v_cndmask_b32_e64 v47, v47, v43, s[4:5]
	v_pk_add_f32 v[32:33], v[32:33], v[44:45] neg_lo:[0,1] neg_hi:[0,1]
	v_pk_add_f32 v[34:35], v[34:35], v[46:47] neg_lo:[0,1] neg_hi:[0,1]
	v_lshlrev_b32_e32 v36, 16, v166
	v_and_b32_e32 v37, 0xffff0000, v166
	v_lshlrev_b32_e32 v38, 16, v167
	v_and_b32_e32 v39, 0xffff0000, v167
	v_pk_add_f32 v[32:33], v[32:33], v[36:37]
	v_pk_add_f32 v[34:35], v[34:35], v[38:39]
	s_cmp_eq_u32 s11, 0
	s_cbranch_scc1 .Ldf_np_22
	v_mov_b32_e32 v74, 0x3eaaaaab
	v_mov_b32_e32 v69, 0x3eaaaaab
	v_mov_b32_e32 v150, 0x3eaaaaab
	v_mov_b32_e32 v151, 0x3f000000
	v_cndmask_b32_e64 v74, v69, v74, s[8:9]
	v_cndmask_b32_e64 v74, v150, v74, s[6:7]
	v_cndmask_b32_e64 v74, v74, v151, s[4:5]
.Ldf_np_22:
	v_fma_f32 v44, v74, v32, -v36
	v_fma_f32 v45, v74, v33, -v37
	v_fma_f32 v46, v74, v34, -v38
	v_fma_f32 v47, v74, v35, -v39
	v_cvt_pk_bf16_f32 v56, v44, v45
	v_cvt_pk_bf16_f32 v57, v46, v47
	global_store_dwordx2 v73, v[56:57], s[54:55] offset:8 nt
	v_lshlrev_b32_e32 v40, 16, v148
	v_and_b32_e32 v41, 0xffff0000, v148
	v_lshlrev_b32_e32 v42, 16, v149
	v_and_b32_e32 v43, 0xffff0000, v149
	v_cndmask_b32_e64 v44, v116, v84, s[8:9]
	v_cndmask_b32_e64 v44, v138, v44, s[6:7]
	v_cndmask_b32_e64 v44, v44, v40, s[4:5]
	v_cndmask_b32_e64 v45, v117, v85, s[8:9]
	v_cndmask_b32_e64 v45, v139, v45, s[6:7]
	v_cndmask_b32_e64 v45, v45, v41, s[4:5]
	v_cndmask_b32_e64 v46, v118, v86, s[8:9]
	v_cndmask_b32_e64 v46, v140, v46, s[6:7]
	v_cndmask_b32_e64 v46, v46, v42, s[4:5]
	v_cndmask_b32_e64 v47, v119, v87, s[8:9]
	v_cndmask_b32_e64 v47, v141, v47, s[6:7]
	v_cndmask_b32_e64 v47, v47, v43, s[4:5]
	v_pk_add_f32 v[32:33], v[32:33], v[44:45] neg_lo:[0,1] neg_hi:[0,1]
	v_pk_add_f32 v[34:35], v[34:35], v[46:47] neg_lo:[0,1] neg_hi:[0,1]
	v_lshlrev_b32_e32 v36, 16, v170
	v_and_b32_e32 v37, 0xffff0000, v170
	v_lshlrev_b32_e32 v38, 16, v171
	v_and_b32_e32 v39, 0xffff0000, v171
	v_pk_add_f32 v[32:33], v[32:33], v[36:37]
	v_pk_add_f32 v[34:35], v[34:35], v[38:39]
	s_cmp_eq_u32 s11, 0
	s_cbranch_scc1 .Ldf_np_23
	v_mov_b32_e32 v74, 0x3e800000
	v_mov_b32_e32 v69, 0x3e800000
	v_mov_b32_e32 v150, 0x3e800000
	v_mov_b32_e32 v151, 0x3f000000
	v_cndmask_b32_e64 v74, v69, v74, s[8:9]
	v_cndmask_b32_e64 v74, v150, v74, s[6:7]
	v_cndmask_b32_e64 v74, v74, v151, s[4:5]
.Ldf_np_23:
	v_fma_f32 v44, v74, v32, -v36
	v_fma_f32 v45, v74, v33, -v37
	v_fma_f32 v46, v74, v34, -v38
	v_fma_f32 v47, v74, v35, -v39
	v_cvt_pk_bf16_f32 v56, v44, v45
	v_cvt_pk_bf16_f32 v57, v46, v47
	global_store_dwordx2 v73, v[56:57], s[54:55] offset:2056 nt
	s_add_u32 s54, s54, 0x1000
	s_addc_u32 s55, s55, 0
	v_lshlrev_b32_e32 v62, 16, v144
	v_and_b32_e32 v64, 0xffff0000, v144
	v_lshlrev_b32_e32 v66, 16, v145
	v_and_b32_e32 v67, 0xffff0000, v145
	v_lshlrev_b32_e32 v40, 16, v166
	v_and_b32_e32 v41, 0xffff0000, v166
	v_lshlrev_b32_e32 v42, 16, v167
	v_and_b32_e32 v43, 0xffff0000, v167
	v_cndmask_b32_e64 v44, v120, v88, s[8:9]
	v_cndmask_b32_e64 v44, v62, v44, s[6:7]
	v_cndmask_b32_e64 v44, v44, v40, s[4:5]
	v_cndmask_b32_e64 v45, v121, v89, s[8:9]
	v_cndmask_b32_e64 v45, v64, v45, s[6:7]
	v_cndmask_b32_e64 v45, v45, v41, s[4:5]
	v_cndmask_b32_e64 v46, v122, v90, s[8:9]
	v_cndmask_b32_e64 v46, v66, v46, s[6:7]
	v_cndmask_b32_e64 v46, v46, v42, s[4:5]
	v_cndmask_b32_e64 v47, v123, v91, s[8:9]
	v_cndmask_b32_e64 v47, v67, v47, s[6:7]
	v_cndmask_b32_e64 v47, v47, v43, s[4:5]
	v_pk_add_f32 v[32:33], v[32:33], v[44:45] neg_lo:[0,1] neg_hi:[0,1]
	v_pk_add_f32 v[34:35], v[34:35], v[46:47] neg_lo:[0,1] neg_hi:[0,1]
	v_lshlrev_b32_e32 v36, 16, v174
	v_and_b32_e32 v37, 0xffff0000, v174
	v_lshlrev_b32_e32 v38, 16, v175
	v_and_b32_e32 v39, 0xffff0000, v175
	v_pk_add_f32 v[32:33], v[32:33], v[36:37]
	v_pk_add_f32 v[34:35], v[34:35], v[38:39]
	s_cmp_eq_u32 s11, 0
	s_cbranch_scc1 .Ldf_np_24
	v_mov_b32_e32 v74, 0x3e4ccccd
	v_mov_b32_e32 v69, 0x3e4ccccd
	v_mov_b32_e32 v150, 0x3e800000
	v_mov_b32_e32 v151, 0x3f000000
	v_cndmask_b32_e64 v74, v69, v74, s[8:9]
	v_cndmask_b32_e64 v74, v150, v74, s[6:7]
	v_cndmask_b32_e64 v74, v74, v151, s[4:5]
; __device__ __forceinline__ unsigned pk2(float lo, float hi) { return pg8::cvt_pk_bf16(lo, hi); }
; __device__ __forceinline__ void phase_diff(const Args& a, int l, int G, const int bid, const int tid) {
;     ...
;         for (int i = 0; i < 32; ++i) {
;             const int t = t0 + i; float cur[8], old[8], o[8];
;             FETCH8(cur, t); FETCH8(old, t - w + 1);
;             const float inv = 1.0f / (float)(prm ? min(t + 1, w) : w);
; #pragma unroll
;             for (int e = 0; e < 8; ++e) { ws_[e] += cur[e]; o[e] = ws_[e] * inv - cur[e]; ws_[e] -= old[e]; }
;             u32x4 pw; pw.x = pk2(o[0], o[1]); pw.y = pk2(o[2], o[3]); pw.z = pk2(o[4], o[5]); pw.w = pk2(o[6], o[7]);
;             *(u32x4*)(MIXB + (size_t)(mseq + t) * DM + n0) = pw;
;             if (t >= L - 15) { float* hp = hout + (size_t)(t - (L - 15)) * WB + n0; *(f32x4*)hp = (f32x4){cur[0], cur[1], cur[2], cur[3]}; *(f32x4*)(hp + 4) = (f32x4){cur[4], cur[5], cur[6], cur[7]}; }
.Ldf_np_24:
	v_fma_f32 v44, v74, v32, -v36
	v_fma_f32 v45, v74, v33, -v37
	v_fma_f32 v46, v74, v34, -v38
	v_fma_f32 v47, v74, v35, -v39
	v_cvt_pk_bf16_f32 v56, v44, v45
	v_cvt_pk_bf16_f32 v57, v46, v47
	global_store_dwordx2 v73, v[56:57], s[54:55] offset:8 nt
	v_lshlrev_b32_e32 v62, 16, v148
	v_and_b32_e32 v64, 0xffff0000, v148
	v_lshlrev_b32_e32 v66, 16, v149
	v_and_b32_e32 v67, 0xffff0000, v149
	v_lshlrev_b32_e32 v40, 16, v170
	v_and_b32_e32 v41, 0xffff0000, v170
	v_lshlrev_b32_e32 v42, 16, v171
	v_and_b32_e32 v43, 0xffff0000, v171
	v_cndmask_b32_e64 v44, v124, v92, s[8:9]
	v_cndmask_b32_e64 v44, v62, v44, s[6:7]
	v_cndmask_b32_e64 v44, v44, v40, s[4:5]
	v_cndmask_b32_e64 v45, v125, v93, s[8:9]
	v_cndmask_b32_e64 v45, v64, v45, s[6:7]
	v_cndmask_b32_e64 v45, v45, v41, s[4:5]
	v_cndmask_b32_e64 v46, v126, v94, s[8:9]
	v_cndmask_b32_e64 v46, v66, v46, s[6:7]
	v_cndmask_b32_e64 v46, v46, v42, s[4:5]
	v_cndmask_b32_e64 v47, v127, v95, s[8:9]
	v_cndmask_b32_e64 v47, v67, v47, s[6:7]
	v_cndmask_b32_e64 v47, v47, v43, s[4:5]
	v_pk_add_f32 v[32:33], v[32:33], v[44:45] neg_lo:[0,1] neg_hi:[0,1]
	v_pk_add_f32 v[34:35], v[34:35], v[46:47] neg_lo:[0,1] neg_hi:[0,1]
	v_lshlrev_b32_e32 v36, 16, v178
	v_and_b32_e32 v37, 0xffff0000, v178
	v_lshlrev_b32_e32 v38, 16, v179
	v_and_b32_e32 v39, 0xffff0000, v179
	v_pk_add_f32 v[32:33], v[32:33], v[36:37]
	v_pk_add_f32 v[34:35], v[34:35], v[38:39]
	s_cmp_eq_u32 s11, 0
	s_cbranch_scc1 .Ldf_np_25
	v_mov_b32_e32 v74, 0x3e2aaaab
	v_mov_b32_e32 v69, 0x3e2aaaab
	v_mov_b32_e32 v150, 0x3e800000
	v_mov_b32_e32 v151, 0x3f000000
	v_cndmask_b32_e64 v74, v69, v74, s[8:9]
	v_cndmask_b32_e64 v74, v150, v74, s[6:7]
	v_cndmask_b32_e64 v74, v74, v151, s[4:5]
.Ldf_np_25:
	v_fma_f32 v44, v74, v32, -v36
	v_fma_f32 v45, v74, v33, -v37
	v_fma_f32 v46, v74, v34, -v38
	v_fma_f32 v47, v74, v35, -v39
	v_cvt_pk_bf16_f32 v56, v44, v45
	v_cvt_pk_bf16_f32 v57, v46, v47
	global_store_dwordx2 v73, v[56:57], s[54:55] offset:2056 nt
	s_add_u32 s54, s54, 0x1000
	s_addc_u32 s55, s55, 0
	v_lshlrev_b32_e32 v62, 16, v166
	v_and_b32_e32 v64, 0xffff0000, v166
	v_lshlrev_b32_e32 v66, 16, v167
	v_and_b32_e32 v67, 0xffff0000, v167
	v_lshlrev_b32_e32 v40, 16, v174
	v_and_b32_e32 v41, 0xffff0000, v174
	v_lshlrev_b32_e32 v42, 16, v175
	v_and_b32_e32 v43, 0xffff0000, v175
	v_cndmask_b32_e64 v44, v134, v96, s[8:9]
	v_cndmask_b32_e64 v44, v62, v44, s[6:7]
	v_cndmask_b32_e64 v44, v44, v40, s[4:5]
	v_cndmask_b32_e64 v45, v135, v97, s[8:9]
	v_cndmask_b32_e64 v45, v64, v45, s[6:7]
	v_cndmask_b32_e64 v45, v45, v41, s[4:5]
	v_cndmask_b32_e64 v46, v136, v98, s[8:9]
	v_cndmask_b32_e64 v46, v66, v46, s[6:7]
	v_cndmask_b32_e64 v46, v46, v42, s[4:5]
	v_cndmask_b32_e64 v47, v137, v99, s[8:9]
	v_cndmask_b32_e64 v47, v67, v47, s[6:7]
	v_cndmask_b32_e64 v47, v47, v43, s[4:5]
	v_pk_add_f32 v[32:33], v[32:33], v[44:45] neg_lo:[0,1] neg_hi:[0,1]
	v_pk_add_f32 v[34:35], v[34:35], v[46:47] neg_lo:[0,1] neg_hi:[0,1]
	v_lshlrev_b32_e32 v36, 16, v182
	v_and_b32_e32 v37, 0xffff0000, v182
	v_lshlrev_b32_e32 v38, 16, v183
	v_and_b32_e32 v39, 0xffff0000, v183
	v_pk_add_f32 v[32:33], v[32:33], v[36:37]
	v_pk_add_f32 v[34:35], v[34:35], v[38:39]
	s_cmp_eq_u32 s11, 0
	s_cbranch_scc1 .Ldf_np_26
	v_mov_b32_e32 v74, 0x3e124925
	v_mov_b32_e32 v69, 0x3e124925
	v_mov_b32_e32 v150, 0x3e800000
	v_mov_b32_e32 v151, 0x3f000000
	v_cndmask_b32_e64 v74, v69, v74, s[8:9]
	v_cndmask_b32_e64 v74, v150, v74, s[6:7]
	v_cndmask_b32_e64 v74, v74, v151, s[4:5]
.Ldf_np_26:
	v_fma_f32 v44, v74, v32, -v36
	v_fma_f32 v45, v74, v33, -v37
	v_fma_f32 v46, v74, v34, -v38
	v_fma_f32 v47, v74, v35, -v39
	v_cvt_pk_bf16_f32 v56, v44, v45
	v_cvt_pk_bf16_f32 v57, v46, v47
	global_store_dwordx2 v73, v[56:57], s[54:55] offset:8 nt
	v_lshlrev_b32_e32 v62, 16, v170
	v_and_b32_e32 v64, 0xffff0000, v170
	v_lshlrev_b32_e32 v66, 16, v171
	v_and_b32_e32 v67, 0xffff0000, v171
	v_lshlrev_b32_e32 v40, 16, v178
	v_and_b32_e32 v41, 0xffff0000, v178
	v_lshlrev_b32_e32 v42, 16, v179
	v_and_b32_e32 v43, 0xffff0000, v179
	v_cndmask_b32_e64 v44, v138, v100, s[8:9]
	v_cndmask_b32_e64 v44, v62, v44, s[6:7]
	v_cndmask_b32_e64 v44, v44, v40, s[4:5]
	v_cndmask_b32_e64 v45, v139, v101, s[8:9]
	v_cndmask_b32_e64 v45, v64, v45, s[6:7]
	v_cndmask_b32_e64 v45, v45, v41, s[4:5]
	v_cndmask_b32_e64 v46, v140, v102, s[8:9]
	v_cndmask_b32_e64 v46, v66, v46, s[6:7]
	v_cndmask_b32_e64 v46, v46, v42, s[4:5]
	v_cndmask_b32_e64 v47, v141, v103, s[8:9]
	v_cndmask_b32_e64 v47, v67, v47, s[6:7]
	v_cndmask_b32_e64 v47, v47, v43, s[4:5]
	v_pk_add_f32 v[32:33], v[32:33], v[44:45] neg_lo:[0,1] neg_hi:[0,1]
	v_pk_add_f32 v[34:35], v[34:35], v[46:47] neg_lo:[0,1] neg_hi:[0,1]
	v_lshlrev_b32_e32 v36, 16, v186
	v_and_b32_e32 v37, 0xffff0000, v186
	v_lshlrev_b32_e32 v38, 16, v187
	v_and_b32_e32 v39, 0xffff0000, v187
	v_pk_add_f32 v[32:33], v[32:33], v[36:37]
	v_pk_add_f32 v[34:35], v[34:35], v[38:39]
	s_cmp_eq_u32 s11, 0
	s_cbranch_scc1 .Ldf_np_27
	v_mov_b32_e32 v74, 0x3e000000
	v_mov_b32_e32 v69, 0x3e000000
	v_mov_b32_e32 v150, 0x3e800000
	v_mov_b32_e32 v151, 0x3f000000
	v_cndmask_b32_e64 v74, v69, v74, s[8:9]
	v_cndmask_b32_e64 v74, v150, v74, s[6:7]
	v_cndmask_b32_e64 v74, v74, v151, s[4:5]
; __device__ __forceinline__ unsigned pk2(float lo, float hi) { return pg8::cvt_pk_bf16(lo, hi); }
; __device__ __forceinline__ void phase_diff(const Args& a, int l, int G, const int bid, const int tid) {
;     ...
;         for (int i = 0; i < 32; ++i) {
;             const int t = t0 + i; float cur[8], old[8], o[8];
;             FETCH8(cur, t); FETCH8(old, t - w + 1);
;             const float inv = 1.0f / (float)(prm ? min(t + 1, w) : w);
; #pragma unroll
;             for (int e = 0; e < 8; ++e) { ws_[e] += cur[e]; o[e] = ws_[e] * inv - cur[e]; ws_[e] -= old[e]; }
;             u32x4 pw; pw.x = pk2(o[0], o[1]); pw.y = pk2(o[2], o[3]); pw.z = pk2(o[4], o[5]); pw.w = pk2(o[6], o[7]);
;             *(u32x4*)(MIXB + (size_t)(mseq + t) * DM + n0) = pw;
;             if (t >= L - 15) { float* hp = hout + (size_t)(t - (L - 15)) * WB + n0; *(f32x4*)hp = (f32x4){cur[0], cur[1], cur[2], cur[3]}; *(f32x4*)(hp + 4) = (f32x4){cur[4], cur[5], cur[6], cur[7]}; }
.Ldf_np_27:
	v_fma_f32 v44, v74, v32, -v36
	v_fma_f32 v45, v74, v33, -v37
	v_fma_f32 v46, v74, v34, -v38
	v_fma_f32 v47, v74, v35, -v39
	v_cvt_pk_bf16_f32 v56, v44, v45
	v_cvt_pk_bf16_f32 v57, v46, v47
	global_store_dwordx2 v73, v[56:57], s[54:55] offset:2056 nt
	s_add_u32 s54, s54, 0x1000
	s_addc_u32 s55, s55, 0
	v_lshlrev_b32_e32 v192, 16, v144
	v_and_b32_e32 v193, 0xffff0000, v144
	v_lshlrev_b32_e32 v242, 16, v145
	v_and_b32_e32 v243, 0xffff0000, v145
	v_lshlrev_b32_e32 v62, 16, v174
	v_and_b32_e32 v64, 0xffff0000, v174
	v_lshlrev_b32_e32 v66, 16, v175
	v_and_b32_e32 v67, 0xffff0000, v175
	v_lshlrev_b32_e32 v40, 16, v182
	v_and_b32_e32 v41, 0xffff0000, v182
	v_lshlrev_b32_e32 v42, 16, v183
	v_and_b32_e32 v43, 0xffff0000, v183
	v_cndmask_b32_e64 v44, v192, v104, s[8:9]
	v_cndmask_b32_e64 v44, v62, v44, s[6:7]
	v_cndmask_b32_e64 v44, v44, v40, s[4:5]
	v_cndmask_b32_e64 v45, v193, v105, s[8:9]
	v_cndmask_b32_e64 v45, v64, v45, s[6:7]
	v_cndmask_b32_e64 v45, v45, v41, s[4:5]
	v_cndmask_b32_e64 v46, v242, v106, s[8:9]
	v_cndmask_b32_e64 v46, v66, v46, s[6:7]
	v_cndmask_b32_e64 v46, v46, v42, s[4:5]
	v_cndmask_b32_e64 v47, v243, v107, s[8:9]
	v_cndmask_b32_e64 v47, v67, v47, s[6:7]
	v_cndmask_b32_e64 v47, v47, v43, s[4:5]
	v_pk_add_f32 v[32:33], v[32:33], v[44:45] neg_lo:[0,1] neg_hi:[0,1]
	v_pk_add_f32 v[34:35], v[34:35], v[46:47] neg_lo:[0,1] neg_hi:[0,1]
	v_lshlrev_b32_e32 v36, 16, v190
	v_and_b32_e32 v37, 0xffff0000, v190
	v_lshlrev_b32_e32 v38, 16, v191
	v_and_b32_e32 v39, 0xffff0000, v191
	v_pk_add_f32 v[32:33], v[32:33], v[36:37]
	v_pk_add_f32 v[34:35], v[34:35], v[38:39]
	s_cmp_eq_u32 s11, 0
	s_cbranch_scc1 .Ldf_np_28
	v_mov_b32_e32 v74, 0x3de38e39
	v_mov_b32_e32 v69, 0x3e000000
	v_mov_b32_e32 v150, 0x3e800000
	v_mov_b32_e32 v151, 0x3f000000
	v_cndmask_b32_e64 v74, v69, v74, s[8:9]
	v_cndmask_b32_e64 v74, v150, v74, s[6:7]
	v_cndmask_b32_e64 v74, v74, v151, s[4:5]
.Ldf_np_28:
	v_fma_f32 v44, v74, v32, -v36
	v_fma_f32 v45, v74, v33, -v37
	v_fma_f32 v46, v74, v34, -v38
	v_fma_f32 v47, v74, v35, -v39
	v_cvt_pk_bf16_f32 v56, v44, v45
	v_cvt_pk_bf16_f32 v57, v46, v47
	global_store_dwordx2 v73, v[56:57], s[54:55] offset:8 nt
	v_lshlrev_b32_e32 v192, 16, v148
	v_and_b32_e32 v193, 0xffff0000, v148
	v_lshlrev_b32_e32 v242, 16, v149
	v_and_b32_e32 v243, 0xffff0000, v149
	v_lshlrev_b32_e32 v62, 16, v178
	v_and_b32_e32 v64, 0xffff0000, v178
	v_lshlrev_b32_e32 v66, 16, v179
	v_and_b32_e32 v67, 0xffff0000, v179
	v_lshlrev_b32_e32 v40, 16, v186
	v_and_b32_e32 v41, 0xffff0000, v186
	v_lshlrev_b32_e32 v42, 16, v187
	v_and_b32_e32 v43, 0xffff0000, v187
	v_cndmask_b32_e64 v44, v192, v108, s[8:9]
	v_cndmask_b32_e64 v44, v62, v44, s[6:7]
	v_cndmask_b32_e64 v44, v44, v40, s[4:5]
	v_cndmask_b32_e64 v45, v193, v109, s[8:9]
	v_cndmask_b32_e64 v45, v64, v45, s[6:7]
	v_cndmask_b32_e64 v45, v45, v41, s[4:5]
	v_cndmask_b32_e64 v46, v242, v110, s[8:9]
	v_cndmask_b32_e64 v46, v66, v46, s[6:7]
	v_cndmask_b32_e64 v46, v46, v42, s[4:5]
	v_cndmask_b32_e64 v47, v243, v111, s[8:9]
	v_cndmask_b32_e64 v47, v67, v47, s[6:7]
	v_cndmask_b32_e64 v47, v47, v43, s[4:5]
	v_pk_add_f32 v[32:33], v[32:33], v[44:45] neg_lo:[0,1] neg_hi:[0,1]
	v_pk_add_f32 v[34:35], v[34:35], v[46:47] neg_lo:[0,1] neg_hi:[0,1]
	v_lshlrev_b32_e32 v36, 16, v212
	v_and_b32_e32 v37, 0xffff0000, v212
	v_lshlrev_b32_e32 v38, 16, v213
	v_and_b32_e32 v39, 0xffff0000, v213
	v_pk_add_f32 v[32:33], v[32:33], v[36:37]
	v_pk_add_f32 v[34:35], v[34:35], v[38:39]
	s_cmp_eq_u32 s11, 0
	s_cbranch_scc1 .Ldf_np_29
	v_mov_b32_e32 v74, 0x3dcccccd
	v_mov_b32_e32 v69, 0x3e000000
	v_mov_b32_e32 v150, 0x3e800000
	v_mov_b32_e32 v151, 0x3f000000
	v_cndmask_b32_e64 v74, v69, v74, s[8:9]
	v_cndmask_b32_e64 v74, v150, v74, s[6:7]
	v_cndmask_b32_e64 v74, v74, v151, s[4:5]
.Ldf_np_29:
	v_fma_f32 v44, v74, v32, -v36
	v_fma_f32 v45, v74, v33, -v37
	v_fma_f32 v46, v74, v34, -v38
	v_fma_f32 v47, v74, v35, -v39
	v_cvt_pk_bf16_f32 v56, v44, v45
	v_cvt_pk_bf16_f32 v57, v46, v47
	global_store_dwordx2 v73, v[56:57], s[54:55] offset:2056 nt
	s_add_u32 s54, s54, 0x1000
	s_addc_u32 s55, s55, 0
	v_lshlrev_b32_e32 v192, 16, v166
	v_and_b32_e32 v193, 0xffff0000, v166
	v_lshlrev_b32_e32 v242, 16, v167
	v_and_b32_e32 v243, 0xffff0000, v167
	v_lshlrev_b32_e32 v62, 16, v182
	v_and_b32_e32 v64, 0xffff0000, v182
	v_lshlrev_b32_e32 v66, 16, v183
	v_and_b32_e32 v67, 0xffff0000, v183
	v_lshlrev_b32_e32 v40, 16, v190
	v_and_b32_e32 v41, 0xffff0000, v190
	v_lshlrev_b32_e32 v42, 16, v191
	v_and_b32_e32 v43, 0xffff0000, v191
	v_cndmask_b32_e64 v44, v192, v112, s[8:9]
	v_cndmask_b32_e64 v44, v62, v44, s[6:7]
	v_cndmask_b32_e64 v44, v44, v40, s[4:5]
	v_cndmask_b32_e64 v45, v193, v113, s[8:9]
	v_cndmask_b32_e64 v45, v64, v45, s[6:7]
	v_cndmask_b32_e64 v45, v45, v41, s[4:5]
	v_cndmask_b32_e64 v46, v242, v114, s[8:9]
	v_cndmask_b32_e64 v46, v66, v46, s[6:7]
	v_cndmask_b32_e64 v46, v46, v42, s[4:5]
	v_cndmask_b32_e64 v47, v243, v115, s[8:9]
	v_cndmask_b32_e64 v47, v67, v47, s[6:7]
	v_cndmask_b32_e64 v47, v47, v43, s[4:5]
	v_pk_add_f32 v[32:33], v[32:33], v[44:45] neg_lo:[0,1] neg_hi:[0,1]
	v_pk_add_f32 v[34:35], v[34:35], v[46:47] neg_lo:[0,1] neg_hi:[0,1]
	v_lshlrev_b32_e32 v36, 16, v216
	v_and_b32_e32 v37, 0xffff0000, v216
	v_lshlrev_b32_e32 v38, 16, v217
	v_and_b32_e32 v39, 0xffff0000, v217
	v_pk_add_f32 v[32:33], v[32:33], v[36:37]
	v_pk_add_f32 v[34:35], v[34:35], v[38:39]
	s_cmp_eq_u32 s11, 0
	s_cbranch_scc1 .Ldf_np_30
	v_mov_b32_e32 v74, 0x3dba2e8c
	v_mov_b32_e32 v69, 0x3e000000
	v_mov_b32_e32 v150, 0x3e800000
	v_mov_b32_e32 v151, 0x3f000000
	v_cndmask_b32_e64 v74, v69, v74, s[8:9]
	v_cndmask_b32_e64 v74, v150, v74, s[6:7]
	v_cndmask_b32_e64 v74, v74, v151, s[4:5]
; __device__ __forceinline__ unsigned pk2(float lo, float hi) { return pg8::cvt_pk_bf16(lo, hi); }
; __device__ __forceinline__ void phase_diff(const Args& a, int l, int G, const int bid, const int tid) {
;     ...
;         for (int i = 0; i < 32; ++i) {
;             const int t = t0 + i; float cur[8], old[8], o[8];
;             FETCH8(cur, t); FETCH8(old, t - w + 1);
;             const float inv = 1.0f / (float)(prm ? min(t + 1, w) : w);
; #pragma unroll
;             for (int e = 0; e < 8; ++e) { ws_[e] += cur[e]; o[e] = ws_[e] * inv - cur[e]; ws_[e] -= old[e]; }
;             u32x4 pw; pw.x = pk2(o[0], o[1]); pw.y = pk2(o[2], o[3]); pw.z = pk2(o[4], o[5]); pw.w = pk2(o[6], o[7]);
;             *(u32x4*)(MIXB + (size_t)(mseq + t) * DM + n0) = pw;
;             if (t >= L - 15) { float* hp = hout + (size_t)(t - (L - 15)) * WB + n0; *(f32x4*)hp = (f32x4){cur[0], cur[1], cur[2], cur[3]}; *(f32x4*)(hp + 4) = (f32x4){cur[4], cur[5], cur[6], cur[7]}; }
.Ldf_np_30:
	v_fma_f32 v44, v74, v32, -v36
	v_fma_f32 v45, v74, v33, -v37
	v_fma_f32 v46, v74, v34, -v38
	v_fma_f32 v47, v74, v35, -v39
	v_cvt_pk_bf16_f32 v56, v44, v45
	v_cvt_pk_bf16_f32 v57, v46, v47
	global_store_dwordx2 v73, v[56:57], s[54:55] offset:8 nt
	v_lshlrev_b32_e32 v192, 16, v170
	v_and_b32_e32 v193, 0xffff0000, v170
	v_lshlrev_b32_e32 v242, 16, v171
	v_and_b32_e32 v243, 0xffff0000, v171
	v_lshlrev_b32_e32 v62, 16, v186
	v_and_b32_e32 v64, 0xffff0000, v186
	v_lshlrev_b32_e32 v66, 16, v187
	v_and_b32_e32 v67, 0xffff0000, v187
	v_lshlrev_b32_e32 v40, 16, v212
	v_and_b32_e32 v41, 0xffff0000, v212
	v_lshlrev_b32_e32 v42, 16, v213
	v_and_b32_e32 v43, 0xffff0000, v213
	v_cndmask_b32_e64 v44, v192, v116, s[8:9]
	v_cndmask_b32_e64 v44, v62, v44, s[6:7]
	v_cndmask_b32_e64 v44, v44, v40, s[4:5]
	v_cndmask_b32_e64 v45, v193, v117, s[8:9]
	v_cndmask_b32_e64 v45, v64, v45, s[6:7]
	v_cndmask_b32_e64 v45, v45, v41, s[4:5]
	v_cndmask_b32_e64 v46, v242, v118, s[8:9]
	v_cndmask_b32_e64 v46, v66, v46, s[6:7]
	v_cndmask_b32_e64 v46, v46, v42, s[4:5]
	v_cndmask_b32_e64 v47, v243, v119, s[8:9]
	v_cndmask_b32_e64 v47, v67, v47, s[6:7]
	v_cndmask_b32_e64 v47, v47, v43, s[4:5]
	v_pk_add_f32 v[32:33], v[32:33], v[44:45] neg_lo:[0,1] neg_hi:[0,1]
	v_pk_add_f32 v[34:35], v[34:35], v[46:47] neg_lo:[0,1] neg_hi:[0,1]
	v_lshlrev_b32_e32 v36, 16, v220
	v_and_b32_e32 v37, 0xffff0000, v220
	v_lshlrev_b32_e32 v38, 16, v221
	v_and_b32_e32 v39, 0xffff0000, v221
	v_pk_add_f32 v[32:33], v[32:33], v[36:37]
	v_pk_add_f32 v[34:35], v[34:35], v[38:39]
	s_cmp_eq_u32 s11, 0
	s_cbranch_scc1 .Ldf_np_31
	v_mov_b32_e32 v74, 0x3daaaaab
	v_mov_b32_e32 v69, 0x3e000000
	v_mov_b32_e32 v150, 0x3e800000
	v_mov_b32_e32 v151, 0x3f000000
	v_cndmask_b32_e64 v74, v69, v74, s[8:9]
	v_cndmask_b32_e64 v74, v150, v74, s[6:7]
	v_cndmask_b32_e64 v74, v74, v151, s[4:5]
.Ldf_np_31:
	v_fma_f32 v44, v74, v32, -v36
	v_fma_f32 v45, v74, v33, -v37
	v_fma_f32 v46, v74, v34, -v38
	v_fma_f32 v47, v74, v35, -v39
	v_cvt_pk_bf16_f32 v56, v44, v45
	v_cvt_pk_bf16_f32 v57, v46, v47
	global_store_dwordx2 v73, v[56:57], s[54:55] offset:2056 nt
	s_add_u32 s54, s54, 0x1000
	s_addc_u32 s55, s55, 0
	v_lshlrev_b32_e32 v192, 16, v174
	v_and_b32_e32 v193, 0xffff0000, v174
	v_lshlrev_b32_e32 v242, 16, v175
	v_and_b32_e32 v243, 0xffff0000, v175
	v_lshlrev_b32_e32 v62, 16, v190
	v_and_b32_e32 v64, 0xffff0000, v190
	v_lshlrev_b32_e32 v66, 16, v191
	v_and_b32_e32 v67, 0xffff0000, v191
	v_lshlrev_b32_e32 v40, 16, v216
	v_and_b32_e32 v41, 0xffff0000, v216
	v_lshlrev_b32_e32 v42, 16, v217
	v_and_b32_e32 v43, 0xffff0000, v217
	v_cndmask_b32_e64 v44, v192, v120, s[8:9]
	v_cndmask_b32_e64 v44, v62, v44, s[6:7]
	v_cndmask_b32_e64 v44, v44, v40, s[4:5]
	v_cndmask_b32_e64 v45, v193, v121, s[8:9]
	v_cndmask_b32_e64 v45, v64, v45, s[6:7]
	v_cndmask_b32_e64 v45, v45, v41, s[4:5]
	v_cndmask_b32_e64 v46, v242, v122, s[8:9]
	v_cndmask_b32_e64 v46, v66, v46, s[6:7]
	v_cndmask_b32_e64 v46, v46, v42, s[4:5]
	v_cndmask_b32_e64 v47, v243, v123, s[8:9]
	v_cndmask_b32_e64 v47, v67, v47, s[6:7]
	v_cndmask_b32_e64 v47, v47, v43, s[4:5]
	v_pk_add_f32 v[32:33], v[32:33], v[44:45] neg_lo:[0,1] neg_hi:[0,1]
	v_pk_add_f32 v[34:35], v[34:35], v[46:47] neg_lo:[0,1] neg_hi:[0,1]
	v_lshlrev_b32_e32 v36, 16, v224
	v_and_b32_e32 v37, 0xffff0000, v224
	v_lshlrev_b32_e32 v38, 16, v225
	v_and_b32_e32 v39, 0xffff0000, v225
	v_pk_add_f32 v[32:33], v[32:33], v[36:37]
	v_pk_add_f32 v[34:35], v[34:35], v[38:39]
	s_cmp_eq_u32 s11, 0
	s_cbranch_scc1 .Ldf_np_32
	v_mov_b32_e32 v74, 0x3d9d89d9
	v_mov_b32_e32 v69, 0x3e000000
	v_mov_b32_e32 v150, 0x3e800000
	v_mov_b32_e32 v151, 0x3f000000
	v_cndmask_b32_e64 v74, v69, v74, s[8:9]
	v_cndmask_b32_e64 v74, v150, v74, s[6:7]
	v_cndmask_b32_e64 v74, v74, v151, s[4:5]
.Ldf_np_32:
	v_fma_f32 v44, v74, v32, -v36
	v_fma_f32 v45, v74, v33, -v37
	v_fma_f32 v46, v74, v34, -v38
	v_fma_f32 v47, v74, v35, -v39
	v_cvt_pk_bf16_f32 v56, v44, v45
	v_cvt_pk_bf16_f32 v57, v46, v47
	global_store_dwordx2 v73, v[56:57], s[54:55] offset:8 nt
	v_lshlrev_b32_e32 v192, 16, v178
	v_and_b32_e32 v193, 0xffff0000, v178
	v_lshlrev_b32_e32 v242, 16, v179
	v_and_b32_e32 v243, 0xffff0000, v179
	v_lshlrev_b32_e32 v62, 16, v212
	v_and_b32_e32 v64, 0xffff0000, v212
	v_lshlrev_b32_e32 v66, 16, v213
	v_and_b32_e32 v67, 0xffff0000, v213
	v_lshlrev_b32_e32 v40, 16, v220
	v_and_b32_e32 v41, 0xffff0000, v220
	v_lshlrev_b32_e32 v42, 16, v221
	v_and_b32_e32 v43, 0xffff0000, v221
	v_cndmask_b32_e64 v44, v192, v124, s[8:9]
	v_cndmask_b32_e64 v44, v62, v44, s[6:7]
	v_cndmask_b32_e64 v44, v44, v40, s[4:5]
	v_cndmask_b32_e64 v45, v193, v125, s[8:9]
	v_cndmask_b32_e64 v45, v64, v45, s[6:7]
	v_cndmask_b32_e64 v45, v45, v41, s[4:5]
	v_cndmask_b32_e64 v46, v242, v126, s[8:9]
	v_cndmask_b32_e64 v46, v66, v46, s[6:7]
	v_cndmask_b32_e64 v46, v46, v42, s[4:5]
	v_cndmask_b32_e64 v47, v243, v127, s[8:9]
	v_cndmask_b32_e64 v47, v67, v47, s[6:7]
	v_cndmask_b32_e64 v47, v47, v43, s[4:5]
	v_pk_add_f32 v[32:33], v[32:33], v[44:45] neg_lo:[0,1] neg_hi:[0,1]
	v_pk_add_f32 v[34:35], v[34:35], v[46:47] neg_lo:[0,1] neg_hi:[0,1]
	v_lshlrev_b32_e32 v36, 16, v228
	v_and_b32_e32 v37, 0xffff0000, v228
	v_lshlrev_b32_e32 v38, 16, v229
	v_and_b32_e32 v39, 0xffff0000, v229
	v_pk_add_f32 v[32:33], v[32:33], v[36:37]
	v_pk_add_f32 v[34:35], v[34:35], v[38:39]
	s_cmp_eq_u32 s11, 0
	s_cbranch_scc1 .Ldf_np_33
	v_mov_b32_e32 v74, 0x3d924925
	v_mov_b32_e32 v69, 0x3e000000
	v_mov_b32_e32 v150, 0x3e800000
	v_mov_b32_e32 v151, 0x3f000000
	v_cndmask_b32_e64 v74, v69, v74, s[8:9]
	v_cndmask_b32_e64 v74, v150, v74, s[6:7]
	v_cndmask_b32_e64 v74, v74, v151, s[4:5]
; __device__ __forceinline__ unsigned pk2(float lo, float hi) { return pg8::cvt_pk_bf16(lo, hi); }
; #define UNPK8(dst, _w) do { dst[0] = pg8::bf_lo(_w.x); dst[1] = pg8::bf_hi(_w.x); dst[2] = pg8::bf_lo(_w.y); dst[3] = pg8::bf_hi(_w.y); dst[4] = pg8::bf_lo(_w.z); dst[5] = pg8::bf_hi(_w.z); dst[6] = pg8::bf_lo(_w.w); dst[7] = pg8::bf_hi(_w.w); } while (0)
; __device__ __forceinline__ void phase_diff(const Args& a, int l, int G, const int bid, const int tid) {
;     ...
;             for (int i0 = 0; i0 < 32; i0 += 4) {
;                 u32x4 cw[4], ow[4];
; #pragma unroll
;                 for (int k = 0; k < 4; ++k) { cw[k] = *(const u32x4*)(ub + (size_t)(i0 + k) * WB); ow[k] = *(const u32x4*)(ub + (size_t)(i0 + k - w + 1) * WB); }
; #pragma unroll
;                 for (int k = 0; k < 4; ++k) {
;                     const int t = t0 + i0 + k; float cur[8], old[8], o[8];
;                     UNPK8(cur, cw[k]); UNPK8(old, ow[k]);
; #pragma unroll
;                     for (int e = 0; e < 8; ++e) { ws_[e] += cur[e]; o[e] = ws_[e] * inv - cur[e]; ws_[e] -= old[e]; }
;                     u32x4 pw; pw.x = pk2(o[0], o[1]); pw.y = pk2(o[2], o[3]); pw.z = pk2(o[4], o[5]); pw.w = pk2(o[6], o[7]);
;                     *(u32x4*)(MIXB + (size_t)(mseq + t) * DM + n0) = pw;
;                     if (t >= L - 15) { float* hp = hout + (size_t)(t - (L - 15)) * WB + n0; *(f32x4*)hp = (f32x4){cur[0], cur[1], cur[2], cur[3]}; *(f32x4*)(hp + 4) = (f32x4){cur[4], cur[5], cur[6], cur[7]}; }
;     ...
;         for (int i = 0; i < 32; ++i) {
;             const int t = t0 + i; float cur[8], old[8], o[8];
;             FETCH8(cur, t); FETCH8(old, t - w + 1);
;             const float inv = 1.0f / (float)(prm ? min(t + 1, w) : w);
; #pragma unroll
;             for (int e = 0; e < 8; ++e) { ws_[e] += cur[e]; o[e] = ws_[e] * inv - cur[e]; ws_[e] -= old[e]; }
;             u32x4 pw; pw.x = pk2(o[0], o[1]); pw.y = pk2(o[2], o[3]); pw.z = pk2(o[4], o[5]); pw.w = pk2(o[6], o[7]);
;             *(u32x4*)(MIXB + (size_t)(mseq + t) * DM + n0) = pw;
;             if (t >= L - 15) { float* hp = hout + (size_t)(t - (L - 15)) * WB + n0; *(f32x4*)hp = (f32x4){cur[0], cur[1], cur[2], cur[3]}; *(f32x4*)(hp + 4) = (f32x4){cur[4], cur[5], cur[6], cur[7]}; }
.Ldf_np_33:
	v_fma_f32 v44, v74, v32, -v36
	v_fma_f32 v45, v74, v33, -v37
	v_fma_f32 v46, v74, v34, -v38
	v_fma_f32 v47, v74, v35, -v39
	v_cvt_pk_bf16_f32 v56, v44, v45
	v_cvt_pk_bf16_f32 v57, v46, v47
	global_store_dwordx2 v73, v[56:57], s[54:55] offset:2056 nt
	s_add_u32 s54, s54, 0x1000
	s_addc_u32 s55, s55, 0
	v_lshlrev_b32_e32 v192, 16, v182
	v_and_b32_e32 v193, 0xffff0000, v182
	v_lshlrev_b32_e32 v242, 16, v183
	v_and_b32_e32 v243, 0xffff0000, v183
	v_lshlrev_b32_e32 v62, 16, v216
	v_and_b32_e32 v64, 0xffff0000, v216
	v_lshlrev_b32_e32 v66, 16, v217
	v_and_b32_e32 v67, 0xffff0000, v217
	v_lshlrev_b32_e32 v40, 16, v224
	v_and_b32_e32 v41, 0xffff0000, v224
	v_lshlrev_b32_e32 v42, 16, v225
	v_and_b32_e32 v43, 0xffff0000, v225
	v_cndmask_b32_e64 v44, v192, v134, s[8:9]
	v_cndmask_b32_e64 v44, v62, v44, s[6:7]
	v_cndmask_b32_e64 v44, v44, v40, s[4:5]
	v_cndmask_b32_e64 v45, v193, v135, s[8:9]
	v_cndmask_b32_e64 v45, v64, v45, s[6:7]
	v_cndmask_b32_e64 v45, v45, v41, s[4:5]
	v_cndmask_b32_e64 v46, v242, v136, s[8:9]
	v_cndmask_b32_e64 v46, v66, v46, s[6:7]
	v_cndmask_b32_e64 v46, v46, v42, s[4:5]
	v_cndmask_b32_e64 v47, v243, v137, s[8:9]
	v_cndmask_b32_e64 v47, v67, v47, s[6:7]
	v_cndmask_b32_e64 v47, v47, v43, s[4:5]
	v_pk_add_f32 v[32:33], v[32:33], v[44:45] neg_lo:[0,1] neg_hi:[0,1]
	v_pk_add_f32 v[34:35], v[34:35], v[46:47] neg_lo:[0,1] neg_hi:[0,1]
	v_lshlrev_b32_e32 v36, 16, v232
	v_and_b32_e32 v37, 0xffff0000, v232
	v_lshlrev_b32_e32 v38, 16, v233
	v_and_b32_e32 v39, 0xffff0000, v233
	v_pk_add_f32 v[32:33], v[32:33], v[36:37]
	v_pk_add_f32 v[34:35], v[34:35], v[38:39]
	s_cmp_eq_u32 s11, 0
	s_cbranch_scc1 .Ldf_np_34
	v_mov_b32_e32 v74, 0x3d888889
	v_mov_b32_e32 v69, 0x3e000000
	v_mov_b32_e32 v150, 0x3e800000
	v_mov_b32_e32 v151, 0x3f000000
	v_cndmask_b32_e64 v74, v69, v74, s[8:9]
	v_cndmask_b32_e64 v74, v150, v74, s[6:7]
	v_cndmask_b32_e64 v74, v74, v151, s[4:5]
.Ldf_np_34:
	v_fma_f32 v44, v74, v32, -v36
	v_fma_f32 v45, v74, v33, -v37
	v_fma_f32 v46, v74, v34, -v38
	v_fma_f32 v47, v74, v35, -v39
	v_cvt_pk_bf16_f32 v56, v44, v45
	v_cvt_pk_bf16_f32 v57, v46, v47
	global_store_dwordx2 v73, v[56:57], s[54:55] offset:8 nt
	v_lshlrev_b32_e32 v192, 16, v186
	v_and_b32_e32 v193, 0xffff0000, v186
	v_lshlrev_b32_e32 v242, 16, v187
	v_and_b32_e32 v243, 0xffff0000, v187
	v_lshlrev_b32_e32 v62, 16, v220
	v_and_b32_e32 v64, 0xffff0000, v220
	v_lshlrev_b32_e32 v66, 16, v221
	v_and_b32_e32 v67, 0xffff0000, v221
	v_lshlrev_b32_e32 v40, 16, v228
	v_and_b32_e32 v41, 0xffff0000, v228
	v_lshlrev_b32_e32 v42, 16, v229
	v_and_b32_e32 v43, 0xffff0000, v229
	v_cndmask_b32_e64 v44, v192, v138, s[8:9]
	v_cndmask_b32_e64 v44, v62, v44, s[6:7]
	v_cndmask_b32_e64 v44, v44, v40, s[4:5]
	v_cndmask_b32_e64 v45, v193, v139, s[8:9]
	v_cndmask_b32_e64 v45, v64, v45, s[6:7]
	v_cndmask_b32_e64 v45, v45, v41, s[4:5]
	v_cndmask_b32_e64 v46, v242, v140, s[8:9]
	v_cndmask_b32_e64 v46, v66, v46, s[6:7]
	v_cndmask_b32_e64 v46, v46, v42, s[4:5]
	v_cndmask_b32_e64 v47, v243, v141, s[8:9]
	v_cndmask_b32_e64 v47, v67, v47, s[6:7]
	v_cndmask_b32_e64 v47, v47, v43, s[4:5]
	v_pk_add_f32 v[32:33], v[32:33], v[44:45] neg_lo:[0,1] neg_hi:[0,1]
	v_pk_add_f32 v[34:35], v[34:35], v[46:47] neg_lo:[0,1] neg_hi:[0,1]
	global_load_dwordx4 v[76:79], v73, s[16:17] offset:-4096
	global_load_dwordx4 v[80:83], v73, s[16:17] offset:-3072
	global_load_dwordx4 v[84:87], v73, s[16:17] offset:-2048
	global_load_dwordx4 v[88:91], v73, s[16:17] offset:-1024
	global_load_dwordx4 v[92:95], v73, s[16:17] offset:0
	global_load_dwordx4 v[96:99], v73, s[16:17] offset:1024
	global_load_dwordx4 v[100:103], v73, s[16:17] offset:2048
	global_load_dwordx4 v[104:107], v73, s[16:17] offset:3072
	s_add_u32 s34, s34, 0x7000
	s_addc_u32 s35, s35, 0
.Ldf_tail:
	v_lshlrev_b32_e32 v36, 16, v234
	v_and_b32_e32 v37, 0xffff0000, v234
	v_lshlrev_b32_e32 v38, 16, v235
	v_and_b32_e32 v39, 0xffff0000, v235
	v_lshlrev_b32_e32 v40, 16, v236
	v_and_b32_e32 v41, 0xffff0000, v236
	v_lshlrev_b32_e32 v42, 16, v237
	v_and_b32_e32 v43, 0xffff0000, v237
	v_pk_add_f32 v[28:29], v[28:29], v[36:37]
	v_pk_add_f32 v[30:31], v[30:31], v[38:39]
	v_pk_add_f32 v[32:33], v[32:33], v[40:41]
	v_pk_add_f32 v[34:35], v[34:35], v[42:43]
	v_fma_f32 v44, v72, v28, -v36
	v_fma_f32 v45, v72, v29, -v37
	v_fma_f32 v46, v72, v30, -v38
	v_fma_f32 v47, v72, v31, -v39
	v_fma_f32 v52, v72, v32, -v40
	v_fma_f32 v53, v72, v33, -v41
	v_fma_f32 v54, v72, v34, -v42
	v_fma_f32 v55, v72, v35, -v43
	v_cvt_pk_bf16_f32 v56, v44, v45
	v_cvt_pk_bf16_f32 v57, v46, v47
	v_cvt_pk_bf16_f32 v58, v52, v53
	v_cvt_pk_bf16_f32 v59, v54, v55
	global_store_dwordx4 v73, v[56:59], s[34:35] offset:2048 nt
	s_add_u32 s34, s34, 0x1000
	s_addc_u32 s35, s35, 0
	v_cndmask_b32_e64 v61, v188, v142, s[8:9]
	v_cndmask_b32_e64 v61, v222, v61, s[6:7]
	v_cndmask_b32_e64 v61, v61, v230, s[4:5]
	v_cndmask_b32_e64 v63, v189, v143, s[8:9]
	v_cndmask_b32_e64 v63, v223, v63, s[6:7]
	v_cndmask_b32_e64 v63, v63, v231, s[4:5]
	v_cndmask_b32_e64 v65, v190, v144, s[8:9]
	v_cndmask_b32_e64 v65, v224, v65, s[6:7]
	v_cndmask_b32_e64 v65, v65, v232, s[4:5]
	v_cndmask_b32_e64 v68, v191, v145, s[8:9]
	v_cndmask_b32_e64 v68, v225, v68, s[6:7]
	v_cndmask_b32_e64 v68, v68, v233, s[4:5]
	v_lshlrev_b32_e32 v44, 16, v61
	v_and_b32_e32 v45, 0xffff0000, v61
	v_lshlrev_b32_e32 v46, 16, v63
	v_and_b32_e32 v47, 0xffff0000, v63
	v_lshlrev_b32_e32 v52, 16, v65
	v_and_b32_e32 v53, 0xffff0000, v65
	v_lshlrev_b32_e32 v54, 16, v68
	v_and_b32_e32 v55, 0xffff0000, v68
	v_pk_add_f32 v[28:29], v[28:29], v[44:45] neg_lo:[0,1] neg_hi:[0,1]
	v_pk_add_f32 v[30:31], v[30:31], v[46:47] neg_lo:[0,1] neg_hi:[0,1]
; __device__ __forceinline__ unsigned pk2(float lo, float hi) { return pg8::cvt_pk_bf16(lo, hi); }
; #define UNPK8(dst, _w) do { dst[0] = pg8::bf_lo(_w.x); dst[1] = pg8::bf_hi(_w.x); dst[2] = pg8::bf_lo(_w.y); dst[3] = pg8::bf_hi(_w.y); dst[4] = pg8::bf_lo(_w.z); dst[5] = pg8::bf_hi(_w.z); dst[6] = pg8::bf_lo(_w.w); dst[7] = pg8::bf_hi(_w.w); } while (0)
; __device__ __forceinline__ void phase_diff(const Args& a, int l, int G, const int bid, const int tid) {
;     ...
;             for (int i0 = 0; i0 < 32; i0 += 4) {
;                 u32x4 cw[4], ow[4];
; #pragma unroll
;                 for (int k = 0; k < 4; ++k) { cw[k] = *(const u32x4*)(ub + (size_t)(i0 + k) * WB); ow[k] = *(const u32x4*)(ub + (size_t)(i0 + k - w + 1) * WB); }
; #pragma unroll
;                 for (int k = 0; k < 4; ++k) {
;                     const int t = t0 + i0 + k; float cur[8], old[8], o[8];
;                     UNPK8(cur, cw[k]); UNPK8(old, ow[k]);
; #pragma unroll
;                     for (int e = 0; e < 8; ++e) { ws_[e] += cur[e]; o[e] = ws_[e] * inv - cur[e]; ws_[e] -= old[e]; }
;                     u32x4 pw; pw.x = pk2(o[0], o[1]); pw.y = pk2(o[2], o[3]); pw.z = pk2(o[4], o[5]); pw.w = pk2(o[6], o[7]);
;                     *(u32x4*)(MIXB + (size_t)(mseq + t) * DM + n0) = pw;
;                     if (t >= L - 15) { float* hp = hout + (size_t)(t - (L - 15)) * WB + n0; *(f32x4*)hp = (f32x4){cur[0], cur[1], cur[2], cur[3]}; *(f32x4*)(hp + 4) = (f32x4){cur[4], cur[5], cur[6], cur[7]}; }
	v_pk_add_f32 v[32:33], v[32:33], v[52:53] neg_lo:[0,1] neg_hi:[0,1]
	v_pk_add_f32 v[34:35], v[34:35], v[54:55] neg_lo:[0,1] neg_hi:[0,1]
	v_lshlrev_b32_e32 v36, 16, v238
	v_and_b32_e32 v37, 0xffff0000, v238
	v_lshlrev_b32_e32 v38, 16, v239
	v_and_b32_e32 v39, 0xffff0000, v239
	v_lshlrev_b32_e32 v40, 16, v240
	v_and_b32_e32 v41, 0xffff0000, v240
	v_lshlrev_b32_e32 v42, 16, v241
	v_and_b32_e32 v43, 0xffff0000, v241
	v_pk_add_f32 v[28:29], v[28:29], v[36:37]
	v_pk_add_f32 v[30:31], v[30:31], v[38:39]
	v_pk_add_f32 v[32:33], v[32:33], v[40:41]
	v_pk_add_f32 v[34:35], v[34:35], v[42:43]
	v_fma_f32 v44, v72, v28, -v36
	v_fma_f32 v45, v72, v29, -v37
	v_fma_f32 v46, v72, v30, -v38
	v_fma_f32 v47, v72, v31, -v39
	v_fma_f32 v52, v72, v32, -v40
	v_fma_f32 v53, v72, v33, -v41
	v_fma_f32 v54, v72, v34, -v42
	v_fma_f32 v55, v72, v35, -v43
	v_cvt_pk_bf16_f32 v56, v44, v45
	v_cvt_pk_bf16_f32 v57, v46, v47
	v_cvt_pk_bf16_f32 v58, v52, v53
	v_cvt_pk_bf16_f32 v59, v54, v55
	global_store_dwordx4 v73, v[56:59], s[34:35] offset:0 nt
	v_cndmask_b32_e64 v61, v210, v146, s[8:9]
	v_cndmask_b32_e64 v61, v226, v61, s[6:7]
	v_cndmask_b32_e64 v61, v61, v234, s[4:5]
	v_cndmask_b32_e64 v63, v211, v147, s[8:9]
	v_cndmask_b32_e64 v63, v227, v63, s[6:7]
	v_cndmask_b32_e64 v63, v63, v235, s[4:5]
	v_cndmask_b32_e64 v65, v212, v148, s[8:9]
	v_cndmask_b32_e64 v65, v228, v65, s[6:7]
	v_cndmask_b32_e64 v65, v65, v236, s[4:5]
	v_cndmask_b32_e64 v68, v213, v149, s[8:9]
	v_cndmask_b32_e64 v68, v229, v68, s[6:7]
	v_cndmask_b32_e64 v68, v68, v237, s[4:5]
	v_lshlrev_b32_e32 v44, 16, v61
	v_and_b32_e32 v45, 0xffff0000, v61
	v_lshlrev_b32_e32 v46, 16, v63
	v_and_b32_e32 v47, 0xffff0000, v63
	v_lshlrev_b32_e32 v52, 16, v65
	v_and_b32_e32 v53, 0xffff0000, v65
	v_lshlrev_b32_e32 v54, 16, v68
	v_and_b32_e32 v55, 0xffff0000, v68
	v_pk_add_f32 v[28:29], v[28:29], v[44:45] neg_lo:[0,1] neg_hi:[0,1]
	v_pk_add_f32 v[30:31], v[30:31], v[46:47] neg_lo:[0,1] neg_hi:[0,1]
	v_pk_add_f32 v[32:33], v[32:33], v[52:53] neg_lo:[0,1] neg_hi:[0,1]
	v_pk_add_f32 v[34:35], v[34:35], v[54:55] neg_lo:[0,1] neg_hi:[0,1]
	v_lshlrev_b32_e32 v36, 16, v0
	v_and_b32_e32 v37, 0xffff0000, v0
	v_lshlrev_b32_e32 v38, 16, v1
	v_and_b32_e32 v39, 0xffff0000, v1
	v_lshlrev_b32_e32 v40, 16, v2
	v_and_b32_e32 v41, 0xffff0000, v2
	v_lshlrev_b32_e32 v42, 16, v3
	v_and_b32_e32 v43, 0xffff0000, v3
	v_pk_add_f32 v[28:29], v[28:29], v[36:37]
	v_pk_add_f32 v[30:31], v[30:31], v[38:39]
	v_pk_add_f32 v[32:33], v[32:33], v[40:41]
	v_pk_add_f32 v[34:35], v[34:35], v[42:43]
	v_fma_f32 v44, v72, v28, -v36
	v_fma_f32 v45, v72, v29, -v37
	v_fma_f32 v46, v72, v30, -v38
	v_fma_f32 v47, v72, v31, -v39
	v_fma_f32 v52, v72, v32, -v40
	v_fma_f32 v53, v72, v33, -v41
	v_fma_f32 v54, v72, v34, -v42
	v_fma_f32 v55, v72, v35, -v43
	v_cvt_pk_bf16_f32 v56, v44, v45
	v_cvt_pk_bf16_f32 v57, v46, v47
	v_cvt_pk_bf16_f32 v58, v52, v53
	v_cvt_pk_bf16_f32 v59, v54, v55
	global_store_dwordx4 v73, v[56:59], s[34:35] offset:2048 nt
	s_add_u32 s34, s34, 0x1000
	s_addc_u32 s35, s35, 0
	s_cmp_eq_u32 s53, 0
	s_cbranch_scc1 .Ldf_nh_35
	global_store_dwordx4 v60, v[36:39], s[24:25] offset:0
	global_store_dwordx4 v60, v[40:43], s[24:25] offset:16
.Ldf_nh_35:
	v_cndmask_b32_e64 v61, v214, v164, s[8:9]
	v_cndmask_b32_e64 v61, v230, v61, s[6:7]
	v_cndmask_b32_e64 v61, v61, v238, s[4:5]
	v_cndmask_b32_e64 v63, v215, v165, s[8:9]
	v_cndmask_b32_e64 v63, v231, v63, s[6:7]
	v_cndmask_b32_e64 v63, v63, v239, s[4:5]
	v_cndmask_b32_e64 v65, v216, v166, s[8:9]
	v_cndmask_b32_e64 v65, v232, v65, s[6:7]
	v_cndmask_b32_e64 v65, v65, v240, s[4:5]
	v_cndmask_b32_e64 v68, v217, v167, s[8:9]
	v_cndmask_b32_e64 v68, v233, v68, s[6:7]
	v_cndmask_b32_e64 v68, v68, v241, s[4:5]
	v_lshlrev_b32_e32 v44, 16, v61
	v_and_b32_e32 v45, 0xffff0000, v61
	v_lshlrev_b32_e32 v46, 16, v63
	v_and_b32_e32 v47, 0xffff0000, v63
	v_lshlrev_b32_e32 v52, 16, v65
	v_and_b32_e32 v53, 0xffff0000, v65
	v_lshlrev_b32_e32 v54, 16, v68
	v_and_b32_e32 v55, 0xffff0000, v68
	v_pk_add_f32 v[28:29], v[28:29], v[44:45] neg_lo:[0,1] neg_hi:[0,1]
	v_pk_add_f32 v[30:31], v[30:31], v[46:47] neg_lo:[0,1] neg_hi:[0,1]
	v_pk_add_f32 v[32:33], v[32:33], v[52:53] neg_lo:[0,1] neg_hi:[0,1]
	v_pk_add_f32 v[34:35], v[34:35], v[54:55] neg_lo:[0,1] neg_hi:[0,1]
	v_lshlrev_b32_e32 v36, 16, v4
	v_and_b32_e32 v37, 0xffff0000, v4
	v_lshlrev_b32_e32 v38, 16, v5
	v_and_b32_e32 v39, 0xffff0000, v5
	v_lshlrev_b32_e32 v40, 16, v6
	v_and_b32_e32 v41, 0xffff0000, v6
	v_lshlrev_b32_e32 v42, 16, v7
	v_and_b32_e32 v43, 0xffff0000, v7
	v_pk_add_f32 v[28:29], v[28:29], v[36:37]
	v_pk_add_f32 v[30:31], v[30:31], v[38:39]
	v_pk_add_f32 v[32:33], v[32:33], v[40:41]
	v_pk_add_f32 v[34:35], v[34:35], v[42:43]
	v_fma_f32 v44, v72, v28, -v36
	v_fma_f32 v45, v72, v29, -v37
	v_fma_f32 v46, v72, v30, -v38
	v_fma_f32 v47, v72, v31, -v39
	v_fma_f32 v52, v72, v32, -v40
	v_fma_f32 v53, v72, v33, -v41
	v_fma_f32 v54, v72, v34, -v42
	v_fma_f32 v55, v72, v35, -v43
	v_cvt_pk_bf16_f32 v56, v44, v45
	v_cvt_pk_bf16_f32 v57, v46, v47
	v_cvt_pk_bf16_f32 v58, v52, v53
	v_cvt_pk_bf16_f32 v59, v54, v55
	global_store_dwordx4 v73, v[56:59], s[34:35] offset:0 nt
	s_cmp_eq_u32 s53, 0
	s_cbranch_scc1 .Ldf_nh_36
	global_store_dwordx4 v60, v[36:39], s[24:25] offset:2048
	global_store_dwordx4 v60, v[40:43], s[24:25] offset:2064
	s_add_u32 s24, s24, 0x1000
	s_addc_u32 s25, s25, 0
; __device__ __forceinline__ unsigned pk2(float lo, float hi) { return pg8::cvt_pk_bf16(lo, hi); }
; #define UNPK8(dst, _w) do { dst[0] = pg8::bf_lo(_w.x); dst[1] = pg8::bf_hi(_w.x); dst[2] = pg8::bf_lo(_w.y); dst[3] = pg8::bf_hi(_w.y); dst[4] = pg8::bf_lo(_w.z); dst[5] = pg8::bf_hi(_w.z); dst[6] = pg8::bf_lo(_w.w); dst[7] = pg8::bf_hi(_w.w); } while (0)
; __device__ __forceinline__ void phase_diff(const Args& a, int l, int G, const int bid, const int tid) {
;     ...
;             for (int i0 = 0; i0 < 32; i0 += 4) {
;                 u32x4 cw[4], ow[4];
; #pragma unroll
;                 for (int k = 0; k < 4; ++k) { cw[k] = *(const u32x4*)(ub + (size_t)(i0 + k) * WB); ow[k] = *(const u32x4*)(ub + (size_t)(i0 + k - w + 1) * WB); }
; #pragma unroll
;                 for (int k = 0; k < 4; ++k) {
;                     const int t = t0 + i0 + k; float cur[8], old[8], o[8];
;                     UNPK8(cur, cw[k]); UNPK8(old, ow[k]);
; #pragma unroll
;                     for (int e = 0; e < 8; ++e) { ws_[e] += cur[e]; o[e] = ws_[e] * inv - cur[e]; ws_[e] -= old[e]; }
;                     u32x4 pw; pw.x = pk2(o[0], o[1]); pw.y = pk2(o[2], o[3]); pw.z = pk2(o[4], o[5]); pw.w = pk2(o[6], o[7]);
;                     *(u32x4*)(MIXB + (size_t)(mseq + t) * DM + n0) = pw;
;                     if (t >= L - 15) { float* hp = hout + (size_t)(t - (L - 15)) * WB + n0; *(f32x4*)hp = (f32x4){cur[0], cur[1], cur[2], cur[3]}; *(f32x4*)(hp + 4) = (f32x4){cur[4], cur[5], cur[6], cur[7]}; }
.Ldf_nh_36:
	v_cndmask_b32_e64 v61, v218, v168, s[8:9]
	v_cndmask_b32_e64 v61, v234, v61, s[6:7]
	v_cndmask_b32_e64 v61, v61, v0, s[4:5]
	v_cndmask_b32_e64 v63, v219, v169, s[8:9]
	v_cndmask_b32_e64 v63, v235, v63, s[6:7]
	v_cndmask_b32_e64 v63, v63, v1, s[4:5]
	v_cndmask_b32_e64 v65, v220, v170, s[8:9]
	v_cndmask_b32_e64 v65, v236, v65, s[6:7]
	v_cndmask_b32_e64 v65, v65, v2, s[4:5]
	v_cndmask_b32_e64 v68, v221, v171, s[8:9]
	v_cndmask_b32_e64 v68, v237, v68, s[6:7]
	v_cndmask_b32_e64 v68, v68, v3, s[4:5]
	v_lshlrev_b32_e32 v44, 16, v61
	v_and_b32_e32 v45, 0xffff0000, v61
	v_lshlrev_b32_e32 v46, 16, v63
	v_and_b32_e32 v47, 0xffff0000, v63
	v_lshlrev_b32_e32 v52, 16, v65
	v_and_b32_e32 v53, 0xffff0000, v65
	v_lshlrev_b32_e32 v54, 16, v68
	v_and_b32_e32 v55, 0xffff0000, v68
	v_pk_add_f32 v[28:29], v[28:29], v[44:45] neg_lo:[0,1] neg_hi:[0,1]
	v_pk_add_f32 v[30:31], v[30:31], v[46:47] neg_lo:[0,1] neg_hi:[0,1]
	v_pk_add_f32 v[32:33], v[32:33], v[52:53] neg_lo:[0,1] neg_hi:[0,1]
	v_pk_add_f32 v[34:35], v[34:35], v[54:55] neg_lo:[0,1] neg_hi:[0,1]
	v_lshlrev_b32_e32 v36, 16, v8
	v_and_b32_e32 v37, 0xffff0000, v8
	v_lshlrev_b32_e32 v38, 16, v9
	v_and_b32_e32 v39, 0xffff0000, v9
	v_lshlrev_b32_e32 v40, 16, v10
	v_and_b32_e32 v41, 0xffff0000, v10
	v_lshlrev_b32_e32 v42, 16, v11
	v_and_b32_e32 v43, 0xffff0000, v11
	v_pk_add_f32 v[28:29], v[28:29], v[36:37]
	v_pk_add_f32 v[30:31], v[30:31], v[38:39]
	v_pk_add_f32 v[32:33], v[32:33], v[40:41]
	v_pk_add_f32 v[34:35], v[34:35], v[42:43]
	v_fma_f32 v44, v72, v28, -v36
	v_fma_f32 v45, v72, v29, -v37
	v_fma_f32 v46, v72, v30, -v38
	v_fma_f32 v47, v72, v31, -v39
	v_fma_f32 v52, v72, v32, -v40
	v_fma_f32 v53, v72, v33, -v41
	v_fma_f32 v54, v72, v34, -v42
	v_fma_f32 v55, v72, v35, -v43
	v_cvt_pk_bf16_f32 v56, v44, v45
	v_cvt_pk_bf16_f32 v57, v46, v47
	v_cvt_pk_bf16_f32 v58, v52, v53
	v_cvt_pk_bf16_f32 v59, v54, v55
	global_store_dwordx4 v73, v[56:59], s[34:35] offset:2048 nt
	s_add_u32 s34, s34, 0x1000
	s_addc_u32 s35, s35, 0
	s_cmp_eq_u32 s53, 0
	s_cbranch_scc1 .Ldf_nh_37
	global_store_dwordx4 v60, v[36:39], s[24:25] offset:0
	global_store_dwordx4 v60, v[40:43], s[24:25] offset:16
.Ldf_nh_37:
	v_cndmask_b32_e64 v61, v222, v172, s[8:9]
	v_cndmask_b32_e64 v61, v238, v61, s[6:7]
	v_cndmask_b32_e64 v61, v61, v4, s[4:5]
	v_cndmask_b32_e64 v63, v223, v173, s[8:9]
	v_cndmask_b32_e64 v63, v239, v63, s[6:7]
	v_cndmask_b32_e64 v63, v63, v5, s[4:5]
	v_cndmask_b32_e64 v65, v224, v174, s[8:9]
	v_cndmask_b32_e64 v65, v240, v65, s[6:7]
	v_cndmask_b32_e64 v65, v65, v6, s[4:5]
	v_cndmask_b32_e64 v68, v225, v175, s[8:9]
	v_cndmask_b32_e64 v68, v241, v68, s[6:7]
	v_cndmask_b32_e64 v68, v68, v7, s[4:5]
	v_lshlrev_b32_e32 v44, 16, v61
	v_and_b32_e32 v45, 0xffff0000, v61
	v_lshlrev_b32_e32 v46, 16, v63
	v_and_b32_e32 v47, 0xffff0000, v63
	v_lshlrev_b32_e32 v52, 16, v65
	v_and_b32_e32 v53, 0xffff0000, v65
	v_lshlrev_b32_e32 v54, 16, v68
	v_and_b32_e32 v55, 0xffff0000, v68
	v_pk_add_f32 v[28:29], v[28:29], v[44:45] neg_lo:[0,1] neg_hi:[0,1]
	v_pk_add_f32 v[30:31], v[30:31], v[46:47] neg_lo:[0,1] neg_hi:[0,1]
	v_pk_add_f32 v[32:33], v[32:33], v[52:53] neg_lo:[0,1] neg_hi:[0,1]
	v_pk_add_f32 v[34:35], v[34:35], v[54:55] neg_lo:[0,1] neg_hi:[0,1]
	v_lshlrev_b32_e32 v36, 16, v12
	v_and_b32_e32 v37, 0xffff0000, v12
	v_lshlrev_b32_e32 v38, 16, v13
	v_and_b32_e32 v39, 0xffff0000, v13
	v_lshlrev_b32_e32 v40, 16, v14
	v_and_b32_e32 v41, 0xffff0000, v14
	v_lshlrev_b32_e32 v42, 16, v15
	v_and_b32_e32 v43, 0xffff0000, v15
	v_pk_add_f32 v[28:29], v[28:29], v[36:37]
	v_pk_add_f32 v[30:31], v[30:31], v[38:39]
	v_pk_add_f32 v[32:33], v[32:33], v[40:41]
	v_pk_add_f32 v[34:35], v[34:35], v[42:43]
	v_fma_f32 v44, v72, v28, -v36
	v_fma_f32 v45, v72, v29, -v37
	v_fma_f32 v46, v72, v30, -v38
	v_fma_f32 v47, v72, v31, -v39
	v_fma_f32 v52, v72, v32, -v40
	v_fma_f32 v53, v72, v33, -v41
	v_fma_f32 v54, v72, v34, -v42
	v_fma_f32 v55, v72, v35, -v43
	v_cvt_pk_bf16_f32 v56, v44, v45
	v_cvt_pk_bf16_f32 v57, v46, v47
	v_cvt_pk_bf16_f32 v58, v52, v53
	v_cvt_pk_bf16_f32 v59, v54, v55
	global_store_dwordx4 v73, v[56:59], s[34:35] offset:0 nt
	s_cmp_eq_u32 s53, 0
	s_cbranch_scc1 .Ldf_nh_38
	global_store_dwordx4 v60, v[36:39], s[24:25] offset:2048
	global_store_dwordx4 v60, v[40:43], s[24:25] offset:2064
	s_add_u32 s24, s24, 0x1000
	s_addc_u32 s25, s25, 0
.Ldf_nh_38:
	v_cndmask_b32_e64 v61, v226, v176, s[8:9]
	v_cndmask_b32_e64 v61, v0, v61, s[6:7]
	v_cndmask_b32_e64 v61, v61, v8, s[4:5]
	v_cndmask_b32_e64 v63, v227, v177, s[8:9]
	v_cndmask_b32_e64 v63, v1, v63, s[6:7]
	v_cndmask_b32_e64 v63, v63, v9, s[4:5]
	v_cndmask_b32_e64 v65, v228, v178, s[8:9]
	v_cndmask_b32_e64 v65, v2, v65, s[6:7]
	v_cndmask_b32_e64 v65, v65, v10, s[4:5]
	v_cndmask_b32_e64 v68, v229, v179, s[8:9]
	v_cndmask_b32_e64 v68, v3, v68, s[6:7]
	v_cndmask_b32_e64 v68, v68, v11, s[4:5]
	v_lshlrev_b32_e32 v44, 16, v61
	v_and_b32_e32 v45, 0xffff0000, v61
	v_lshlrev_b32_e32 v46, 16, v63
	v_and_b32_e32 v47, 0xffff0000, v63
	v_lshlrev_b32_e32 v52, 16, v65
	v_and_b32_e32 v53, 0xffff0000, v65
	v_lshlrev_b32_e32 v54, 16, v68
	v_and_b32_e32 v55, 0xffff0000, v68
	v_pk_add_f32 v[28:29], v[28:29], v[44:45] neg_lo:[0,1] neg_hi:[0,1]
	v_pk_add_f32 v[30:31], v[30:31], v[46:47] neg_lo:[0,1] neg_hi:[0,1]
	v_pk_add_f32 v[32:33], v[32:33], v[52:53] neg_lo:[0,1] neg_hi:[0,1]
	v_pk_add_f32 v[34:35], v[34:35], v[54:55] neg_lo:[0,1] neg_hi:[0,1]
	v_lshlrev_b32_e32 v36, 16, v16
	v_and_b32_e32 v37, 0xffff0000, v16
	v_lshlrev_b32_e32 v38, 16, v17
	v_and_b32_e32 v39, 0xffff0000, v17
	v_lshlrev_b32_e32 v40, 16, v18
	v_and_b32_e32 v41, 0xffff0000, v18
	v_lshlrev_b32_e32 v42, 16, v19
	v_and_b32_e32 v43, 0xffff0000, v19
	v_pk_add_f32 v[28:29], v[28:29], v[36:37]
	v_pk_add_f32 v[30:31], v[30:31], v[38:39]
	v_pk_add_f32 v[32:33], v[32:33], v[40:41]
	v_pk_add_f32 v[34:35], v[34:35], v[42:43]
	v_fma_f32 v44, v72, v28, -v36
	v_fma_f32 v45, v72, v29, -v37
	v_fma_f32 v46, v72, v30, -v38
	v_fma_f32 v47, v72, v31, -v39
	v_fma_f32 v52, v72, v32, -v40
	v_fma_f32 v53, v72, v33, -v41
	v_fma_f32 v54, v72, v34, -v42
	v_fma_f32 v55, v72, v35, -v43
	v_cvt_pk_bf16_f32 v56, v44, v45
	v_cvt_pk_bf16_f32 v57, v46, v47
	v_cvt_pk_bf16_f32 v58, v52, v53
	v_cvt_pk_bf16_f32 v59, v54, v55
	global_store_dwordx4 v73, v[56:59], s[34:35] offset:2048 nt
	s_add_u32 s34, s34, 0x1000
	s_addc_u32 s35, s35, 0
	s_cmp_eq_u32 s53, 0
	s_cbranch_scc1 .Ldf_nh_39
	global_store_dwordx4 v60, v[36:39], s[24:25] offset:0
	global_store_dwordx4 v60, v[40:43], s[24:25] offset:16
; __device__ __forceinline__ unsigned pk2(float lo, float hi) { return pg8::cvt_pk_bf16(lo, hi); }
; #define UNPK8(dst, _w) do { dst[0] = pg8::bf_lo(_w.x); dst[1] = pg8::bf_hi(_w.x); dst[2] = pg8::bf_lo(_w.y); dst[3] = pg8::bf_hi(_w.y); dst[4] = pg8::bf_lo(_w.z); dst[5] = pg8::bf_hi(_w.z); dst[6] = pg8::bf_lo(_w.w); dst[7] = pg8::bf_hi(_w.w); } while (0)
; __device__ __forceinline__ void phase_diff(const Args& a, int l, int G, const int bid, const int tid) {
;     ...
;             for (int i0 = 0; i0 < 32; i0 += 4) {
;                 u32x4 cw[4], ow[4];
; #pragma unroll
;                 for (int k = 0; k < 4; ++k) { cw[k] = *(const u32x4*)(ub + (size_t)(i0 + k) * WB); ow[k] = *(const u32x4*)(ub + (size_t)(i0 + k - w + 1) * WB); }
; #pragma unroll
;                 for (int k = 0; k < 4; ++k) {
;                     const int t = t0 + i0 + k; float cur[8], old[8], o[8];
;                     UNPK8(cur, cw[k]); UNPK8(old, ow[k]);
; #pragma unroll
;                     for (int e = 0; e < 8; ++e) { ws_[e] += cur[e]; o[e] = ws_[e] * inv - cur[e]; ws_[e] -= old[e]; }
;                     u32x4 pw; pw.x = pk2(o[0], o[1]); pw.y = pk2(o[2], o[3]); pw.z = pk2(o[4], o[5]); pw.w = pk2(o[6], o[7]);
;                     *(u32x4*)(MIXB + (size_t)(mseq + t) * DM + n0) = pw;
;                     if (t >= L - 15) { float* hp = hout + (size_t)(t - (L - 15)) * WB + n0; *(f32x4*)hp = (f32x4){cur[0], cur[1], cur[2], cur[3]}; *(f32x4*)(hp + 4) = (f32x4){cur[4], cur[5], cur[6], cur[7]}; }
.Ldf_nh_39:
	v_cndmask_b32_e64 v61, v230, v180, s[8:9]
	v_cndmask_b32_e64 v61, v4, v61, s[6:7]
	v_cndmask_b32_e64 v61, v61, v12, s[4:5]
	v_cndmask_b32_e64 v63, v231, v181, s[8:9]
	v_cndmask_b32_e64 v63, v5, v63, s[6:7]
	v_cndmask_b32_e64 v63, v63, v13, s[4:5]
	v_cndmask_b32_e64 v65, v232, v182, s[8:9]
	v_cndmask_b32_e64 v65, v6, v65, s[6:7]
	v_cndmask_b32_e64 v65, v65, v14, s[4:5]
	v_cndmask_b32_e64 v68, v233, v183, s[8:9]
	v_cndmask_b32_e64 v68, v7, v68, s[6:7]
	v_cndmask_b32_e64 v68, v68, v15, s[4:5]
	v_lshlrev_b32_e32 v44, 16, v61
	v_and_b32_e32 v45, 0xffff0000, v61
	v_lshlrev_b32_e32 v46, 16, v63
	v_and_b32_e32 v47, 0xffff0000, v63
	v_lshlrev_b32_e32 v52, 16, v65
	v_and_b32_e32 v53, 0xffff0000, v65
	v_lshlrev_b32_e32 v54, 16, v68
	v_and_b32_e32 v55, 0xffff0000, v68
	v_pk_add_f32 v[28:29], v[28:29], v[44:45] neg_lo:[0,1] neg_hi:[0,1]
	v_pk_add_f32 v[30:31], v[30:31], v[46:47] neg_lo:[0,1] neg_hi:[0,1]
	v_pk_add_f32 v[32:33], v[32:33], v[52:53] neg_lo:[0,1] neg_hi:[0,1]
	v_pk_add_f32 v[34:35], v[34:35], v[54:55] neg_lo:[0,1] neg_hi:[0,1]
	v_lshlrev_b32_e32 v36, 16, v20
	v_and_b32_e32 v37, 0xffff0000, v20
	v_lshlrev_b32_e32 v38, 16, v21
	v_and_b32_e32 v39, 0xffff0000, v21
	v_lshlrev_b32_e32 v40, 16, v22
	v_and_b32_e32 v41, 0xffff0000, v22
	v_lshlrev_b32_e32 v42, 16, v23
	v_and_b32_e32 v43, 0xffff0000, v23
	v_pk_add_f32 v[28:29], v[28:29], v[36:37]
	v_pk_add_f32 v[30:31], v[30:31], v[38:39]
	v_pk_add_f32 v[32:33], v[32:33], v[40:41]
	v_pk_add_f32 v[34:35], v[34:35], v[42:43]
	v_fma_f32 v44, v72, v28, -v36
	v_fma_f32 v45, v72, v29, -v37
	v_fma_f32 v46, v72, v30, -v38
	v_fma_f32 v47, v72, v31, -v39
	v_fma_f32 v52, v72, v32, -v40
	v_fma_f32 v53, v72, v33, -v41
	v_fma_f32 v54, v72, v34, -v42
	v_fma_f32 v55, v72, v35, -v43
	v_cvt_pk_bf16_f32 v56, v44, v45
	v_cvt_pk_bf16_f32 v57, v46, v47
	v_cvt_pk_bf16_f32 v58, v52, v53
	v_cvt_pk_bf16_f32 v59, v54, v55
	global_store_dwordx4 v73, v[56:59], s[34:35] offset:0 nt
	s_cmp_eq_u32 s53, 0
	s_cbranch_scc1 .Ldf_nh_40
	global_store_dwordx4 v60, v[36:39], s[24:25] offset:2048
	global_store_dwordx4 v60, v[40:43], s[24:25] offset:2064
	s_add_u32 s24, s24, 0x1000
	s_addc_u32 s25, s25, 0
.Ldf_nh_40:
	v_cndmask_b32_e64 v61, v234, v184, s[8:9]
	v_cndmask_b32_e64 v61, v8, v61, s[6:7]
	v_cndmask_b32_e64 v61, v61, v16, s[4:5]
	v_cndmask_b32_e64 v63, v235, v185, s[8:9]
	v_cndmask_b32_e64 v63, v9, v63, s[6:7]
	v_cndmask_b32_e64 v63, v63, v17, s[4:5]
	v_cndmask_b32_e64 v65, v236, v186, s[8:9]
	v_cndmask_b32_e64 v65, v10, v65, s[6:7]
	v_cndmask_b32_e64 v65, v65, v18, s[4:5]
	v_cndmask_b32_e64 v68, v237, v187, s[8:9]
	v_cndmask_b32_e64 v68, v11, v68, s[6:7]
	v_cndmask_b32_e64 v68, v68, v19, s[4:5]
	v_lshlrev_b32_e32 v44, 16, v61
	v_and_b32_e32 v45, 0xffff0000, v61
	v_lshlrev_b32_e32 v46, 16, v63
	v_and_b32_e32 v47, 0xffff0000, v63
	v_lshlrev_b32_e32 v52, 16, v65
	v_and_b32_e32 v53, 0xffff0000, v65
	v_lshlrev_b32_e32 v54, 16, v68
	v_and_b32_e32 v55, 0xffff0000, v68
	v_pk_add_f32 v[28:29], v[28:29], v[44:45] neg_lo:[0,1] neg_hi:[0,1]
	v_pk_add_f32 v[30:31], v[30:31], v[46:47] neg_lo:[0,1] neg_hi:[0,1]
	v_pk_add_f32 v[32:33], v[32:33], v[52:53] neg_lo:[0,1] neg_hi:[0,1]
	v_pk_add_f32 v[34:35], v[34:35], v[54:55] neg_lo:[0,1] neg_hi:[0,1]
	v_lshlrev_b32_e32 v36, 16, v24
	v_and_b32_e32 v37, 0xffff0000, v24
	v_lshlrev_b32_e32 v38, 16, v25
	v_and_b32_e32 v39, 0xffff0000, v25
	v_lshlrev_b32_e32 v40, 16, v26
	v_and_b32_e32 v41, 0xffff0000, v26
	v_lshlrev_b32_e32 v42, 16, v27
	v_and_b32_e32 v43, 0xffff0000, v27
	v_pk_add_f32 v[28:29], v[28:29], v[36:37]
	v_pk_add_f32 v[30:31], v[30:31], v[38:39]
	v_pk_add_f32 v[32:33], v[32:33], v[40:41]
	v_pk_add_f32 v[34:35], v[34:35], v[42:43]
	v_fma_f32 v44, v72, v28, -v36
	v_fma_f32 v45, v72, v29, -v37
	v_fma_f32 v46, v72, v30, -v38
	v_fma_f32 v47, v72, v31, -v39
	v_fma_f32 v52, v72, v32, -v40
	v_fma_f32 v53, v72, v33, -v41
	v_fma_f32 v54, v72, v34, -v42
	v_fma_f32 v55, v72, v35, -v43
	v_cvt_pk_bf16_f32 v56, v44, v45
	v_cvt_pk_bf16_f32 v57, v46, v47
	v_cvt_pk_bf16_f32 v58, v52, v53
	v_cvt_pk_bf16_f32 v59, v54, v55
	global_store_dwordx4 v73, v[56:59], s[34:35] offset:2048 nt
	s_add_u32 s34, s34, 0x1000
	s_addc_u32 s35, s35, 0
	s_cmp_eq_u32 s53, 0
	s_cbranch_scc1 .Ldf_nh_41
	global_store_dwordx4 v60, v[36:39], s[24:25] offset:0
	global_store_dwordx4 v60, v[40:43], s[24:25] offset:16
.Ldf_nh_41:
	v_cndmask_b32_e64 v61, v238, v188, s[8:9]
	v_cndmask_b32_e64 v61, v12, v61, s[6:7]
	v_cndmask_b32_e64 v61, v61, v20, s[4:5]
	v_cndmask_b32_e64 v63, v239, v189, s[8:9]
	v_cndmask_b32_e64 v63, v13, v63, s[6:7]
	v_cndmask_b32_e64 v63, v63, v21, s[4:5]
	v_cndmask_b32_e64 v65, v240, v190, s[8:9]
	v_cndmask_b32_e64 v65, v14, v65, s[6:7]
	v_cndmask_b32_e64 v65, v65, v22, s[4:5]
	v_cndmask_b32_e64 v68, v241, v191, s[8:9]
	v_cndmask_b32_e64 v68, v15, v68, s[6:7]
	v_cndmask_b32_e64 v68, v68, v23, s[4:5]
	v_lshlrev_b32_e32 v44, 16, v61
	v_and_b32_e32 v45, 0xffff0000, v61
	v_lshlrev_b32_e32 v46, 16, v63
	v_and_b32_e32 v47, 0xffff0000, v63
	v_lshlrev_b32_e32 v52, 16, v65
	v_and_b32_e32 v53, 0xffff0000, v65
	v_lshlrev_b32_e32 v54, 16, v68
	v_and_b32_e32 v55, 0xffff0000, v68
	v_pk_add_f32 v[28:29], v[28:29], v[44:45] neg_lo:[0,1] neg_hi:[0,1]
	v_pk_add_f32 v[30:31], v[30:31], v[46:47] neg_lo:[0,1] neg_hi:[0,1]
	v_pk_add_f32 v[32:33], v[32:33], v[52:53] neg_lo:[0,1] neg_hi:[0,1]
	v_pk_add_f32 v[34:35], v[34:35], v[54:55] neg_lo:[0,1] neg_hi:[0,1]
	s_waitcnt vmcnt(9)
	v_lshlrev_b32_e32 v36, 16, v76
	v_and_b32_e32 v37, 0xffff0000, v76
	v_lshlrev_b32_e32 v38, 16, v77
	v_and_b32_e32 v39, 0xffff0000, v77
	v_lshlrev_b32_e32 v40, 16, v78
	v_and_b32_e32 v41, 0xffff0000, v78
	v_lshlrev_b32_e32 v42, 16, v79
	v_and_b32_e32 v43, 0xffff0000, v79
	v_pk_add_f32 v[28:29], v[28:29], v[36:37]
	v_pk_add_f32 v[30:31], v[30:31], v[38:39]
	v_pk_add_f32 v[32:33], v[32:33], v[40:41]
	v_pk_add_f32 v[34:35], v[34:35], v[42:43]
	v_fma_f32 v44, v72, v28, -v36
	v_fma_f32 v45, v72, v29, -v37
	v_fma_f32 v46, v72, v30, -v38
	v_fma_f32 v47, v72, v31, -v39
	v_fma_f32 v52, v72, v32, -v40
	v_fma_f32 v53, v72, v33, -v41
	v_fma_f32 v54, v72, v34, -v42
	v_fma_f32 v55, v72, v35, -v43
	v_cvt_pk_bf16_f32 v56, v44, v45
	v_cvt_pk_bf16_f32 v57, v46, v47
	v_cvt_pk_bf16_f32 v58, v52, v53
	v_cvt_pk_bf16_f32 v59, v54, v55
	global_store_dwordx4 v73, v[56:59], s[34:35] offset:0 nt
	s_cmp_eq_u32 s53, 0
	s_cbranch_scc1 .Ldf_nh_42
	global_store_dwordx4 v60, v[36:39], s[24:25] offset:2048
	global_store_dwordx4 v60, v[40:43], s[24:25] offset:2064
	s_add_u32 s24, s24, 0x1000
	s_addc_u32 s25, s25, 0
; __device__ __forceinline__ unsigned pk2(float lo, float hi) { return pg8::cvt_pk_bf16(lo, hi); }
; #define UNPK8(dst, _w) do { dst[0] = pg8::bf_lo(_w.x); dst[1] = pg8::bf_hi(_w.x); dst[2] = pg8::bf_lo(_w.y); dst[3] = pg8::bf_hi(_w.y); dst[4] = pg8::bf_lo(_w.z); dst[5] = pg8::bf_hi(_w.z); dst[6] = pg8::bf_lo(_w.w); dst[7] = pg8::bf_hi(_w.w); } while (0)
; __device__ __forceinline__ void phase_diff(const Args& a, int l, int G, const int bid, const int tid) {
;     ...
;             for (int i0 = 0; i0 < 32; i0 += 4) {
;                 u32x4 cw[4], ow[4];
; #pragma unroll
;                 for (int k = 0; k < 4; ++k) { cw[k] = *(const u32x4*)(ub + (size_t)(i0 + k) * WB); ow[k] = *(const u32x4*)(ub + (size_t)(i0 + k - w + 1) * WB); }
; #pragma unroll
;                 for (int k = 0; k < 4; ++k) {
;                     const int t = t0 + i0 + k; float cur[8], old[8], o[8];
;                     UNPK8(cur, cw[k]); UNPK8(old, ow[k]);
; #pragma unroll
;                     for (int e = 0; e < 8; ++e) { ws_[e] += cur[e]; o[e] = ws_[e] * inv - cur[e]; ws_[e] -= old[e]; }
;                     u32x4 pw; pw.x = pk2(o[0], o[1]); pw.y = pk2(o[2], o[3]); pw.z = pk2(o[4], o[5]); pw.w = pk2(o[6], o[7]);
;                     *(u32x4*)(MIXB + (size_t)(mseq + t) * DM + n0) = pw;
;                     if (t >= L - 15) { float* hp = hout + (size_t)(t - (L - 15)) * WB + n0; *(f32x4*)hp = (f32x4){cur[0], cur[1], cur[2], cur[3]}; *(f32x4*)(hp + 4) = (f32x4){cur[4], cur[5], cur[6], cur[7]}; }
.Ldf_nh_42:
	v_cndmask_b32_e64 v61, v0, v210, s[8:9]
	v_cndmask_b32_e64 v61, v16, v61, s[6:7]
	v_cndmask_b32_e64 v61, v61, v24, s[4:5]
	v_cndmask_b32_e64 v63, v1, v211, s[8:9]
	v_cndmask_b32_e64 v63, v17, v63, s[6:7]
	v_cndmask_b32_e64 v63, v63, v25, s[4:5]
	v_cndmask_b32_e64 v65, v2, v212, s[8:9]
	v_cndmask_b32_e64 v65, v18, v65, s[6:7]
	v_cndmask_b32_e64 v65, v65, v26, s[4:5]
	v_cndmask_b32_e64 v68, v3, v213, s[8:9]
	v_cndmask_b32_e64 v68, v19, v68, s[6:7]
	v_cndmask_b32_e64 v68, v68, v27, s[4:5]
	v_lshlrev_b32_e32 v44, 16, v61
	v_and_b32_e32 v45, 0xffff0000, v61
	v_lshlrev_b32_e32 v46, 16, v63
	v_and_b32_e32 v47, 0xffff0000, v63
	v_lshlrev_b32_e32 v52, 16, v65
	v_and_b32_e32 v53, 0xffff0000, v65
	v_lshlrev_b32_e32 v54, 16, v68
	v_and_b32_e32 v55, 0xffff0000, v68
	v_pk_add_f32 v[28:29], v[28:29], v[44:45] neg_lo:[0,1] neg_hi:[0,1]
	v_pk_add_f32 v[30:31], v[30:31], v[46:47] neg_lo:[0,1] neg_hi:[0,1]
	v_pk_add_f32 v[32:33], v[32:33], v[52:53] neg_lo:[0,1] neg_hi:[0,1]
	v_pk_add_f32 v[34:35], v[34:35], v[54:55] neg_lo:[0,1] neg_hi:[0,1]
	v_lshlrev_b32_e32 v36, 16, v80
	v_and_b32_e32 v37, 0xffff0000, v80
	v_lshlrev_b32_e32 v38, 16, v81
	v_and_b32_e32 v39, 0xffff0000, v81
	v_lshlrev_b32_e32 v40, 16, v82
	v_and_b32_e32 v41, 0xffff0000, v82
	v_lshlrev_b32_e32 v42, 16, v83
	v_and_b32_e32 v43, 0xffff0000, v83
	v_pk_add_f32 v[28:29], v[28:29], v[36:37]
	v_pk_add_f32 v[30:31], v[30:31], v[38:39]
	v_pk_add_f32 v[32:33], v[32:33], v[40:41]
	v_pk_add_f32 v[34:35], v[34:35], v[42:43]
	v_fma_f32 v44, v72, v28, -v36
	v_fma_f32 v45, v72, v29, -v37
	v_fma_f32 v46, v72, v30, -v38
	v_fma_f32 v47, v72, v31, -v39
	v_fma_f32 v52, v72, v32, -v40
	v_fma_f32 v53, v72, v33, -v41
	v_fma_f32 v54, v72, v34, -v42
	v_fma_f32 v55, v72, v35, -v43
	v_cvt_pk_bf16_f32 v56, v44, v45
	v_cvt_pk_bf16_f32 v57, v46, v47
	v_cvt_pk_bf16_f32 v58, v52, v53
	v_cvt_pk_bf16_f32 v59, v54, v55
	global_store_dwordx4 v73, v[56:59], s[34:35] offset:2048 nt
	s_add_u32 s34, s34, 0x1000
	s_addc_u32 s35, s35, 0
	s_cmp_eq_u32 s53, 0
	s_cbranch_scc1 .Ldf_nh_43
	global_store_dwordx4 v60, v[36:39], s[24:25] offset:0
	global_store_dwordx4 v60, v[40:43], s[24:25] offset:16
.Ldf_nh_43:
	v_cndmask_b32_e64 v61, v4, v214, s[8:9]
	v_cndmask_b32_e64 v61, v20, v61, s[6:7]
	v_cndmask_b32_e64 v61, v61, v76, s[4:5]
	v_cndmask_b32_e64 v63, v5, v215, s[8:9]
	v_cndmask_b32_e64 v63, v21, v63, s[6:7]
	v_cndmask_b32_e64 v63, v63, v77, s[4:5]
	v_cndmask_b32_e64 v65, v6, v216, s[8:9]
	v_cndmask_b32_e64 v65, v22, v65, s[6:7]
	v_cndmask_b32_e64 v65, v65, v78, s[4:5]
	v_cndmask_b32_e64 v68, v7, v217, s[8:9]
	v_cndmask_b32_e64 v68, v23, v68, s[6:7]
	v_cndmask_b32_e64 v68, v68, v79, s[4:5]
	v_lshlrev_b32_e32 v44, 16, v61
	v_and_b32_e32 v45, 0xffff0000, v61
	v_lshlrev_b32_e32 v46, 16, v63
	v_and_b32_e32 v47, 0xffff0000, v63
	v_lshlrev_b32_e32 v52, 16, v65
	v_and_b32_e32 v53, 0xffff0000, v65
	v_lshlrev_b32_e32 v54, 16, v68
	v_and_b32_e32 v55, 0xffff0000, v68
	v_pk_add_f32 v[28:29], v[28:29], v[44:45] neg_lo:[0,1] neg_hi:[0,1]
	v_pk_add_f32 v[30:31], v[30:31], v[46:47] neg_lo:[0,1] neg_hi:[0,1]
	v_pk_add_f32 v[32:33], v[32:33], v[52:53] neg_lo:[0,1] neg_hi:[0,1]
	v_pk_add_f32 v[34:35], v[34:35], v[54:55] neg_lo:[0,1] neg_hi:[0,1]
	v_lshlrev_b32_e32 v36, 16, v84
	v_and_b32_e32 v37, 0xffff0000, v84
	v_lshlrev_b32_e32 v38, 16, v85
	v_and_b32_e32 v39, 0xffff0000, v85
	v_lshlrev_b32_e32 v40, 16, v86
	v_and_b32_e32 v41, 0xffff0000, v86
	v_lshlrev_b32_e32 v42, 16, v87
	v_and_b32_e32 v43, 0xffff0000, v87
	v_pk_add_f32 v[28:29], v[28:29], v[36:37]
	v_pk_add_f32 v[30:31], v[30:31], v[38:39]
	v_pk_add_f32 v[32:33], v[32:33], v[40:41]
	v_pk_add_f32 v[34:35], v[34:35], v[42:43]
	v_fma_f32 v44, v72, v28, -v36
	v_fma_f32 v45, v72, v29, -v37
	v_fma_f32 v46, v72, v30, -v38
	v_fma_f32 v47, v72, v31, -v39
	v_fma_f32 v52, v72, v32, -v40
	v_fma_f32 v53, v72, v33, -v41
	v_fma_f32 v54, v72, v34, -v42
	v_fma_f32 v55, v72, v35, -v43
	v_cvt_pk_bf16_f32 v56, v44, v45
	v_cvt_pk_bf16_f32 v57, v46, v47
	v_cvt_pk_bf16_f32 v58, v52, v53
	v_cvt_pk_bf16_f32 v59, v54, v55
	global_store_dwordx4 v73, v[56:59], s[34:35] offset:0 nt
	s_cmp_eq_u32 s53, 0
	s_cbranch_scc1 .Ldf_nh_44
	global_store_dwordx4 v60, v[36:39], s[24:25] offset:2048
	global_store_dwordx4 v60, v[40:43], s[24:25] offset:2064
	s_add_u32 s24, s24, 0x1000
	s_addc_u32 s25, s25, 0
.Ldf_nh_44:
	v_cndmask_b32_e64 v61, v8, v218, s[8:9]
	v_cndmask_b32_e64 v61, v24, v61, s[6:7]
	v_cndmask_b32_e64 v61, v61, v80, s[4:5]
	v_cndmask_b32_e64 v63, v9, v219, s[8:9]
	v_cndmask_b32_e64 v63, v25, v63, s[6:7]
	v_cndmask_b32_e64 v63, v63, v81, s[4:5]
	v_cndmask_b32_e64 v65, v10, v220, s[8:9]
	v_cndmask_b32_e64 v65, v26, v65, s[6:7]
	v_cndmask_b32_e64 v65, v65, v82, s[4:5]
	v_cndmask_b32_e64 v68, v11, v221, s[8:9]
	v_cndmask_b32_e64 v68, v27, v68, s[6:7]
	v_cndmask_b32_e64 v68, v68, v83, s[4:5]
	v_lshlrev_b32_e32 v44, 16, v61
	v_and_b32_e32 v45, 0xffff0000, v61
	v_lshlrev_b32_e32 v46, 16, v63
	v_and_b32_e32 v47, 0xffff0000, v63
	v_lshlrev_b32_e32 v52, 16, v65
	v_and_b32_e32 v53, 0xffff0000, v65
	v_lshlrev_b32_e32 v54, 16, v68
	v_and_b32_e32 v55, 0xffff0000, v68
	v_pk_add_f32 v[28:29], v[28:29], v[44:45] neg_lo:[0,1] neg_hi:[0,1]
	v_pk_add_f32 v[30:31], v[30:31], v[46:47] neg_lo:[0,1] neg_hi:[0,1]
	v_pk_add_f32 v[32:33], v[32:33], v[52:53] neg_lo:[0,1] neg_hi:[0,1]
	v_pk_add_f32 v[34:35], v[34:35], v[54:55] neg_lo:[0,1] neg_hi:[0,1]
	v_lshlrev_b32_e32 v36, 16, v88
	v_and_b32_e32 v37, 0xffff0000, v88
	v_lshlrev_b32_e32 v38, 16, v89
	v_and_b32_e32 v39, 0xffff0000, v89
	v_lshlrev_b32_e32 v40, 16, v90
	v_and_b32_e32 v41, 0xffff0000, v90
	v_lshlrev_b32_e32 v42, 16, v91
	v_and_b32_e32 v43, 0xffff0000, v91
	v_pk_add_f32 v[28:29], v[28:29], v[36:37]
	v_pk_add_f32 v[30:31], v[30:31], v[38:39]
	v_pk_add_f32 v[32:33], v[32:33], v[40:41]
	v_pk_add_f32 v[34:35], v[34:35], v[42:43]
	v_fma_f32 v44, v72, v28, -v36
	v_fma_f32 v45, v72, v29, -v37
	v_fma_f32 v46, v72, v30, -v38
	v_fma_f32 v47, v72, v31, -v39
	v_fma_f32 v52, v72, v32, -v40
	v_fma_f32 v53, v72, v33, -v41
	v_fma_f32 v54, v72, v34, -v42
	v_fma_f32 v55, v72, v35, -v43
	v_cvt_pk_bf16_f32 v56, v44, v45
	v_cvt_pk_bf16_f32 v57, v46, v47
	v_cvt_pk_bf16_f32 v58, v52, v53
	v_cvt_pk_bf16_f32 v59, v54, v55
	global_store_dwordx4 v73, v[56:59], s[34:35] offset:2048 nt
	s_add_u32 s34, s34, 0x1000
	s_addc_u32 s35, s35, 0
	s_cmp_eq_u32 s53, 0
	s_cbranch_scc1 .Ldf_nh_45
	global_store_dwordx4 v60, v[36:39], s[24:25] offset:0
	global_store_dwordx4 v60, v[40:43], s[24:25] offset:16
; __device__ __forceinline__ unsigned pk2(float lo, float hi) { return pg8::cvt_pk_bf16(lo, hi); }
; #define UNPK8(dst, _w) do { dst[0] = pg8::bf_lo(_w.x); dst[1] = pg8::bf_hi(_w.x); dst[2] = pg8::bf_lo(_w.y); dst[3] = pg8::bf_hi(_w.y); dst[4] = pg8::bf_lo(_w.z); dst[5] = pg8::bf_hi(_w.z); dst[6] = pg8::bf_lo(_w.w); dst[7] = pg8::bf_hi(_w.w); } while (0)
; __device__ __forceinline__ void phase_diff(const Args& a, int l, int G, const int bid, const int tid) {
;     ...
;             for (int i0 = 0; i0 < 32; i0 += 4) {
;                 u32x4 cw[4], ow[4];
; #pragma unroll
;                 for (int k = 0; k < 4; ++k) { cw[k] = *(const u32x4*)(ub + (size_t)(i0 + k) * WB); ow[k] = *(const u32x4*)(ub + (size_t)(i0 + k - w + 1) * WB); }
; #pragma unroll
;                 for (int k = 0; k < 4; ++k) {
;                     const int t = t0 + i0 + k; float cur[8], old[8], o[8];
;                     UNPK8(cur, cw[k]); UNPK8(old, ow[k]);
; #pragma unroll
;                     for (int e = 0; e < 8; ++e) { ws_[e] += cur[e]; o[e] = ws_[e] * inv - cur[e]; ws_[e] -= old[e]; }
;                     u32x4 pw; pw.x = pk2(o[0], o[1]); pw.y = pk2(o[2], o[3]); pw.z = pk2(o[4], o[5]); pw.w = pk2(o[6], o[7]);
;                     *(u32x4*)(MIXB + (size_t)(mseq + t) * DM + n0) = pw;
;                     if (t >= L - 15) { float* hp = hout + (size_t)(t - (L - 15)) * WB + n0; *(f32x4*)hp = (f32x4){cur[0], cur[1], cur[2], cur[3]}; *(f32x4*)(hp + 4) = (f32x4){cur[4], cur[5], cur[6], cur[7]}; }
.Ldf_nh_45:
	v_cndmask_b32_e64 v61, v12, v222, s[8:9]
	v_cndmask_b32_e64 v61, v76, v61, s[6:7]
	v_cndmask_b32_e64 v61, v61, v84, s[4:5]
	v_cndmask_b32_e64 v63, v13, v223, s[8:9]
	v_cndmask_b32_e64 v63, v77, v63, s[6:7]
	v_cndmask_b32_e64 v63, v63, v85, s[4:5]
	v_cndmask_b32_e64 v65, v14, v224, s[8:9]
	v_cndmask_b32_e64 v65, v78, v65, s[6:7]
	v_cndmask_b32_e64 v65, v65, v86, s[4:5]
	v_cndmask_b32_e64 v68, v15, v225, s[8:9]
	v_cndmask_b32_e64 v68, v79, v68, s[6:7]
	v_cndmask_b32_e64 v68, v68, v87, s[4:5]
	v_lshlrev_b32_e32 v44, 16, v61
	v_and_b32_e32 v45, 0xffff0000, v61
	v_lshlrev_b32_e32 v46, 16, v63
	v_and_b32_e32 v47, 0xffff0000, v63
	v_lshlrev_b32_e32 v52, 16, v65
	v_and_b32_e32 v53, 0xffff0000, v65
	v_lshlrev_b32_e32 v54, 16, v68
	v_and_b32_e32 v55, 0xffff0000, v68
	v_pk_add_f32 v[28:29], v[28:29], v[44:45] neg_lo:[0,1] neg_hi:[0,1]
	v_pk_add_f32 v[30:31], v[30:31], v[46:47] neg_lo:[0,1] neg_hi:[0,1]
	v_pk_add_f32 v[32:33], v[32:33], v[52:53] neg_lo:[0,1] neg_hi:[0,1]
	v_pk_add_f32 v[34:35], v[34:35], v[54:55] neg_lo:[0,1] neg_hi:[0,1]
	v_lshlrev_b32_e32 v36, 16, v92
	v_and_b32_e32 v37, 0xffff0000, v92
	v_lshlrev_b32_e32 v38, 16, v93
	v_and_b32_e32 v39, 0xffff0000, v93
	v_lshlrev_b32_e32 v40, 16, v94
	v_and_b32_e32 v41, 0xffff0000, v94
	v_lshlrev_b32_e32 v42, 16, v95
	v_and_b32_e32 v43, 0xffff0000, v95
	v_pk_add_f32 v[28:29], v[28:29], v[36:37]
	v_pk_add_f32 v[30:31], v[30:31], v[38:39]
	v_pk_add_f32 v[32:33], v[32:33], v[40:41]
	v_pk_add_f32 v[34:35], v[34:35], v[42:43]
	v_fma_f32 v44, v72, v28, -v36
	v_fma_f32 v45, v72, v29, -v37
	v_fma_f32 v46, v72, v30, -v38
	v_fma_f32 v47, v72, v31, -v39
	v_fma_f32 v52, v72, v32, -v40
	v_fma_f32 v53, v72, v33, -v41
	v_fma_f32 v54, v72, v34, -v42
	v_fma_f32 v55, v72, v35, -v43
	v_cvt_pk_bf16_f32 v56, v44, v45
	v_cvt_pk_bf16_f32 v57, v46, v47
	v_cvt_pk_bf16_f32 v58, v52, v53
	v_cvt_pk_bf16_f32 v59, v54, v55
	global_store_dwordx4 v73, v[56:59], s[34:35] offset:0 nt
	s_cmp_eq_u32 s53, 0
	s_cbranch_scc1 .Ldf_nh_46
	global_store_dwordx4 v60, v[36:39], s[24:25] offset:2048
	global_store_dwordx4 v60, v[40:43], s[24:25] offset:2064
	s_add_u32 s24, s24, 0x1000
	s_addc_u32 s25, s25, 0
.Ldf_nh_46:
	v_cndmask_b32_e64 v61, v16, v226, s[8:9]
	v_cndmask_b32_e64 v61, v80, v61, s[6:7]
	v_cndmask_b32_e64 v61, v61, v88, s[4:5]
	v_cndmask_b32_e64 v63, v17, v227, s[8:9]
	v_cndmask_b32_e64 v63, v81, v63, s[6:7]
	v_cndmask_b32_e64 v63, v63, v89, s[4:5]
	v_cndmask_b32_e64 v65, v18, v228, s[8:9]
	v_cndmask_b32_e64 v65, v82, v65, s[6:7]
	v_cndmask_b32_e64 v65, v65, v90, s[4:5]
	v_cndmask_b32_e64 v68, v19, v229, s[8:9]
	v_cndmask_b32_e64 v68, v83, v68, s[6:7]
	v_cndmask_b32_e64 v68, v68, v91, s[4:5]
	v_lshlrev_b32_e32 v44, 16, v61
	v_and_b32_e32 v45, 0xffff0000, v61
	v_lshlrev_b32_e32 v46, 16, v63
	v_and_b32_e32 v47, 0xffff0000, v63
	v_lshlrev_b32_e32 v52, 16, v65
	v_and_b32_e32 v53, 0xffff0000, v65
	v_lshlrev_b32_e32 v54, 16, v68
	v_and_b32_e32 v55, 0xffff0000, v68
	v_pk_add_f32 v[28:29], v[28:29], v[44:45] neg_lo:[0,1] neg_hi:[0,1]
	v_pk_add_f32 v[30:31], v[30:31], v[46:47] neg_lo:[0,1] neg_hi:[0,1]
	v_pk_add_f32 v[32:33], v[32:33], v[52:53] neg_lo:[0,1] neg_hi:[0,1]
	v_pk_add_f32 v[34:35], v[34:35], v[54:55] neg_lo:[0,1] neg_hi:[0,1]
	v_lshlrev_b32_e32 v36, 16, v96
	v_and_b32_e32 v37, 0xffff0000, v96
	v_lshlrev_b32_e32 v38, 16, v97
	v_and_b32_e32 v39, 0xffff0000, v97
	v_lshlrev_b32_e32 v40, 16, v98
	v_and_b32_e32 v41, 0xffff0000, v98
	v_lshlrev_b32_e32 v42, 16, v99
	v_and_b32_e32 v43, 0xffff0000, v99
	v_pk_add_f32 v[28:29], v[28:29], v[36:37]
	v_pk_add_f32 v[30:31], v[30:31], v[38:39]
	v_pk_add_f32 v[32:33], v[32:33], v[40:41]
	v_pk_add_f32 v[34:35], v[34:35], v[42:43]
	v_fma_f32 v44, v72, v28, -v36
	v_fma_f32 v45, v72, v29, -v37
	v_fma_f32 v46, v72, v30, -v38
	v_fma_f32 v47, v72, v31, -v39
	v_fma_f32 v52, v72, v32, -v40
	v_fma_f32 v53, v72, v33, -v41
	v_fma_f32 v54, v72, v34, -v42
	v_fma_f32 v55, v72, v35, -v43
	v_cvt_pk_bf16_f32 v56, v44, v45
	v_cvt_pk_bf16_f32 v57, v46, v47
	v_cvt_pk_bf16_f32 v58, v52, v53
	v_cvt_pk_bf16_f32 v59, v54, v55
	global_store_dwordx4 v73, v[56:59], s[34:35] offset:2048 nt
	s_add_u32 s34, s34, 0x1000
	s_addc_u32 s35, s35, 0
	s_cmp_eq_u32 s53, 0
	s_cbranch_scc1 .Ldf_nh_47
	global_store_dwordx4 v60, v[36:39], s[24:25] offset:0
	global_store_dwordx4 v60, v[40:43], s[24:25] offset:16
; __device__ __forceinline__ unsigned pk2(float lo, float hi) { return pg8::cvt_pk_bf16(lo, hi); }
; #define UNPK8(dst, _w) do { dst[0] = pg8::bf_lo(_w.x); dst[1] = pg8::bf_hi(_w.x); dst[2] = pg8::bf_lo(_w.y); dst[3] = pg8::bf_hi(_w.y); dst[4] = pg8::bf_lo(_w.z); dst[5] = pg8::bf_hi(_w.z); dst[6] = pg8::bf_lo(_w.w); dst[7] = pg8::bf_hi(_w.w); } while (0)
; __device__ __forceinline__ void phase_diff(const Args& a, int l, int G, const int bid, const int tid) {
;     ...
;             for (int i0 = 0; i0 < 32; i0 += 4) {
;                 u32x4 cw[4], ow[4];
; #pragma unroll
;                 for (int k = 0; k < 4; ++k) { cw[k] = *(const u32x4*)(ub + (size_t)(i0 + k) * WB); ow[k] = *(const u32x4*)(ub + (size_t)(i0 + k - w + 1) * WB); }
; #pragma unroll
;                 for (int k = 0; k < 4; ++k) {
;                     const int t = t0 + i0 + k; float cur[8], old[8], o[8];
;                     UNPK8(cur, cw[k]); UNPK8(old, ow[k]);
; #pragma unroll
;                     for (int e = 0; e < 8; ++e) { ws_[e] += cur[e]; o[e] = ws_[e] * inv - cur[e]; ws_[e] -= old[e]; }
;                     u32x4 pw; pw.x = pk2(o[0], o[1]); pw.y = pk2(o[2], o[3]); pw.z = pk2(o[4], o[5]); pw.w = pk2(o[6], o[7]);
;                     *(u32x4*)(MIXB + (size_t)(mseq + t) * DM + n0) = pw;
;                     if (t >= L - 15) { float* hp = hout + (size_t)(t - (L - 15)) * WB + n0; *(f32x4*)hp = (f32x4){cur[0], cur[1], cur[2], cur[3]}; *(f32x4*)(hp + 4) = (f32x4){cur[4], cur[5], cur[6], cur[7]}; }
.Ldf_nh_47:
	v_cndmask_b32_e64 v61, v20, v230, s[8:9]
	v_cndmask_b32_e64 v61, v84, v61, s[6:7]
	v_cndmask_b32_e64 v61, v61, v92, s[4:5]
	v_cndmask_b32_e64 v63, v21, v231, s[8:9]
	v_cndmask_b32_e64 v63, v85, v63, s[6:7]
	v_cndmask_b32_e64 v63, v63, v93, s[4:5]
	v_cndmask_b32_e64 v65, v22, v232, s[8:9]
	v_cndmask_b32_e64 v65, v86, v65, s[6:7]
	v_cndmask_b32_e64 v65, v65, v94, s[4:5]
	v_cndmask_b32_e64 v68, v23, v233, s[8:9]
	v_cndmask_b32_e64 v68, v87, v68, s[6:7]
	v_cndmask_b32_e64 v68, v68, v95, s[4:5]
	v_lshlrev_b32_e32 v44, 16, v61
	v_and_b32_e32 v45, 0xffff0000, v61
	v_lshlrev_b32_e32 v46, 16, v63
	v_and_b32_e32 v47, 0xffff0000, v63
	v_lshlrev_b32_e32 v52, 16, v65
	v_and_b32_e32 v53, 0xffff0000, v65
	v_lshlrev_b32_e32 v54, 16, v68
	v_and_b32_e32 v55, 0xffff0000, v68
	v_pk_add_f32 v[28:29], v[28:29], v[44:45] neg_lo:[0,1] neg_hi:[0,1]
	v_pk_add_f32 v[30:31], v[30:31], v[46:47] neg_lo:[0,1] neg_hi:[0,1]
	v_pk_add_f32 v[32:33], v[32:33], v[52:53] neg_lo:[0,1] neg_hi:[0,1]
	v_pk_add_f32 v[34:35], v[34:35], v[54:55] neg_lo:[0,1] neg_hi:[0,1]
	v_lshlrev_b32_e32 v36, 16, v100
	v_and_b32_e32 v37, 0xffff0000, v100
	v_lshlrev_b32_e32 v38, 16, v101
	v_and_b32_e32 v39, 0xffff0000, v101
	v_lshlrev_b32_e32 v40, 16, v102
	v_and_b32_e32 v41, 0xffff0000, v102
	v_lshlrev_b32_e32 v42, 16, v103
	v_and_b32_e32 v43, 0xffff0000, v103
	v_pk_add_f32 v[28:29], v[28:29], v[36:37]
	v_pk_add_f32 v[30:31], v[30:31], v[38:39]
	v_pk_add_f32 v[32:33], v[32:33], v[40:41]
	v_pk_add_f32 v[34:35], v[34:35], v[42:43]
	v_fma_f32 v44, v72, v28, -v36
	v_fma_f32 v45, v72, v29, -v37
	v_fma_f32 v46, v72, v30, -v38
	v_fma_f32 v47, v72, v31, -v39
	v_fma_f32 v52, v72, v32, -v40
	v_fma_f32 v53, v72, v33, -v41
	v_fma_f32 v54, v72, v34, -v42
	v_fma_f32 v55, v72, v35, -v43
	v_cvt_pk_bf16_f32 v56, v44, v45
	v_cvt_pk_bf16_f32 v57, v46, v47
	v_cvt_pk_bf16_f32 v58, v52, v53
	v_cvt_pk_bf16_f32 v59, v54, v55
	global_store_dwordx4 v73, v[56:59], s[34:35] offset:0 nt
	s_cmp_eq_u32 s53, 0
	s_cbranch_scc1 .Ldf_nh_48
	global_store_dwordx4 v60, v[36:39], s[24:25] offset:2048
	global_store_dwordx4 v60, v[40:43], s[24:25] offset:2064
	s_add_u32 s24, s24, 0x1000
	s_addc_u32 s25, s25, 0
.Ldf_nh_48:
	v_cndmask_b32_e64 v61, v24, v234, s[8:9]
	v_cndmask_b32_e64 v61, v88, v61, s[6:7]
	v_cndmask_b32_e64 v61, v61, v96, s[4:5]
	v_cndmask_b32_e64 v63, v25, v235, s[8:9]
	v_cndmask_b32_e64 v63, v89, v63, s[6:7]
	v_cndmask_b32_e64 v63, v63, v97, s[4:5]
	v_cndmask_b32_e64 v65, v26, v236, s[8:9]
	v_cndmask_b32_e64 v65, v90, v65, s[6:7]
	v_cndmask_b32_e64 v65, v65, v98, s[4:5]
	v_cndmask_b32_e64 v68, v27, v237, s[8:9]
	v_cndmask_b32_e64 v68, v91, v68, s[6:7]
	v_cndmask_b32_e64 v68, v68, v99, s[4:5]
	v_lshlrev_b32_e32 v44, 16, v61
	v_and_b32_e32 v45, 0xffff0000, v61
	v_lshlrev_b32_e32 v46, 16, v63
	v_and_b32_e32 v47, 0xffff0000, v63
	v_lshlrev_b32_e32 v52, 16, v65
	v_and_b32_e32 v53, 0xffff0000, v65
	v_lshlrev_b32_e32 v54, 16, v68
	v_and_b32_e32 v55, 0xffff0000, v68
	v_pk_add_f32 v[28:29], v[28:29], v[44:45] neg_lo:[0,1] neg_hi:[0,1]
	v_pk_add_f32 v[30:31], v[30:31], v[46:47] neg_lo:[0,1] neg_hi:[0,1]
	v_pk_add_f32 v[32:33], v[32:33], v[52:53] neg_lo:[0,1] neg_hi:[0,1]
	v_pk_add_f32 v[34:35], v[34:35], v[54:55] neg_lo:[0,1] neg_hi:[0,1]
	v_lshlrev_b32_e32 v36, 16, v104
	v_and_b32_e32 v37, 0xffff0000, v104
	v_lshlrev_b32_e32 v38, 16, v105
	v_and_b32_e32 v39, 0xffff0000, v105
	v_lshlrev_b32_e32 v40, 16, v106
	v_and_b32_e32 v41, 0xffff0000, v106
	v_lshlrev_b32_e32 v42, 16, v107
	v_and_b32_e32 v43, 0xffff0000, v107
	v_pk_add_f32 v[28:29], v[28:29], v[36:37]
	v_pk_add_f32 v[30:31], v[30:31], v[38:39]
	v_pk_add_f32 v[32:33], v[32:33], v[40:41]
	v_pk_add_f32 v[34:35], v[34:35], v[42:43]
	v_fma_f32 v44, v72, v28, -v36
	v_fma_f32 v45, v72, v29, -v37
	v_fma_f32 v46, v72, v30, -v38
	v_fma_f32 v47, v72, v31, -v39
	v_fma_f32 v52, v72, v32, -v40
	v_fma_f32 v53, v72, v33, -v41
	v_fma_f32 v54, v72, v34, -v42
	v_fma_f32 v55, v72, v35, -v43
	v_cvt_pk_bf16_f32 v56, v44, v45
	v_cvt_pk_bf16_f32 v57, v46, v47
	v_cvt_pk_bf16_f32 v58, v52, v53
	v_cvt_pk_bf16_f32 v59, v54, v55
	global_store_dwordx4 v73, v[56:59], s[34:35] offset:2048 nt
	s_add_u32 s34, s34, 0x1000
	s_addc_u32 s35, s35, 0
	s_cmp_eq_u32 s53, 0
	s_cbranch_scc1 .Ldf_nh_49
	global_store_dwordx4 v60, v[36:39], s[24:25] offset:0
	global_store_dwordx4 v60, v[40:43], s[24:25] offset:16
